# packed-FMA forward substitution with the mid-solve barrier moved from row pair 26 to row pair 30
# speedup vs baseline: 1.0067x; 1.0067x over previous
.LBB0_416:
	s_andn2_saveexec_b64 s[6:7], s[6:7]
	s_cbranch_execz .LBB0_284
	v_cmp_gt_i32_e64 s[0:1], s96, v77
	v_add_u32_e32 v39, 0xffffff80, v77
	v_cmp_lt_i32_e32 vcc, s93, v77
	v_cndmask_b32_e64 v0, v65, v74, s[0:1]
	v_cndmask_b32_e64 v1, v39, v77, s[0:1]
	v_lshl_add_u32 v0, v1, 1, v0
	v_cndmask_b32_e64 v1, v75, v76, s[0:1]
	s_nop 0
	v_add_u32_e32 v11, 0, v1
	v_add_u32_e32 v10, 0, v0
	ds_read_b128 v[24:27], v11 offset:0
	ds_read_b128 v[28:31], v11 offset:16
	ds_read_u16 v0, v10 offset:0
	ds_read_u16 v1, v10 offset:272
	ds_read_u16 v2, v10 offset:544
	ds_read_u16 v3, v10 offset:816
	ds_read_u16 v4, v10 offset:1088
	ds_read_u16 v5, v10 offset:1360
	ds_read_u16 v6, v10 offset:1632
	ds_read_u16 v7, v10 offset:1904
	ds_read_b128 v[40:43], v11 offset:32
	ds_read_b128 v[44:47], v11 offset:48
	ds_read_u16 v80, v10 offset:2176
	ds_read_u16 v81, v10 offset:2448
	ds_read_u16 v82, v10 offset:2720
	ds_read_u16 v83, v10 offset:2992
	ds_read_u16 v84, v10 offset:3264
	ds_read_u16 v85, v10 offset:3536
	ds_read_u16 v86, v10 offset:3808
	ds_read_u16 v87, v10 offset:4080
	s_waitcnt lgkmcnt(10)
	v_lshlrev_b32_e32 v0, 16, v0
	v_lshlrev_b32_e32 v1, 16, v1
	v_lshlrev_b32_e32 v2, 16, v2
	v_lshlrev_b32_e32 v3, 16, v3
	v_lshlrev_b32_e32 v4, 16, v4
	v_lshlrev_b32_e32 v5, 16, v5
	v_lshlrev_b32_e32 v6, 16, v6
	v_lshlrev_b32_e32 v7, 16, v7
	v_pk_mul_f32 v[100:101], v[24:25], v[0:1]
	v_pk_mul_f32 v[102:103], v[26:27], v[2:3]
	v_pk_mul_f32 v[104:105], v[28:29], v[4:5]
	v_pk_mul_f32 v[106:107], v[30:31], v[6:7]
	ds_read_b128 v[24:27], v11 offset:64
	ds_read_b128 v[28:31], v11 offset:80
	ds_read_u16 v0, v10 offset:4352
	ds_read_u16 v1, v10 offset:4624
	ds_read_u16 v2, v10 offset:4896
	ds_read_u16 v3, v10 offset:5168
	ds_read_u16 v4, v10 offset:5440
	ds_read_u16 v5, v10 offset:5712
	ds_read_u16 v6, v10 offset:5984
	ds_read_u16 v7, v10 offset:6256
	s_waitcnt lgkmcnt(10)
	v_lshlrev_b32_e32 v80, 16, v80
	v_lshlrev_b32_e32 v81, 16, v81
	v_lshlrev_b32_e32 v82, 16, v82
	v_lshlrev_b32_e32 v83, 16, v83
	v_lshlrev_b32_e32 v84, 16, v84
	v_lshlrev_b32_e32 v85, 16, v85
	v_lshlrev_b32_e32 v86, 16, v86
	v_lshlrev_b32_e32 v87, 16, v87
	v_pk_mul_f32 v[108:109], v[40:41], v[80:81]
	v_pk_mul_f32 v[110:111], v[42:43], v[82:83]
	v_pk_mul_f32 v[112:113], v[44:45], v[84:85]
	v_pk_mul_f32 v[114:115], v[46:47], v[86:87]
	ds_read_b128 v[40:43], v11 offset:96
	ds_read_b128 v[44:47], v11 offset:112
	ds_read_u16 v80, v10 offset:6528
	ds_read_u16 v81, v10 offset:6800
	ds_read_u16 v82, v10 offset:7072
	ds_read_u16 v83, v10 offset:7344
	ds_read_u16 v84, v10 offset:7616
	ds_read_u16 v85, v10 offset:7888
	ds_read_u16 v86, v10 offset:8160
	ds_read_u16 v87, v10 offset:8432
	s_waitcnt lgkmcnt(10)
	v_lshlrev_b32_e32 v0, 16, v0
	v_lshlrev_b32_e32 v1, 16, v1
	v_lshlrev_b32_e32 v2, 16, v2
	v_lshlrev_b32_e32 v3, 16, v3
	v_lshlrev_b32_e32 v4, 16, v4
	v_lshlrev_b32_e32 v5, 16, v5
	v_lshlrev_b32_e32 v6, 16, v6
	v_lshlrev_b32_e32 v7, 16, v7
	v_pk_mul_f32 v[116:117], v[24:25], v[0:1]
	v_pk_mul_f32 v[118:119], v[26:27], v[2:3]
	v_pk_mul_f32 v[120:121], v[28:29], v[4:5]
	v_pk_mul_f32 v[122:123], v[30:31], v[6:7]
	ds_read_b128 v[24:27], v11 offset:128
	ds_read_b128 v[28:31], v11 offset:144
	ds_read_u16 v0, v10 offset:8704
	ds_read_u16 v1, v10 offset:8976
	ds_read_u16 v2, v10 offset:9248
	ds_read_u16 v3, v10 offset:9520
	ds_read_u16 v4, v10 offset:9792
	ds_read_u16 v5, v10 offset:10064
	ds_read_u16 v6, v10 offset:10336
	ds_read_u16 v7, v10 offset:10608
	s_waitcnt lgkmcnt(10)
	v_lshlrev_b32_e32 v80, 16, v80
	v_lshlrev_b32_e32 v81, 16, v81
	v_lshlrev_b32_e32 v82, 16, v82
	v_lshlrev_b32_e32 v83, 16, v83
	v_lshlrev_b32_e32 v84, 16, v84
	v_lshlrev_b32_e32 v85, 16, v85
	v_lshlrev_b32_e32 v86, 16, v86
	v_lshlrev_b32_e32 v87, 16, v87
	v_pk_mul_f32 v[124:125], v[40:41], v[80:81]
	v_pk_mul_f32 v[126:127], v[42:43], v[82:83]
	v_pk_mul_f32 v[128:129], v[44:45], v[84:85]
	v_pk_mul_f32 v[130:131], v[46:47], v[86:87]
	ds_read_b128 v[40:43], v11 offset:160
	ds_read_b128 v[44:47], v11 offset:176
	ds_read_u16 v80, v10 offset:10880
	ds_read_u16 v81, v10 offset:11152
	ds_read_u16 v82, v10 offset:11424
	ds_read_u16 v83, v10 offset:11696
	ds_read_u16 v84, v10 offset:11968
	ds_read_u16 v85, v10 offset:12240
	ds_read_u16 v86, v10 offset:12512
	ds_read_u16 v87, v10 offset:12784
	s_waitcnt lgkmcnt(10)
	v_lshlrev_b32_e32 v0, 16, v0
	v_lshlrev_b32_e32 v1, 16, v1
	v_lshlrev_b32_e32 v2, 16, v2
	v_lshlrev_b32_e32 v3, 16, v3
	v_lshlrev_b32_e32 v4, 16, v4
	v_lshlrev_b32_e32 v5, 16, v5
	v_lshlrev_b32_e32 v6, 16, v6
	v_lshlrev_b32_e32 v7, 16, v7
	v_pk_mul_f32 v[132:133], v[24:25], v[0:1]
	v_pk_mul_f32 v[134:135], v[26:27], v[2:3]
	v_pk_mul_f32 v[136:137], v[28:29], v[4:5]
	v_pk_mul_f32 v[138:139], v[30:31], v[6:7]
	ds_read_b128 v[24:27], v11 offset:192
	ds_read_b128 v[28:31], v11 offset:208
	ds_read_u16 v0, v10 offset:13056
	ds_read_u16 v1, v10 offset:13328
	ds_read_u16 v2, v10 offset:13600
	ds_read_u16 v3, v10 offset:13872
	ds_read_u16 v4, v10 offset:14144
	ds_read_u16 v5, v10 offset:14416
	ds_read_u16 v6, v10 offset:14688
	ds_read_u16 v7, v10 offset:14960
	s_waitcnt lgkmcnt(10)
	v_lshlrev_b32_e32 v80, 16, v80
	v_lshlrev_b32_e32 v81, 16, v81
	v_lshlrev_b32_e32 v82, 16, v82
	v_lshlrev_b32_e32 v83, 16, v83
	v_lshlrev_b32_e32 v84, 16, v84
	v_lshlrev_b32_e32 v85, 16, v85
	v_lshlrev_b32_e32 v86, 16, v86
	v_lshlrev_b32_e32 v87, 16, v87
	v_pk_mul_f32 v[140:141], v[40:41], v[80:81]
	v_pk_mul_f32 v[142:143], v[42:43], v[82:83]
	v_pk_mul_f32 v[144:145], v[44:45], v[84:85]
	v_pk_mul_f32 v[146:147], v[46:47], v[86:87]
	ds_read_b128 v[40:43], v11 offset:224
	ds_read_b128 v[44:47], v11 offset:240
	ds_read_u16 v80, v10 offset:15232
	ds_read_u16 v81, v10 offset:15504
	ds_read_u16 v82, v10 offset:15776
	ds_read_u16 v83, v10 offset:16048
	ds_read_u16 v84, v10 offset:16320
	ds_read_u16 v85, v10 offset:16592
	ds_read_u16 v86, v10 offset:16864
	ds_read_u16 v87, v10 offset:17136
	s_waitcnt lgkmcnt(10)
	v_lshlrev_b32_e32 v0, 16, v0
	v_lshlrev_b32_e32 v1, 16, v1
	v_lshlrev_b32_e32 v2, 16, v2
	v_lshlrev_b32_e32 v3, 16, v3
	v_lshlrev_b32_e32 v4, 16, v4
	v_lshlrev_b32_e32 v5, 16, v5
	v_lshlrev_b32_e32 v6, 16, v6
	v_lshlrev_b32_e32 v7, 16, v7
	v_pk_mul_f32 v[148:149], v[24:25], v[0:1]
	v_pk_mul_f32 v[150:151], v[26:27], v[2:3]
	v_pk_mul_f32 v[152:153], v[28:29], v[4:5]
	v_pk_mul_f32 v[154:155], v[30:31], v[6:7]
	s_waitcnt lgkmcnt(0)
	v_lshlrev_b32_e32 v80, 16, v80
	v_lshlrev_b32_e32 v81, 16, v81
	v_lshlrev_b32_e32 v82, 16, v82
	v_lshlrev_b32_e32 v83, 16, v83
	v_lshlrev_b32_e32 v84, 16, v84
	v_lshlrev_b32_e32 v85, 16, v85
	v_lshlrev_b32_e32 v86, 16, v86
	v_lshlrev_b32_e32 v87, 16, v87
	v_pk_mul_f32 v[156:157], v[40:41], v[80:81]
	v_pk_mul_f32 v[158:159], v[42:43], v[82:83]
	v_pk_mul_f32 v[160:161], v[44:45], v[84:85]
	v_pk_mul_f32 v[162:163], v[46:47], v[86:87]
	v_mov_b32_e32 v228, 0xcc00
	ds_read_b128 v[164:167], v228 offset:0
	ds_read_b128 v[168:171], v228 offset:512
	ds_read_b128 v[172:175], v228 offset:528
	ds_read_b128 v[176:179], v228 offset:1024
	ds_read_b128 v[180:183], v228 offset:1040
	ds_read_b128 v[184:187], v228 offset:1056
	ds_read_b128 v[188:191], v228 offset:1536
	ds_read_b128 v[192:195], v228 offset:1552
	ds_read_b128 v[196:199], v228 offset:1568
	ds_read_b128 v[200:203], v228 offset:1584
	ds_read_b128 v[204:207], v228 offset:2048
	ds_read_b128 v[208:211], v228 offset:2064
	ds_read_b128 v[212:215], v228 offset:2080
	ds_read_b128 v[216:219], v228 offset:2096
	ds_read_b128 v[220:223], v228 offset:2112
	ds_read_b128 v[224:227], v228 offset:2560
	s_waitcnt lgkmcnt(14)
	v_fma_f32 v101, -v165, v100, v101
	v_pk_fma_f32 v[102:103], v[168:169], v[100:101], v[102:103] op_sel_hi:[1,0,1] neg_lo:[1,0,0] neg_hi:[1,0,0]
	v_pk_fma_f32 v[102:103], v[170:171], v[100:101], v[102:103] op_sel:[0,1,0] neg_lo:[1,0,0] neg_hi:[1,0,0]
	ds_read_b128 v[164:167], v228 offset:2576
	ds_read_b128 v[168:171], v228 offset:2592
	s_waitcnt lgkmcnt(14)
	v_fma_f32 v103, -v173, v102, v103
	v_pk_fma_f32 v[104:105], v[176:177], v[100:101], v[104:105] op_sel_hi:[1,0,1] neg_lo:[1,0,0] neg_hi:[1,0,0]
	v_pk_fma_f32 v[104:105], v[178:179], v[100:101], v[104:105] op_sel:[0,1,0] neg_lo:[1,0,0] neg_hi:[1,0,0]
	ds_read_b128 v[172:175], v228 offset:2608
	ds_read_b128 v[176:179], v228 offset:2624
	s_waitcnt lgkmcnt(14)
	v_pk_fma_f32 v[104:105], v[180:181], v[102:103], v[104:105] op_sel_hi:[1,0,1] neg_lo:[1,0,0] neg_hi:[1,0,0]
	v_pk_fma_f32 v[104:105], v[182:183], v[102:103], v[104:105] op_sel:[0,1,0] neg_lo:[1,0,0] neg_hi:[1,0,0]
	v_fma_f32 v105, -v185, v104, v105
	ds_read_b128 v[180:183], v228 offset:2640
	ds_read_b128 v[184:187], v228 offset:3072
	s_waitcnt lgkmcnt(14)
	v_pk_fma_f32 v[106:107], v[188:189], v[100:101], v[106:107] op_sel_hi:[1,0,1] neg_lo:[1,0,0] neg_hi:[1,0,0]
	v_pk_fma_f32 v[106:107], v[190:191], v[100:101], v[106:107] op_sel:[0,1,0] neg_lo:[1,0,0] neg_hi:[1,0,0]
	v_pk_fma_f32 v[106:107], v[192:193], v[102:103], v[106:107] op_sel_hi:[1,0,1] neg_lo:[1,0,0] neg_hi:[1,0,0]
	v_pk_fma_f32 v[106:107], v[194:195], v[102:103], v[106:107] op_sel:[0,1,0] neg_lo:[1,0,0] neg_hi:[1,0,0]
	ds_read_b128 v[188:191], v228 offset:3088
	ds_read_b128 v[192:195], v228 offset:3104
	s_waitcnt lgkmcnt(14)
	v_pk_fma_f32 v[106:107], v[196:197], v[104:105], v[106:107] op_sel_hi:[1,0,1] neg_lo:[1,0,0] neg_hi:[1,0,0]
	v_pk_fma_f32 v[106:107], v[198:199], v[104:105], v[106:107] op_sel:[0,1,0] neg_lo:[1,0,0] neg_hi:[1,0,0]
	v_fma_f32 v107, -v201, v106, v107
	ds_read_b128 v[196:199], v228 offset:3120
	ds_read_b128 v[200:203], v228 offset:3136
	s_waitcnt lgkmcnt(14)
	v_pk_fma_f32 v[108:109], v[204:205], v[100:101], v[108:109] op_sel_hi:[1,0,1] neg_lo:[1,0,0] neg_hi:[1,0,0]
	v_pk_fma_f32 v[108:109], v[206:207], v[100:101], v[108:109] op_sel:[0,1,0] neg_lo:[1,0,0] neg_hi:[1,0,0]
	v_pk_fma_f32 v[108:109], v[208:209], v[102:103], v[108:109] op_sel_hi:[1,0,1] neg_lo:[1,0,0] neg_hi:[1,0,0]
	v_pk_fma_f32 v[108:109], v[210:211], v[102:103], v[108:109] op_sel:[0,1,0] neg_lo:[1,0,0] neg_hi:[1,0,0]
	ds_read_b128 v[204:207], v228 offset:3152
	ds_read_b128 v[208:211], v228 offset:3168
	s_waitcnt lgkmcnt(14)
	v_pk_fma_f32 v[108:109], v[212:213], v[104:105], v[108:109] op_sel_hi:[1,0,1] neg_lo:[1,0,0] neg_hi:[1,0,0]
	v_pk_fma_f32 v[108:109], v[214:215], v[104:105], v[108:109] op_sel:[0,1,0] neg_lo:[1,0,0] neg_hi:[1,0,0]
	v_pk_fma_f32 v[108:109], v[216:217], v[106:107], v[108:109] op_sel_hi:[1,0,1] neg_lo:[1,0,0] neg_hi:[1,0,0]
	v_pk_fma_f32 v[108:109], v[218:219], v[106:107], v[108:109] op_sel:[0,1,0] neg_lo:[1,0,0] neg_hi:[1,0,0]
	ds_read_b128 v[212:215], v228 offset:3584
	ds_read_b128 v[216:219], v228 offset:3600
	s_waitcnt lgkmcnt(14)
	v_fma_f32 v109, -v221, v108, v109
	v_pk_fma_f32 v[110:111], v[224:225], v[100:101], v[110:111] op_sel_hi:[1,0,1] neg_lo:[1,0,0] neg_hi:[1,0,0]
	v_pk_fma_f32 v[110:111], v[226:227], v[100:101], v[110:111] op_sel:[0,1,0] neg_lo:[1,0,0] neg_hi:[1,0,0]
	ds_read_b128 v[220:223], v228 offset:3616
	ds_read_b128 v[224:227], v228 offset:3632
	s_waitcnt lgkmcnt(14)
	v_pk_fma_f32 v[110:111], v[164:165], v[102:103], v[110:111] op_sel_hi:[1,0,1] neg_lo:[1,0,0] neg_hi:[1,0,0]
	v_pk_fma_f32 v[110:111], v[166:167], v[102:103], v[110:111] op_sel:[0,1,0] neg_lo:[1,0,0] neg_hi:[1,0,0]
	v_pk_fma_f32 v[110:111], v[168:169], v[104:105], v[110:111] op_sel_hi:[1,0,1] neg_lo:[1,0,0] neg_hi:[1,0,0]
	v_pk_fma_f32 v[110:111], v[170:171], v[104:105], v[110:111] op_sel:[0,1,0] neg_lo:[1,0,0] neg_hi:[1,0,0]
	ds_read_b128 v[164:167], v228 offset:3648
	ds_read_b128 v[168:171], v228 offset:3664
	s_waitcnt lgkmcnt(14)
	v_pk_fma_f32 v[110:111], v[172:173], v[106:107], v[110:111] op_sel_hi:[1,0,1] neg_lo:[1,0,0] neg_hi:[1,0,0]
	v_pk_fma_f32 v[110:111], v[174:175], v[106:107], v[110:111] op_sel:[0,1,0] neg_lo:[1,0,0] neg_hi:[1,0,0]
	v_pk_fma_f32 v[110:111], v[176:177], v[108:109], v[110:111] op_sel_hi:[1,0,1] neg_lo:[1,0,0] neg_hi:[1,0,0]
	v_pk_fma_f32 v[110:111], v[178:179], v[108:109], v[110:111] op_sel:[0,1,0] neg_lo:[1,0,0] neg_hi:[1,0,0]
	ds_read_b128 v[172:175], v228 offset:3680
	ds_read_b128 v[176:179], v228 offset:3696
	s_waitcnt lgkmcnt(14)
	v_fma_f32 v111, -v181, v110, v111
	v_pk_fma_f32 v[112:113], v[184:185], v[100:101], v[112:113] op_sel_hi:[1,0,1] neg_lo:[1,0,0] neg_hi:[1,0,0]
	v_pk_fma_f32 v[112:113], v[186:187], v[100:101], v[112:113] op_sel:[0,1,0] neg_lo:[1,0,0] neg_hi:[1,0,0]
	ds_read_b128 v[180:183], v228 offset:4096
	ds_read_b128 v[184:187], v228 offset:4112
	s_waitcnt lgkmcnt(14)
	v_pk_fma_f32 v[112:113], v[188:189], v[102:103], v[112:113] op_sel_hi:[1,0,1] neg_lo:[1,0,0] neg_hi:[1,0,0]
	v_pk_fma_f32 v[112:113], v[190:191], v[102:103], v[112:113] op_sel:[0,1,0] neg_lo:[1,0,0] neg_hi:[1,0,0]
	v_pk_fma_f32 v[112:113], v[192:193], v[104:105], v[112:113] op_sel_hi:[1,0,1] neg_lo:[1,0,0] neg_hi:[1,0,0]
	v_pk_fma_f32 v[112:113], v[194:195], v[104:105], v[112:113] op_sel:[0,1,0] neg_lo:[1,0,0] neg_hi:[1,0,0]
	ds_read_b128 v[188:191], v228 offset:4128
	ds_read_b128 v[192:195], v228 offset:4144
	s_waitcnt lgkmcnt(14)
	v_pk_fma_f32 v[112:113], v[196:197], v[106:107], v[112:113] op_sel_hi:[1,0,1] neg_lo:[1,0,0] neg_hi:[1,0,0]
	v_pk_fma_f32 v[112:113], v[198:199], v[106:107], v[112:113] op_sel:[0,1,0] neg_lo:[1,0,0] neg_hi:[1,0,0]
	v_pk_fma_f32 v[112:113], v[200:201], v[108:109], v[112:113] op_sel_hi:[1,0,1] neg_lo:[1,0,0] neg_hi:[1,0,0]
	v_pk_fma_f32 v[112:113], v[202:203], v[108:109], v[112:113] op_sel:[0,1,0] neg_lo:[1,0,0] neg_hi:[1,0,0]
	ds_read_b128 v[196:199], v228 offset:4160
	ds_read_b128 v[200:203], v228 offset:4176
	s_waitcnt lgkmcnt(14)
	v_pk_fma_f32 v[112:113], v[204:205], v[110:111], v[112:113] op_sel_hi:[1,0,1] neg_lo:[1,0,0] neg_hi:[1,0,0]
	v_pk_fma_f32 v[112:113], v[206:207], v[110:111], v[112:113] op_sel:[0,1,0] neg_lo:[1,0,0] neg_hi:[1,0,0]
	v_fma_f32 v113, -v209, v112, v113
	ds_read_b128 v[204:207], v228 offset:4192
	ds_read_b128 v[208:211], v228 offset:4208
	s_waitcnt lgkmcnt(14)
	v_pk_fma_f32 v[114:115], v[212:213], v[100:101], v[114:115] op_sel_hi:[1,0,1] neg_lo:[1,0,0] neg_hi:[1,0,0]
	v_pk_fma_f32 v[114:115], v[214:215], v[100:101], v[114:115] op_sel:[0,1,0] neg_lo:[1,0,0] neg_hi:[1,0,0]
	v_pk_fma_f32 v[114:115], v[216:217], v[102:103], v[114:115] op_sel_hi:[1,0,1] neg_lo:[1,0,0] neg_hi:[1,0,0]
	v_pk_fma_f32 v[114:115], v[218:219], v[102:103], v[114:115] op_sel:[0,1,0] neg_lo:[1,0,0] neg_hi:[1,0,0]
	ds_read_b128 v[212:215], v228 offset:4224
	ds_read_b128 v[216:219], v228 offset:4608
	s_waitcnt lgkmcnt(14)
	v_pk_fma_f32 v[114:115], v[220:221], v[104:105], v[114:115] op_sel_hi:[1,0,1] neg_lo:[1,0,0] neg_hi:[1,0,0]
	v_pk_fma_f32 v[114:115], v[222:223], v[104:105], v[114:115] op_sel:[0,1,0] neg_lo:[1,0,0] neg_hi:[1,0,0]
	v_pk_fma_f32 v[114:115], v[224:225], v[106:107], v[114:115] op_sel_hi:[1,0,1] neg_lo:[1,0,0] neg_hi:[1,0,0]
	v_pk_fma_f32 v[114:115], v[226:227], v[106:107], v[114:115] op_sel:[0,1,0] neg_lo:[1,0,0] neg_hi:[1,0,0]
	ds_read_b128 v[220:223], v228 offset:4624
	ds_read_b128 v[224:227], v228 offset:4640
	s_waitcnt lgkmcnt(14)
	v_pk_fma_f32 v[114:115], v[164:165], v[108:109], v[114:115] op_sel_hi:[1,0,1] neg_lo:[1,0,0] neg_hi:[1,0,0]
	v_pk_fma_f32 v[114:115], v[166:167], v[108:109], v[114:115] op_sel:[0,1,0] neg_lo:[1,0,0] neg_hi:[1,0,0]
	v_pk_fma_f32 v[114:115], v[168:169], v[110:111], v[114:115] op_sel_hi:[1,0,1] neg_lo:[1,0,0] neg_hi:[1,0,0]
	v_pk_fma_f32 v[114:115], v[170:171], v[110:111], v[114:115] op_sel:[0,1,0] neg_lo:[1,0,0] neg_hi:[1,0,0]
	ds_read_b128 v[164:167], v228 offset:4656
	ds_read_b128 v[168:171], v228 offset:4672
	s_waitcnt lgkmcnt(14)
	v_pk_fma_f32 v[114:115], v[172:173], v[112:113], v[114:115] op_sel_hi:[1,0,1] neg_lo:[1,0,0] neg_hi:[1,0,0]
	v_pk_fma_f32 v[114:115], v[174:175], v[112:113], v[114:115] op_sel:[0,1,0] neg_lo:[1,0,0] neg_hi:[1,0,0]
	v_fma_f32 v115, -v177, v114, v115
	ds_read_b128 v[172:175], v228 offset:4688
	ds_read_b128 v[176:179], v228 offset:4704
	s_waitcnt lgkmcnt(14)
	v_pk_fma_f32 v[116:117], v[180:181], v[100:101], v[116:117] op_sel_hi:[1,0,1] neg_lo:[1,0,0] neg_hi:[1,0,0]
	v_pk_fma_f32 v[116:117], v[182:183], v[100:101], v[116:117] op_sel:[0,1,0] neg_lo:[1,0,0] neg_hi:[1,0,0]
	v_pk_fma_f32 v[116:117], v[184:185], v[102:103], v[116:117] op_sel_hi:[1,0,1] neg_lo:[1,0,0] neg_hi:[1,0,0]
	v_pk_fma_f32 v[116:117], v[186:187], v[102:103], v[116:117] op_sel:[0,1,0] neg_lo:[1,0,0] neg_hi:[1,0,0]
	ds_read_b128 v[180:183], v228 offset:4720
	ds_read_b128 v[184:187], v228 offset:4736
	s_waitcnt lgkmcnt(14)
	v_pk_fma_f32 v[116:117], v[188:189], v[104:105], v[116:117] op_sel_hi:[1,0,1] neg_lo:[1,0,0] neg_hi:[1,0,0]
	v_pk_fma_f32 v[116:117], v[190:191], v[104:105], v[116:117] op_sel:[0,1,0] neg_lo:[1,0,0] neg_hi:[1,0,0]
	v_pk_fma_f32 v[116:117], v[192:193], v[106:107], v[116:117] op_sel_hi:[1,0,1] neg_lo:[1,0,0] neg_hi:[1,0,0]
	v_pk_fma_f32 v[116:117], v[194:195], v[106:107], v[116:117] op_sel:[0,1,0] neg_lo:[1,0,0] neg_hi:[1,0,0]
	ds_read_b128 v[188:191], v228 offset:4752
	ds_read_b128 v[192:195], v228 offset:5120
	s_waitcnt lgkmcnt(14)
	v_pk_fma_f32 v[116:117], v[196:197], v[108:109], v[116:117] op_sel_hi:[1,0,1] neg_lo:[1,0,0] neg_hi:[1,0,0]
	v_pk_fma_f32 v[116:117], v[198:199], v[108:109], v[116:117] op_sel:[0,1,0] neg_lo:[1,0,0] neg_hi:[1,0,0]
	v_pk_fma_f32 v[116:117], v[200:201], v[110:111], v[116:117] op_sel_hi:[1,0,1] neg_lo:[1,0,0] neg_hi:[1,0,0]
	v_pk_fma_f32 v[116:117], v[202:203], v[110:111], v[116:117] op_sel:[0,1,0] neg_lo:[1,0,0] neg_hi:[1,0,0]
	ds_read_b128 v[196:199], v228 offset:5136
	ds_read_b128 v[200:203], v228 offset:5152
	s_waitcnt lgkmcnt(14)
	v_pk_fma_f32 v[116:117], v[204:205], v[112:113], v[116:117] op_sel_hi:[1,0,1] neg_lo:[1,0,0] neg_hi:[1,0,0]
	v_pk_fma_f32 v[116:117], v[206:207], v[112:113], v[116:117] op_sel:[0,1,0] neg_lo:[1,0,0] neg_hi:[1,0,0]
	v_pk_fma_f32 v[116:117], v[208:209], v[114:115], v[116:117] op_sel_hi:[1,0,1] neg_lo:[1,0,0] neg_hi:[1,0,0]
	v_pk_fma_f32 v[116:117], v[210:211], v[114:115], v[116:117] op_sel:[0,1,0] neg_lo:[1,0,0] neg_hi:[1,0,0]
	ds_read_b128 v[204:207], v228 offset:5168
	ds_read_b128 v[208:211], v228 offset:5184
	s_waitcnt lgkmcnt(14)
	v_fma_f32 v117, -v213, v116, v117
	v_pk_fma_f32 v[118:119], v[216:217], v[100:101], v[118:119] op_sel_hi:[1,0,1] neg_lo:[1,0,0] neg_hi:[1,0,0]
	v_pk_fma_f32 v[118:119], v[218:219], v[100:101], v[118:119] op_sel:[0,1,0] neg_lo:[1,0,0] neg_hi:[1,0,0]
	ds_read_b128 v[212:215], v228 offset:5200
	ds_read_b128 v[216:219], v228 offset:5216
	s_waitcnt lgkmcnt(14)
	v_pk_fma_f32 v[118:119], v[220:221], v[102:103], v[118:119] op_sel_hi:[1,0,1] neg_lo:[1,0,0] neg_hi:[1,0,0]
	v_pk_fma_f32 v[118:119], v[222:223], v[102:103], v[118:119] op_sel:[0,1,0] neg_lo:[1,0,0] neg_hi:[1,0,0]
	v_pk_fma_f32 v[118:119], v[224:225], v[104:105], v[118:119] op_sel_hi:[1,0,1] neg_lo:[1,0,0] neg_hi:[1,0,0]
	v_pk_fma_f32 v[118:119], v[226:227], v[104:105], v[118:119] op_sel:[0,1,0] neg_lo:[1,0,0] neg_hi:[1,0,0]
	ds_read_b128 v[220:223], v228 offset:5232
	ds_read_b128 v[224:227], v228 offset:5248
	s_waitcnt lgkmcnt(14)
	v_pk_fma_f32 v[118:119], v[164:165], v[106:107], v[118:119] op_sel_hi:[1,0,1] neg_lo:[1,0,0] neg_hi:[1,0,0]
	v_pk_fma_f32 v[118:119], v[166:167], v[106:107], v[118:119] op_sel:[0,1,0] neg_lo:[1,0,0] neg_hi:[1,0,0]
	v_pk_fma_f32 v[118:119], v[168:169], v[108:109], v[118:119] op_sel_hi:[1,0,1] neg_lo:[1,0,0] neg_hi:[1,0,0]
	v_pk_fma_f32 v[118:119], v[170:171], v[108:109], v[118:119] op_sel:[0,1,0] neg_lo:[1,0,0] neg_hi:[1,0,0]
	ds_read_b128 v[164:167], v228 offset:5264
	ds_read_b128 v[168:171], v228 offset:5280
	s_waitcnt lgkmcnt(14)
	v_pk_fma_f32 v[118:119], v[172:173], v[110:111], v[118:119] op_sel_hi:[1,0,1] neg_lo:[1,0,0] neg_hi:[1,0,0]
	v_pk_fma_f32 v[118:119], v[174:175], v[110:111], v[118:119] op_sel:[0,1,0] neg_lo:[1,0,0] neg_hi:[1,0,0]
	v_pk_fma_f32 v[118:119], v[176:177], v[112:113], v[118:119] op_sel_hi:[1,0,1] neg_lo:[1,0,0] neg_hi:[1,0,0]
	v_pk_fma_f32 v[118:119], v[178:179], v[112:113], v[118:119] op_sel:[0,1,0] neg_lo:[1,0,0] neg_hi:[1,0,0]
	ds_read_b128 v[172:175], v228 offset:5632
	ds_read_b128 v[176:179], v228 offset:5648
	s_waitcnt lgkmcnt(14)
	v_pk_fma_f32 v[118:119], v[180:181], v[114:115], v[118:119] op_sel_hi:[1,0,1] neg_lo:[1,0,0] neg_hi:[1,0,0]
	v_pk_fma_f32 v[118:119], v[182:183], v[114:115], v[118:119] op_sel:[0,1,0] neg_lo:[1,0,0] neg_hi:[1,0,0]
	v_pk_fma_f32 v[118:119], v[184:185], v[116:117], v[118:119] op_sel_hi:[1,0,1] neg_lo:[1,0,0] neg_hi:[1,0,0]
	v_pk_fma_f32 v[118:119], v[186:187], v[116:117], v[118:119] op_sel:[0,1,0] neg_lo:[1,0,0] neg_hi:[1,0,0]
	ds_read_b128 v[180:183], v228 offset:5664
	ds_read_b128 v[184:187], v228 offset:5680
	s_waitcnt lgkmcnt(14)
	v_fma_f32 v119, -v189, v118, v119
	v_pk_fma_f32 v[120:121], v[192:193], v[100:101], v[120:121] op_sel_hi:[1,0,1] neg_lo:[1,0,0] neg_hi:[1,0,0]
	v_pk_fma_f32 v[120:121], v[194:195], v[100:101], v[120:121] op_sel:[0,1,0] neg_lo:[1,0,0] neg_hi:[1,0,0]
	ds_read_b128 v[188:191], v228 offset:5696
	ds_read_b128 v[192:195], v228 offset:5712
	s_waitcnt lgkmcnt(14)
	v_pk_fma_f32 v[120:121], v[196:197], v[102:103], v[120:121] op_sel_hi:[1,0,1] neg_lo:[1,0,0] neg_hi:[1,0,0]
	v_pk_fma_f32 v[120:121], v[198:199], v[102:103], v[120:121] op_sel:[0,1,0] neg_lo:[1,0,0] neg_hi:[1,0,0]
	v_pk_fma_f32 v[120:121], v[200:201], v[104:105], v[120:121] op_sel_hi:[1,0,1] neg_lo:[1,0,0] neg_hi:[1,0,0]
	v_pk_fma_f32 v[120:121], v[202:203], v[104:105], v[120:121] op_sel:[0,1,0] neg_lo:[1,0,0] neg_hi:[1,0,0]
	ds_read_b128 v[196:199], v228 offset:5728
	ds_read_b128 v[200:203], v228 offset:5744
	s_waitcnt lgkmcnt(14)
	v_pk_fma_f32 v[120:121], v[204:205], v[106:107], v[120:121] op_sel_hi:[1,0,1] neg_lo:[1,0,0] neg_hi:[1,0,0]
	v_pk_fma_f32 v[120:121], v[206:207], v[106:107], v[120:121] op_sel:[0,1,0] neg_lo:[1,0,0] neg_hi:[1,0,0]
	v_pk_fma_f32 v[120:121], v[208:209], v[108:109], v[120:121] op_sel_hi:[1,0,1] neg_lo:[1,0,0] neg_hi:[1,0,0]
	v_pk_fma_f32 v[120:121], v[210:211], v[108:109], v[120:121] op_sel:[0,1,0] neg_lo:[1,0,0] neg_hi:[1,0,0]
	ds_read_b128 v[204:207], v228 offset:5760
	ds_read_b128 v[208:211], v228 offset:5776
	s_waitcnt lgkmcnt(14)
	v_pk_fma_f32 v[120:121], v[212:213], v[110:111], v[120:121] op_sel_hi:[1,0,1] neg_lo:[1,0,0] neg_hi:[1,0,0]
	v_pk_fma_f32 v[120:121], v[214:215], v[110:111], v[120:121] op_sel:[0,1,0] neg_lo:[1,0,0] neg_hi:[1,0,0]
	v_pk_fma_f32 v[120:121], v[216:217], v[112:113], v[120:121] op_sel_hi:[1,0,1] neg_lo:[1,0,0] neg_hi:[1,0,0]
	v_pk_fma_f32 v[120:121], v[218:219], v[112:113], v[120:121] op_sel:[0,1,0] neg_lo:[1,0,0] neg_hi:[1,0,0]
	ds_read_b128 v[212:215], v228 offset:5792
	ds_read_b128 v[216:219], v228 offset:5808
	s_waitcnt lgkmcnt(14)
	v_pk_fma_f32 v[120:121], v[220:221], v[114:115], v[120:121] op_sel_hi:[1,0,1] neg_lo:[1,0,0] neg_hi:[1,0,0]
	v_pk_fma_f32 v[120:121], v[222:223], v[114:115], v[120:121] op_sel:[0,1,0] neg_lo:[1,0,0] neg_hi:[1,0,0]
	v_pk_fma_f32 v[120:121], v[224:225], v[116:117], v[120:121] op_sel_hi:[1,0,1] neg_lo:[1,0,0] neg_hi:[1,0,0]
	v_pk_fma_f32 v[120:121], v[226:227], v[116:117], v[120:121] op_sel:[0,1,0] neg_lo:[1,0,0] neg_hi:[1,0,0]
	ds_read_b128 v[220:223], v228 offset:6144
	ds_read_b128 v[224:227], v228 offset:6160
	s_waitcnt lgkmcnt(14)
	v_pk_fma_f32 v[120:121], v[164:165], v[118:119], v[120:121] op_sel_hi:[1,0,1] neg_lo:[1,0,0] neg_hi:[1,0,0]
	v_pk_fma_f32 v[120:121], v[166:167], v[118:119], v[120:121] op_sel:[0,1,0] neg_lo:[1,0,0] neg_hi:[1,0,0]
	v_fma_f32 v121, -v169, v120, v121
	ds_read_b128 v[164:167], v228 offset:6176
	ds_read_b128 v[168:171], v228 offset:6192
	s_waitcnt lgkmcnt(14)
	v_pk_fma_f32 v[122:123], v[172:173], v[100:101], v[122:123] op_sel_hi:[1,0,1] neg_lo:[1,0,0] neg_hi:[1,0,0]
	v_pk_fma_f32 v[122:123], v[174:175], v[100:101], v[122:123] op_sel:[0,1,0] neg_lo:[1,0,0] neg_hi:[1,0,0]
	v_pk_fma_f32 v[122:123], v[176:177], v[102:103], v[122:123] op_sel_hi:[1,0,1] neg_lo:[1,0,0] neg_hi:[1,0,0]
	v_pk_fma_f32 v[122:123], v[178:179], v[102:103], v[122:123] op_sel:[0,1,0] neg_lo:[1,0,0] neg_hi:[1,0,0]
	ds_read_b128 v[172:175], v228 offset:6208
	ds_read_b128 v[176:179], v228 offset:6224
	s_waitcnt lgkmcnt(14)
	v_pk_fma_f32 v[122:123], v[180:181], v[104:105], v[122:123] op_sel_hi:[1,0,1] neg_lo:[1,0,0] neg_hi:[1,0,0]
	v_pk_fma_f32 v[122:123], v[182:183], v[104:105], v[122:123] op_sel:[0,1,0] neg_lo:[1,0,0] neg_hi:[1,0,0]
	v_pk_fma_f32 v[122:123], v[184:185], v[106:107], v[122:123] op_sel_hi:[1,0,1] neg_lo:[1,0,0] neg_hi:[1,0,0]
	v_pk_fma_f32 v[122:123], v[186:187], v[106:107], v[122:123] op_sel:[0,1,0] neg_lo:[1,0,0] neg_hi:[1,0,0]
	ds_read_b128 v[180:183], v228 offset:6240
	ds_read_b128 v[184:187], v228 offset:6256
	s_waitcnt lgkmcnt(14)
	v_pk_fma_f32 v[122:123], v[188:189], v[108:109], v[122:123] op_sel_hi:[1,0,1] neg_lo:[1,0,0] neg_hi:[1,0,0]
	v_pk_fma_f32 v[122:123], v[190:191], v[108:109], v[122:123] op_sel:[0,1,0] neg_lo:[1,0,0] neg_hi:[1,0,0]
	v_pk_fma_f32 v[122:123], v[192:193], v[110:111], v[122:123] op_sel_hi:[1,0,1] neg_lo:[1,0,0] neg_hi:[1,0,0]
	v_pk_fma_f32 v[122:123], v[194:195], v[110:111], v[122:123] op_sel:[0,1,0] neg_lo:[1,0,0] neg_hi:[1,0,0]
	ds_read_b128 v[188:191], v228 offset:6272
	ds_read_b128 v[192:195], v228 offset:6288
	s_waitcnt lgkmcnt(14)
	v_pk_fma_f32 v[122:123], v[196:197], v[112:113], v[122:123] op_sel_hi:[1,0,1] neg_lo:[1,0,0] neg_hi:[1,0,0]
	v_pk_fma_f32 v[122:123], v[198:199], v[112:113], v[122:123] op_sel:[0,1,0] neg_lo:[1,0,0] neg_hi:[1,0,0]
	v_pk_fma_f32 v[122:123], v[200:201], v[114:115], v[122:123] op_sel_hi:[1,0,1] neg_lo:[1,0,0] neg_hi:[1,0,0]
	v_pk_fma_f32 v[122:123], v[202:203], v[114:115], v[122:123] op_sel:[0,1,0] neg_lo:[1,0,0] neg_hi:[1,0,0]
	ds_read_b128 v[196:199], v228 offset:6304
	ds_read_b128 v[200:203], v228 offset:6320
	s_waitcnt lgkmcnt(14)
	v_pk_fma_f32 v[122:123], v[204:205], v[116:117], v[122:123] op_sel_hi:[1,0,1] neg_lo:[1,0,0] neg_hi:[1,0,0]
	v_pk_fma_f32 v[122:123], v[206:207], v[116:117], v[122:123] op_sel:[0,1,0] neg_lo:[1,0,0] neg_hi:[1,0,0]
	v_pk_fma_f32 v[122:123], v[208:209], v[118:119], v[122:123] op_sel_hi:[1,0,1] neg_lo:[1,0,0] neg_hi:[1,0,0]
	v_pk_fma_f32 v[122:123], v[210:211], v[118:119], v[122:123] op_sel:[0,1,0] neg_lo:[1,0,0] neg_hi:[1,0,0]
	ds_read_b128 v[204:207], v228 offset:6336
	ds_read_b128 v[208:211], v228 offset:6656
	s_waitcnt lgkmcnt(14)
	v_pk_fma_f32 v[122:123], v[212:213], v[120:121], v[122:123] op_sel_hi:[1,0,1] neg_lo:[1,0,0] neg_hi:[1,0,0]
	v_pk_fma_f32 v[122:123], v[214:215], v[120:121], v[122:123] op_sel:[0,1,0] neg_lo:[1,0,0] neg_hi:[1,0,0]
	v_fma_f32 v123, -v217, v122, v123
	ds_read_b128 v[212:215], v228 offset:6672
	ds_read_b128 v[216:219], v228 offset:6688
	s_waitcnt lgkmcnt(14)
	v_pk_fma_f32 v[124:125], v[220:221], v[100:101], v[124:125] op_sel_hi:[1,0,1] neg_lo:[1,0,0] neg_hi:[1,0,0]
	v_pk_fma_f32 v[124:125], v[222:223], v[100:101], v[124:125] op_sel:[0,1,0] neg_lo:[1,0,0] neg_hi:[1,0,0]
	v_pk_fma_f32 v[124:125], v[224:225], v[102:103], v[124:125] op_sel_hi:[1,0,1] neg_lo:[1,0,0] neg_hi:[1,0,0]
	v_pk_fma_f32 v[124:125], v[226:227], v[102:103], v[124:125] op_sel:[0,1,0] neg_lo:[1,0,0] neg_hi:[1,0,0]
	ds_read_b128 v[220:223], v228 offset:6704
	ds_read_b128 v[224:227], v228 offset:6720
	s_waitcnt lgkmcnt(14)
	v_pk_fma_f32 v[124:125], v[164:165], v[104:105], v[124:125] op_sel_hi:[1,0,1] neg_lo:[1,0,0] neg_hi:[1,0,0]
	v_pk_fma_f32 v[124:125], v[166:167], v[104:105], v[124:125] op_sel:[0,1,0] neg_lo:[1,0,0] neg_hi:[1,0,0]
	v_pk_fma_f32 v[124:125], v[168:169], v[106:107], v[124:125] op_sel_hi:[1,0,1] neg_lo:[1,0,0] neg_hi:[1,0,0]
	v_pk_fma_f32 v[124:125], v[170:171], v[106:107], v[124:125] op_sel:[0,1,0] neg_lo:[1,0,0] neg_hi:[1,0,0]
	ds_read_b128 v[164:167], v228 offset:6736
	ds_read_b128 v[168:171], v228 offset:6752
	s_waitcnt lgkmcnt(14)
	v_pk_fma_f32 v[124:125], v[172:173], v[108:109], v[124:125] op_sel_hi:[1,0,1] neg_lo:[1,0,0] neg_hi:[1,0,0]
	v_pk_fma_f32 v[124:125], v[174:175], v[108:109], v[124:125] op_sel:[0,1,0] neg_lo:[1,0,0] neg_hi:[1,0,0]
	v_pk_fma_f32 v[124:125], v[176:177], v[110:111], v[124:125] op_sel_hi:[1,0,1] neg_lo:[1,0,0] neg_hi:[1,0,0]
	v_pk_fma_f32 v[124:125], v[178:179], v[110:111], v[124:125] op_sel:[0,1,0] neg_lo:[1,0,0] neg_hi:[1,0,0]
	ds_read_b128 v[172:175], v228 offset:6768
	ds_read_b128 v[176:179], v228 offset:6784
	s_waitcnt lgkmcnt(14)
	v_pk_fma_f32 v[124:125], v[180:181], v[112:113], v[124:125] op_sel_hi:[1,0,1] neg_lo:[1,0,0] neg_hi:[1,0,0]
	v_pk_fma_f32 v[124:125], v[182:183], v[112:113], v[124:125] op_sel:[0,1,0] neg_lo:[1,0,0] neg_hi:[1,0,0]
	v_pk_fma_f32 v[124:125], v[184:185], v[114:115], v[124:125] op_sel_hi:[1,0,1] neg_lo:[1,0,0] neg_hi:[1,0,0]
	v_pk_fma_f32 v[124:125], v[186:187], v[114:115], v[124:125] op_sel:[0,1,0] neg_lo:[1,0,0] neg_hi:[1,0,0]
	ds_read_b128 v[180:183], v228 offset:6800
	ds_read_b128 v[184:187], v228 offset:6816
	s_waitcnt lgkmcnt(14)
	v_pk_fma_f32 v[124:125], v[188:189], v[116:117], v[124:125] op_sel_hi:[1,0,1] neg_lo:[1,0,0] neg_hi:[1,0,0]
	v_pk_fma_f32 v[124:125], v[190:191], v[116:117], v[124:125] op_sel:[0,1,0] neg_lo:[1,0,0] neg_hi:[1,0,0]
	v_pk_fma_f32 v[124:125], v[192:193], v[118:119], v[124:125] op_sel_hi:[1,0,1] neg_lo:[1,0,0] neg_hi:[1,0,0]
	v_pk_fma_f32 v[124:125], v[194:195], v[118:119], v[124:125] op_sel:[0,1,0] neg_lo:[1,0,0] neg_hi:[1,0,0]
	ds_read_b128 v[188:191], v228 offset:6832
	ds_read_b128 v[192:195], v228 offset:6848
	s_waitcnt lgkmcnt(14)
	v_pk_fma_f32 v[124:125], v[196:197], v[120:121], v[124:125] op_sel_hi:[1,0,1] neg_lo:[1,0,0] neg_hi:[1,0,0]
	v_pk_fma_f32 v[124:125], v[198:199], v[120:121], v[124:125] op_sel:[0,1,0] neg_lo:[1,0,0] neg_hi:[1,0,0]
	v_pk_fma_f32 v[124:125], v[200:201], v[122:123], v[124:125] op_sel_hi:[1,0,1] neg_lo:[1,0,0] neg_hi:[1,0,0]
	v_pk_fma_f32 v[124:125], v[202:203], v[122:123], v[124:125] op_sel:[0,1,0] neg_lo:[1,0,0] neg_hi:[1,0,0]
	ds_read_b128 v[196:199], v228 offset:6864
	ds_read_b128 v[200:203], v228 offset:7168
	s_waitcnt lgkmcnt(14)
	v_fma_f32 v125, -v205, v124, v125
	v_pk_fma_f32 v[126:127], v[208:209], v[100:101], v[126:127] op_sel_hi:[1,0,1] neg_lo:[1,0,0] neg_hi:[1,0,0]
	v_pk_fma_f32 v[126:127], v[210:211], v[100:101], v[126:127] op_sel:[0,1,0] neg_lo:[1,0,0] neg_hi:[1,0,0]
	ds_read_b128 v[204:207], v228 offset:7184
	ds_read_b128 v[208:211], v228 offset:7200
	s_waitcnt lgkmcnt(14)
	v_pk_fma_f32 v[126:127], v[212:213], v[102:103], v[126:127] op_sel_hi:[1,0,1] neg_lo:[1,0,0] neg_hi:[1,0,0]
	v_pk_fma_f32 v[126:127], v[214:215], v[102:103], v[126:127] op_sel:[0,1,0] neg_lo:[1,0,0] neg_hi:[1,0,0]
	v_pk_fma_f32 v[126:127], v[216:217], v[104:105], v[126:127] op_sel_hi:[1,0,1] neg_lo:[1,0,0] neg_hi:[1,0,0]
	v_pk_fma_f32 v[126:127], v[218:219], v[104:105], v[126:127] op_sel:[0,1,0] neg_lo:[1,0,0] neg_hi:[1,0,0]
	ds_read_b128 v[212:215], v228 offset:7216
	ds_read_b128 v[216:219], v228 offset:7232
	s_waitcnt lgkmcnt(14)
	v_pk_fma_f32 v[126:127], v[220:221], v[106:107], v[126:127] op_sel_hi:[1,0,1] neg_lo:[1,0,0] neg_hi:[1,0,0]
	v_pk_fma_f32 v[126:127], v[222:223], v[106:107], v[126:127] op_sel:[0,1,0] neg_lo:[1,0,0] neg_hi:[1,0,0]
	v_pk_fma_f32 v[126:127], v[224:225], v[108:109], v[126:127] op_sel_hi:[1,0,1] neg_lo:[1,0,0] neg_hi:[1,0,0]
	v_pk_fma_f32 v[126:127], v[226:227], v[108:109], v[126:127] op_sel:[0,1,0] neg_lo:[1,0,0] neg_hi:[1,0,0]
	ds_read_b128 v[220:223], v228 offset:7248
	ds_read_b128 v[224:227], v228 offset:7264
	s_waitcnt lgkmcnt(14)
	v_pk_fma_f32 v[126:127], v[164:165], v[110:111], v[126:127] op_sel_hi:[1,0,1] neg_lo:[1,0,0] neg_hi:[1,0,0]
	v_pk_fma_f32 v[126:127], v[166:167], v[110:111], v[126:127] op_sel:[0,1,0] neg_lo:[1,0,0] neg_hi:[1,0,0]
	v_pk_fma_f32 v[126:127], v[168:169], v[112:113], v[126:127] op_sel_hi:[1,0,1] neg_lo:[1,0,0] neg_hi:[1,0,0]
	v_pk_fma_f32 v[126:127], v[170:171], v[112:113], v[126:127] op_sel:[0,1,0] neg_lo:[1,0,0] neg_hi:[1,0,0]
	ds_read_b128 v[164:167], v228 offset:7280
	ds_read_b128 v[168:171], v228 offset:7296
	s_waitcnt lgkmcnt(14)
	v_pk_fma_f32 v[126:127], v[172:173], v[114:115], v[126:127] op_sel_hi:[1,0,1] neg_lo:[1,0,0] neg_hi:[1,0,0]
	v_pk_fma_f32 v[126:127], v[174:175], v[114:115], v[126:127] op_sel:[0,1,0] neg_lo:[1,0,0] neg_hi:[1,0,0]
	v_pk_fma_f32 v[126:127], v[176:177], v[116:117], v[126:127] op_sel_hi:[1,0,1] neg_lo:[1,0,0] neg_hi:[1,0,0]
	v_pk_fma_f32 v[126:127], v[178:179], v[116:117], v[126:127] op_sel:[0,1,0] neg_lo:[1,0,0] neg_hi:[1,0,0]
	ds_read_b128 v[172:175], v228 offset:7312
	ds_read_b128 v[176:179], v228 offset:7328
	s_waitcnt lgkmcnt(14)
	v_pk_fma_f32 v[126:127], v[180:181], v[118:119], v[126:127] op_sel_hi:[1,0,1] neg_lo:[1,0,0] neg_hi:[1,0,0]
	v_pk_fma_f32 v[126:127], v[182:183], v[118:119], v[126:127] op_sel:[0,1,0] neg_lo:[1,0,0] neg_hi:[1,0,0]
	v_pk_fma_f32 v[126:127], v[184:185], v[120:121], v[126:127] op_sel_hi:[1,0,1] neg_lo:[1,0,0] neg_hi:[1,0,0]
	v_pk_fma_f32 v[126:127], v[186:187], v[120:121], v[126:127] op_sel:[0,1,0] neg_lo:[1,0,0] neg_hi:[1,0,0]
	ds_read_b128 v[180:183], v228 offset:7344
	ds_read_b128 v[184:187], v228 offset:7360
	s_waitcnt lgkmcnt(14)
	v_pk_fma_f32 v[126:127], v[188:189], v[122:123], v[126:127] op_sel_hi:[1,0,1] neg_lo:[1,0,0] neg_hi:[1,0,0]
	v_pk_fma_f32 v[126:127], v[190:191], v[122:123], v[126:127] op_sel:[0,1,0] neg_lo:[1,0,0] neg_hi:[1,0,0]
	v_pk_fma_f32 v[126:127], v[192:193], v[124:125], v[126:127] op_sel_hi:[1,0,1] neg_lo:[1,0,0] neg_hi:[1,0,0]
	v_pk_fma_f32 v[126:127], v[194:195], v[124:125], v[126:127] op_sel:[0,1,0] neg_lo:[1,0,0] neg_hi:[1,0,0]
	ds_read_b128 v[188:191], v228 offset:7376
	ds_read_b128 v[192:195], v228 offset:7392
	s_waitcnt lgkmcnt(14)
	v_fma_f32 v127, -v197, v126, v127
	v_pk_fma_f32 v[128:129], v[200:201], v[100:101], v[128:129] op_sel_hi:[1,0,1] neg_lo:[1,0,0] neg_hi:[1,0,0]
	v_pk_fma_f32 v[128:129], v[202:203], v[100:101], v[128:129] op_sel:[0,1,0] neg_lo:[1,0,0] neg_hi:[1,0,0]
	ds_read_b128 v[196:199], v228 offset:7680
	ds_read_b128 v[200:203], v228 offset:7696
	s_waitcnt lgkmcnt(14)
	v_pk_fma_f32 v[128:129], v[204:205], v[102:103], v[128:129] op_sel_hi:[1,0,1] neg_lo:[1,0,0] neg_hi:[1,0,0]
	v_pk_fma_f32 v[128:129], v[206:207], v[102:103], v[128:129] op_sel:[0,1,0] neg_lo:[1,0,0] neg_hi:[1,0,0]
	v_pk_fma_f32 v[128:129], v[208:209], v[104:105], v[128:129] op_sel_hi:[1,0,1] neg_lo:[1,0,0] neg_hi:[1,0,0]
	v_pk_fma_f32 v[128:129], v[210:211], v[104:105], v[128:129] op_sel:[0,1,0] neg_lo:[1,0,0] neg_hi:[1,0,0]
	ds_read_b128 v[204:207], v228 offset:7712
	ds_read_b128 v[208:211], v228 offset:7728
	s_waitcnt lgkmcnt(14)
	v_pk_fma_f32 v[128:129], v[212:213], v[106:107], v[128:129] op_sel_hi:[1,0,1] neg_lo:[1,0,0] neg_hi:[1,0,0]
	v_pk_fma_f32 v[128:129], v[214:215], v[106:107], v[128:129] op_sel:[0,1,0] neg_lo:[1,0,0] neg_hi:[1,0,0]
	v_pk_fma_f32 v[128:129], v[216:217], v[108:109], v[128:129] op_sel_hi:[1,0,1] neg_lo:[1,0,0] neg_hi:[1,0,0]
	v_pk_fma_f32 v[128:129], v[218:219], v[108:109], v[128:129] op_sel:[0,1,0] neg_lo:[1,0,0] neg_hi:[1,0,0]
	ds_read_b128 v[212:215], v228 offset:7744
	ds_read_b128 v[216:219], v228 offset:7760
	s_waitcnt lgkmcnt(14)
	v_pk_fma_f32 v[128:129], v[220:221], v[110:111], v[128:129] op_sel_hi:[1,0,1] neg_lo:[1,0,0] neg_hi:[1,0,0]
	v_pk_fma_f32 v[128:129], v[222:223], v[110:111], v[128:129] op_sel:[0,1,0] neg_lo:[1,0,0] neg_hi:[1,0,0]
	v_pk_fma_f32 v[128:129], v[224:225], v[112:113], v[128:129] op_sel_hi:[1,0,1] neg_lo:[1,0,0] neg_hi:[1,0,0]
	v_pk_fma_f32 v[128:129], v[226:227], v[112:113], v[128:129] op_sel:[0,1,0] neg_lo:[1,0,0] neg_hi:[1,0,0]
	ds_read_b128 v[220:223], v228 offset:7776
	ds_read_b128 v[224:227], v228 offset:7792
	s_waitcnt lgkmcnt(14)
	v_pk_fma_f32 v[128:129], v[164:165], v[114:115], v[128:129] op_sel_hi:[1,0,1] neg_lo:[1,0,0] neg_hi:[1,0,0]
	v_pk_fma_f32 v[128:129], v[166:167], v[114:115], v[128:129] op_sel:[0,1,0] neg_lo:[1,0,0] neg_hi:[1,0,0]
	v_pk_fma_f32 v[128:129], v[168:169], v[116:117], v[128:129] op_sel_hi:[1,0,1] neg_lo:[1,0,0] neg_hi:[1,0,0]
	v_pk_fma_f32 v[128:129], v[170:171], v[116:117], v[128:129] op_sel:[0,1,0] neg_lo:[1,0,0] neg_hi:[1,0,0]
	ds_read_b128 v[164:167], v228 offset:7808
	ds_read_b128 v[168:171], v228 offset:7824
	s_waitcnt lgkmcnt(14)
	v_pk_fma_f32 v[128:129], v[172:173], v[118:119], v[128:129] op_sel_hi:[1,0,1] neg_lo:[1,0,0] neg_hi:[1,0,0]
	v_pk_fma_f32 v[128:129], v[174:175], v[118:119], v[128:129] op_sel:[0,1,0] neg_lo:[1,0,0] neg_hi:[1,0,0]
	v_pk_fma_f32 v[128:129], v[176:177], v[120:121], v[128:129] op_sel_hi:[1,0,1] neg_lo:[1,0,0] neg_hi:[1,0,0]
	v_pk_fma_f32 v[128:129], v[178:179], v[120:121], v[128:129] op_sel:[0,1,0] neg_lo:[1,0,0] neg_hi:[1,0,0]
	ds_read_b128 v[172:175], v228 offset:7840
	ds_read_b128 v[176:179], v228 offset:7856
	s_waitcnt lgkmcnt(14)
	v_pk_fma_f32 v[128:129], v[180:181], v[122:123], v[128:129] op_sel_hi:[1,0,1] neg_lo:[1,0,0] neg_hi:[1,0,0]
	v_pk_fma_f32 v[128:129], v[182:183], v[122:123], v[128:129] op_sel:[0,1,0] neg_lo:[1,0,0] neg_hi:[1,0,0]
	v_pk_fma_f32 v[128:129], v[184:185], v[124:125], v[128:129] op_sel_hi:[1,0,1] neg_lo:[1,0,0] neg_hi:[1,0,0]
	v_pk_fma_f32 v[128:129], v[186:187], v[124:125], v[128:129] op_sel:[0,1,0] neg_lo:[1,0,0] neg_hi:[1,0,0]
	ds_read_b128 v[180:183], v228 offset:7872
	ds_read_b128 v[184:187], v228 offset:7888
	s_waitcnt lgkmcnt(14)
	v_pk_fma_f32 v[128:129], v[188:189], v[126:127], v[128:129] op_sel_hi:[1,0,1] neg_lo:[1,0,0] neg_hi:[1,0,0]
	v_pk_fma_f32 v[128:129], v[190:191], v[126:127], v[128:129] op_sel:[0,1,0] neg_lo:[1,0,0] neg_hi:[1,0,0]
	v_fma_f32 v129, -v193, v128, v129
	ds_read_b128 v[188:191], v228 offset:7904
	ds_read_b128 v[192:195], v228 offset:7920
	s_waitcnt lgkmcnt(14)
	v_pk_fma_f32 v[130:131], v[196:197], v[100:101], v[130:131] op_sel_hi:[1,0,1] neg_lo:[1,0,0] neg_hi:[1,0,0]
	v_pk_fma_f32 v[130:131], v[198:199], v[100:101], v[130:131] op_sel:[0,1,0] neg_lo:[1,0,0] neg_hi:[1,0,0]
	v_pk_fma_f32 v[130:131], v[200:201], v[102:103], v[130:131] op_sel_hi:[1,0,1] neg_lo:[1,0,0] neg_hi:[1,0,0]
	v_pk_fma_f32 v[130:131], v[202:203], v[102:103], v[130:131] op_sel:[0,1,0] neg_lo:[1,0,0] neg_hi:[1,0,0]
	ds_read_b128 v[196:199], v228 offset:8192
	ds_read_b128 v[200:203], v228 offset:8208
	s_waitcnt lgkmcnt(14)
	v_pk_fma_f32 v[130:131], v[204:205], v[104:105], v[130:131] op_sel_hi:[1,0,1] neg_lo:[1,0,0] neg_hi:[1,0,0]
	v_pk_fma_f32 v[130:131], v[206:207], v[104:105], v[130:131] op_sel:[0,1,0] neg_lo:[1,0,0] neg_hi:[1,0,0]
	v_pk_fma_f32 v[130:131], v[208:209], v[106:107], v[130:131] op_sel_hi:[1,0,1] neg_lo:[1,0,0] neg_hi:[1,0,0]
	v_pk_fma_f32 v[130:131], v[210:211], v[106:107], v[130:131] op_sel:[0,1,0] neg_lo:[1,0,0] neg_hi:[1,0,0]
	ds_read_b128 v[204:207], v228 offset:8224
	ds_read_b128 v[208:211], v228 offset:8240
	s_waitcnt lgkmcnt(14)
	v_pk_fma_f32 v[130:131], v[212:213], v[108:109], v[130:131] op_sel_hi:[1,0,1] neg_lo:[1,0,0] neg_hi:[1,0,0]
	v_pk_fma_f32 v[130:131], v[214:215], v[108:109], v[130:131] op_sel:[0,1,0] neg_lo:[1,0,0] neg_hi:[1,0,0]
	v_pk_fma_f32 v[130:131], v[216:217], v[110:111], v[130:131] op_sel_hi:[1,0,1] neg_lo:[1,0,0] neg_hi:[1,0,0]
	v_pk_fma_f32 v[130:131], v[218:219], v[110:111], v[130:131] op_sel:[0,1,0] neg_lo:[1,0,0] neg_hi:[1,0,0]
	ds_read_b128 v[212:215], v228 offset:8256
	ds_read_b128 v[216:219], v228 offset:8272
	s_waitcnt lgkmcnt(14)
	v_pk_fma_f32 v[130:131], v[220:221], v[112:113], v[130:131] op_sel_hi:[1,0,1] neg_lo:[1,0,0] neg_hi:[1,0,0]
	v_pk_fma_f32 v[130:131], v[222:223], v[112:113], v[130:131] op_sel:[0,1,0] neg_lo:[1,0,0] neg_hi:[1,0,0]
	v_pk_fma_f32 v[130:131], v[224:225], v[114:115], v[130:131] op_sel_hi:[1,0,1] neg_lo:[1,0,0] neg_hi:[1,0,0]
	v_pk_fma_f32 v[130:131], v[226:227], v[114:115], v[130:131] op_sel:[0,1,0] neg_lo:[1,0,0] neg_hi:[1,0,0]
	ds_read_b128 v[220:223], v228 offset:8288
	ds_read_b128 v[224:227], v228 offset:8304
	s_waitcnt lgkmcnt(14)
	v_pk_fma_f32 v[130:131], v[164:165], v[116:117], v[130:131] op_sel_hi:[1,0,1] neg_lo:[1,0,0] neg_hi:[1,0,0]
	v_pk_fma_f32 v[130:131], v[166:167], v[116:117], v[130:131] op_sel:[0,1,0] neg_lo:[1,0,0] neg_hi:[1,0,0]
	v_pk_fma_f32 v[130:131], v[168:169], v[118:119], v[130:131] op_sel_hi:[1,0,1] neg_lo:[1,0,0] neg_hi:[1,0,0]
	v_pk_fma_f32 v[130:131], v[170:171], v[118:119], v[130:131] op_sel:[0,1,0] neg_lo:[1,0,0] neg_hi:[1,0,0]
	ds_read_b128 v[164:167], v228 offset:8320
	ds_read_b128 v[168:171], v228 offset:8336
	s_waitcnt lgkmcnt(14)
	v_pk_fma_f32 v[130:131], v[172:173], v[120:121], v[130:131] op_sel_hi:[1,0,1] neg_lo:[1,0,0] neg_hi:[1,0,0]
	v_pk_fma_f32 v[130:131], v[174:175], v[120:121], v[130:131] op_sel:[0,1,0] neg_lo:[1,0,0] neg_hi:[1,0,0]
	v_pk_fma_f32 v[130:131], v[176:177], v[122:123], v[130:131] op_sel_hi:[1,0,1] neg_lo:[1,0,0] neg_hi:[1,0,0]
	v_pk_fma_f32 v[130:131], v[178:179], v[122:123], v[130:131] op_sel:[0,1,0] neg_lo:[1,0,0] neg_hi:[1,0,0]
	ds_read_b128 v[172:175], v228 offset:8352
	ds_read_b128 v[176:179], v228 offset:8368
	s_waitcnt lgkmcnt(14)
	v_pk_fma_f32 v[130:131], v[180:181], v[124:125], v[130:131] op_sel_hi:[1,0,1] neg_lo:[1,0,0] neg_hi:[1,0,0]
	v_pk_fma_f32 v[130:131], v[182:183], v[124:125], v[130:131] op_sel:[0,1,0] neg_lo:[1,0,0] neg_hi:[1,0,0]
	v_pk_fma_f32 v[130:131], v[184:185], v[126:127], v[130:131] op_sel_hi:[1,0,1] neg_lo:[1,0,0] neg_hi:[1,0,0]
	v_pk_fma_f32 v[130:131], v[186:187], v[126:127], v[130:131] op_sel:[0,1,0] neg_lo:[1,0,0] neg_hi:[1,0,0]
	ds_read_b128 v[180:183], v228 offset:8384
	ds_read_b128 v[184:187], v228 offset:8400
	s_waitcnt lgkmcnt(14)
	v_pk_fma_f32 v[130:131], v[188:189], v[128:129], v[130:131] op_sel_hi:[1,0,1] neg_lo:[1,0,0] neg_hi:[1,0,0]
	v_pk_fma_f32 v[130:131], v[190:191], v[128:129], v[130:131] op_sel:[0,1,0] neg_lo:[1,0,0] neg_hi:[1,0,0]
	v_fma_f32 v131, -v193, v130, v131
	ds_read_b128 v[188:191], v228 offset:8416
	ds_read_b128 v[192:195], v228 offset:8432
	s_waitcnt lgkmcnt(14)
	v_pk_fma_f32 v[132:133], v[196:197], v[100:101], v[132:133] op_sel_hi:[1,0,1] neg_lo:[1,0,0] neg_hi:[1,0,0]
	v_pk_fma_f32 v[132:133], v[198:199], v[100:101], v[132:133] op_sel:[0,1,0] neg_lo:[1,0,0] neg_hi:[1,0,0]
	v_pk_fma_f32 v[132:133], v[200:201], v[102:103], v[132:133] op_sel_hi:[1,0,1] neg_lo:[1,0,0] neg_hi:[1,0,0]
	v_pk_fma_f32 v[132:133], v[202:203], v[102:103], v[132:133] op_sel:[0,1,0] neg_lo:[1,0,0] neg_hi:[1,0,0]
	ds_read_b128 v[196:199], v228 offset:8448
	ds_read_b128 v[200:203], v228 offset:8704
	s_waitcnt lgkmcnt(14)
	v_pk_fma_f32 v[132:133], v[204:205], v[104:105], v[132:133] op_sel_hi:[1,0,1] neg_lo:[1,0,0] neg_hi:[1,0,0]
	v_pk_fma_f32 v[132:133], v[206:207], v[104:105], v[132:133] op_sel:[0,1,0] neg_lo:[1,0,0] neg_hi:[1,0,0]
	v_pk_fma_f32 v[132:133], v[208:209], v[106:107], v[132:133] op_sel_hi:[1,0,1] neg_lo:[1,0,0] neg_hi:[1,0,0]
	v_pk_fma_f32 v[132:133], v[210:211], v[106:107], v[132:133] op_sel:[0,1,0] neg_lo:[1,0,0] neg_hi:[1,0,0]
	ds_read_b128 v[204:207], v228 offset:8720
	ds_read_b128 v[208:211], v228 offset:8736
	s_waitcnt lgkmcnt(14)
	v_pk_fma_f32 v[132:133], v[212:213], v[108:109], v[132:133] op_sel_hi:[1,0,1] neg_lo:[1,0,0] neg_hi:[1,0,0]
	v_pk_fma_f32 v[132:133], v[214:215], v[108:109], v[132:133] op_sel:[0,1,0] neg_lo:[1,0,0] neg_hi:[1,0,0]
	v_pk_fma_f32 v[132:133], v[216:217], v[110:111], v[132:133] op_sel_hi:[1,0,1] neg_lo:[1,0,0] neg_hi:[1,0,0]
	v_pk_fma_f32 v[132:133], v[218:219], v[110:111], v[132:133] op_sel:[0,1,0] neg_lo:[1,0,0] neg_hi:[1,0,0]
	ds_read_b128 v[212:215], v228 offset:8752
	ds_read_b128 v[216:219], v228 offset:8768
	s_waitcnt lgkmcnt(14)
	v_pk_fma_f32 v[132:133], v[220:221], v[112:113], v[132:133] op_sel_hi:[1,0,1] neg_lo:[1,0,0] neg_hi:[1,0,0]
	v_pk_fma_f32 v[132:133], v[222:223], v[112:113], v[132:133] op_sel:[0,1,0] neg_lo:[1,0,0] neg_hi:[1,0,0]
	v_pk_fma_f32 v[132:133], v[224:225], v[114:115], v[132:133] op_sel_hi:[1,0,1] neg_lo:[1,0,0] neg_hi:[1,0,0]
	v_pk_fma_f32 v[132:133], v[226:227], v[114:115], v[132:133] op_sel:[0,1,0] neg_lo:[1,0,0] neg_hi:[1,0,0]
	ds_read_b128 v[220:223], v228 offset:8784
	ds_read_b128 v[224:227], v228 offset:8800
	s_waitcnt lgkmcnt(14)
	v_pk_fma_f32 v[132:133], v[164:165], v[116:117], v[132:133] op_sel_hi:[1,0,1] neg_lo:[1,0,0] neg_hi:[1,0,0]
	v_pk_fma_f32 v[132:133], v[166:167], v[116:117], v[132:133] op_sel:[0,1,0] neg_lo:[1,0,0] neg_hi:[1,0,0]
	v_pk_fma_f32 v[132:133], v[168:169], v[118:119], v[132:133] op_sel_hi:[1,0,1] neg_lo:[1,0,0] neg_hi:[1,0,0]
	v_pk_fma_f32 v[132:133], v[170:171], v[118:119], v[132:133] op_sel:[0,1,0] neg_lo:[1,0,0] neg_hi:[1,0,0]
	ds_read_b128 v[164:167], v228 offset:8816
	ds_read_b128 v[168:171], v228 offset:8832
	s_waitcnt lgkmcnt(14)
	v_pk_fma_f32 v[132:133], v[172:173], v[120:121], v[132:133] op_sel_hi:[1,0,1] neg_lo:[1,0,0] neg_hi:[1,0,0]
	v_pk_fma_f32 v[132:133], v[174:175], v[120:121], v[132:133] op_sel:[0,1,0] neg_lo:[1,0,0] neg_hi:[1,0,0]
	v_pk_fma_f32 v[132:133], v[176:177], v[122:123], v[132:133] op_sel_hi:[1,0,1] neg_lo:[1,0,0] neg_hi:[1,0,0]
	v_pk_fma_f32 v[132:133], v[178:179], v[122:123], v[132:133] op_sel:[0,1,0] neg_lo:[1,0,0] neg_hi:[1,0,0]
	ds_read_b128 v[172:175], v228 offset:8848
	ds_read_b128 v[176:179], v228 offset:8864
	s_waitcnt lgkmcnt(14)
	v_pk_fma_f32 v[132:133], v[180:181], v[124:125], v[132:133] op_sel_hi:[1,0,1] neg_lo:[1,0,0] neg_hi:[1,0,0]
	v_pk_fma_f32 v[132:133], v[182:183], v[124:125], v[132:133] op_sel:[0,1,0] neg_lo:[1,0,0] neg_hi:[1,0,0]
	v_pk_fma_f32 v[132:133], v[184:185], v[126:127], v[132:133] op_sel_hi:[1,0,1] neg_lo:[1,0,0] neg_hi:[1,0,0]
	v_pk_fma_f32 v[132:133], v[186:187], v[126:127], v[132:133] op_sel:[0,1,0] neg_lo:[1,0,0] neg_hi:[1,0,0]
	ds_read_b128 v[180:183], v228 offset:8880
	ds_read_b128 v[184:187], v228 offset:8896
	s_waitcnt lgkmcnt(14)
	v_pk_fma_f32 v[132:133], v[188:189], v[128:129], v[132:133] op_sel_hi:[1,0,1] neg_lo:[1,0,0] neg_hi:[1,0,0]
	v_pk_fma_f32 v[132:133], v[190:191], v[128:129], v[132:133] op_sel:[0,1,0] neg_lo:[1,0,0] neg_hi:[1,0,0]
	v_pk_fma_f32 v[132:133], v[192:193], v[130:131], v[132:133] op_sel_hi:[1,0,1] neg_lo:[1,0,0] neg_hi:[1,0,0]
	v_pk_fma_f32 v[132:133], v[194:195], v[130:131], v[132:133] op_sel:[0,1,0] neg_lo:[1,0,0] neg_hi:[1,0,0]
	ds_read_b128 v[188:191], v228 offset:8912
	ds_read_b128 v[192:195], v228 offset:8928
	s_waitcnt lgkmcnt(14)
	v_fma_f32 v133, -v197, v132, v133
	v_pk_fma_f32 v[134:135], v[200:201], v[100:101], v[134:135] op_sel_hi:[1,0,1] neg_lo:[1,0,0] neg_hi:[1,0,0]
	v_pk_fma_f32 v[134:135], v[202:203], v[100:101], v[134:135] op_sel:[0,1,0] neg_lo:[1,0,0] neg_hi:[1,0,0]
	ds_read_b128 v[196:199], v228 offset:8944
	ds_read_b128 v[200:203], v228 offset:8960
	s_waitcnt lgkmcnt(14)
	v_pk_fma_f32 v[134:135], v[204:205], v[102:103], v[134:135] op_sel_hi:[1,0,1] neg_lo:[1,0,0] neg_hi:[1,0,0]
	v_pk_fma_f32 v[134:135], v[206:207], v[102:103], v[134:135] op_sel:[0,1,0] neg_lo:[1,0,0] neg_hi:[1,0,0]
	v_pk_fma_f32 v[134:135], v[208:209], v[104:105], v[134:135] op_sel_hi:[1,0,1] neg_lo:[1,0,0] neg_hi:[1,0,0]
	v_pk_fma_f32 v[134:135], v[210:211], v[104:105], v[134:135] op_sel:[0,1,0] neg_lo:[1,0,0] neg_hi:[1,0,0]
	ds_read_b128 v[204:207], v228 offset:8976
	ds_read_b128 v[208:211], v228 offset:9216
	s_waitcnt lgkmcnt(14)
	v_pk_fma_f32 v[134:135], v[212:213], v[106:107], v[134:135] op_sel_hi:[1,0,1] neg_lo:[1,0,0] neg_hi:[1,0,0]
	v_pk_fma_f32 v[134:135], v[214:215], v[106:107], v[134:135] op_sel:[0,1,0] neg_lo:[1,0,0] neg_hi:[1,0,0]
	v_pk_fma_f32 v[134:135], v[216:217], v[108:109], v[134:135] op_sel_hi:[1,0,1] neg_lo:[1,0,0] neg_hi:[1,0,0]
	v_pk_fma_f32 v[134:135], v[218:219], v[108:109], v[134:135] op_sel:[0,1,0] neg_lo:[1,0,0] neg_hi:[1,0,0]
	ds_read_b128 v[212:215], v228 offset:9232
	ds_read_b128 v[216:219], v228 offset:9248
	s_waitcnt lgkmcnt(14)
	v_pk_fma_f32 v[134:135], v[220:221], v[110:111], v[134:135] op_sel_hi:[1,0,1] neg_lo:[1,0,0] neg_hi:[1,0,0]
	v_pk_fma_f32 v[134:135], v[222:223], v[110:111], v[134:135] op_sel:[0,1,0] neg_lo:[1,0,0] neg_hi:[1,0,0]
	v_pk_fma_f32 v[134:135], v[224:225], v[112:113], v[134:135] op_sel_hi:[1,0,1] neg_lo:[1,0,0] neg_hi:[1,0,0]
	v_pk_fma_f32 v[134:135], v[226:227], v[112:113], v[134:135] op_sel:[0,1,0] neg_lo:[1,0,0] neg_hi:[1,0,0]
	ds_read_b128 v[220:223], v228 offset:9264
	ds_read_b128 v[224:227], v228 offset:9280
	s_waitcnt lgkmcnt(14)
	v_pk_fma_f32 v[134:135], v[164:165], v[114:115], v[134:135] op_sel_hi:[1,0,1] neg_lo:[1,0,0] neg_hi:[1,0,0]
	v_pk_fma_f32 v[134:135], v[166:167], v[114:115], v[134:135] op_sel:[0,1,0] neg_lo:[1,0,0] neg_hi:[1,0,0]
	v_pk_fma_f32 v[134:135], v[168:169], v[116:117], v[134:135] op_sel_hi:[1,0,1] neg_lo:[1,0,0] neg_hi:[1,0,0]
	v_pk_fma_f32 v[134:135], v[170:171], v[116:117], v[134:135] op_sel:[0,1,0] neg_lo:[1,0,0] neg_hi:[1,0,0]
	ds_read_b128 v[164:167], v228 offset:9296
	ds_read_b128 v[168:171], v228 offset:9312
	s_waitcnt lgkmcnt(14)
	v_pk_fma_f32 v[134:135], v[172:173], v[118:119], v[134:135] op_sel_hi:[1,0,1] neg_lo:[1,0,0] neg_hi:[1,0,0]
	v_pk_fma_f32 v[134:135], v[174:175], v[118:119], v[134:135] op_sel:[0,1,0] neg_lo:[1,0,0] neg_hi:[1,0,0]
	v_pk_fma_f32 v[134:135], v[176:177], v[120:121], v[134:135] op_sel_hi:[1,0,1] neg_lo:[1,0,0] neg_hi:[1,0,0]
	v_pk_fma_f32 v[134:135], v[178:179], v[120:121], v[134:135] op_sel:[0,1,0] neg_lo:[1,0,0] neg_hi:[1,0,0]
	ds_read_b128 v[172:175], v228 offset:9328
	ds_read_b128 v[176:179], v228 offset:9344
	s_waitcnt lgkmcnt(14)
	v_pk_fma_f32 v[134:135], v[180:181], v[122:123], v[134:135] op_sel_hi:[1,0,1] neg_lo:[1,0,0] neg_hi:[1,0,0]
	v_pk_fma_f32 v[134:135], v[182:183], v[122:123], v[134:135] op_sel:[0,1,0] neg_lo:[1,0,0] neg_hi:[1,0,0]
	v_pk_fma_f32 v[134:135], v[184:185], v[124:125], v[134:135] op_sel_hi:[1,0,1] neg_lo:[1,0,0] neg_hi:[1,0,0]
	v_pk_fma_f32 v[134:135], v[186:187], v[124:125], v[134:135] op_sel:[0,1,0] neg_lo:[1,0,0] neg_hi:[1,0,0]
	ds_read_b128 v[180:183], v228 offset:9360
	ds_read_b128 v[184:187], v228 offset:9376
	s_waitcnt lgkmcnt(14)
	v_pk_fma_f32 v[134:135], v[188:189], v[126:127], v[134:135] op_sel_hi:[1,0,1] neg_lo:[1,0,0] neg_hi:[1,0,0]
	v_pk_fma_f32 v[134:135], v[190:191], v[126:127], v[134:135] op_sel:[0,1,0] neg_lo:[1,0,0] neg_hi:[1,0,0]
	v_pk_fma_f32 v[134:135], v[192:193], v[128:129], v[134:135] op_sel_hi:[1,0,1] neg_lo:[1,0,0] neg_hi:[1,0,0]
	v_pk_fma_f32 v[134:135], v[194:195], v[128:129], v[134:135] op_sel:[0,1,0] neg_lo:[1,0,0] neg_hi:[1,0,0]
	ds_read_b128 v[188:191], v228 offset:9392
	ds_read_b128 v[192:195], v228 offset:9408
	s_waitcnt lgkmcnt(14)
	v_pk_fma_f32 v[134:135], v[196:197], v[130:131], v[134:135] op_sel_hi:[1,0,1] neg_lo:[1,0,0] neg_hi:[1,0,0]
	v_pk_fma_f32 v[134:135], v[198:199], v[130:131], v[134:135] op_sel:[0,1,0] neg_lo:[1,0,0] neg_hi:[1,0,0]
	v_pk_fma_f32 v[134:135], v[200:201], v[132:133], v[134:135] op_sel_hi:[1,0,1] neg_lo:[1,0,0] neg_hi:[1,0,0]
	v_pk_fma_f32 v[134:135], v[202:203], v[132:133], v[134:135] op_sel:[0,1,0] neg_lo:[1,0,0] neg_hi:[1,0,0]
	ds_read_b128 v[196:199], v228 offset:9424
	ds_read_b128 v[200:203], v228 offset:9440
	s_waitcnt lgkmcnt(14)
	v_fma_f32 v135, -v205, v134, v135
	v_pk_fma_f32 v[136:137], v[208:209], v[100:101], v[136:137] op_sel_hi:[1,0,1] neg_lo:[1,0,0] neg_hi:[1,0,0]
	v_pk_fma_f32 v[136:137], v[210:211], v[100:101], v[136:137] op_sel:[0,1,0] neg_lo:[1,0,0] neg_hi:[1,0,0]
	ds_read_b128 v[204:207], v228 offset:9456
	ds_read_b128 v[208:211], v228 offset:9472
	s_waitcnt lgkmcnt(14)
	v_pk_fma_f32 v[136:137], v[212:213], v[102:103], v[136:137] op_sel_hi:[1,0,1] neg_lo:[1,0,0] neg_hi:[1,0,0]
	v_pk_fma_f32 v[136:137], v[214:215], v[102:103], v[136:137] op_sel:[0,1,0] neg_lo:[1,0,0] neg_hi:[1,0,0]
	v_pk_fma_f32 v[136:137], v[216:217], v[104:105], v[136:137] op_sel_hi:[1,0,1] neg_lo:[1,0,0] neg_hi:[1,0,0]
	v_pk_fma_f32 v[136:137], v[218:219], v[104:105], v[136:137] op_sel:[0,1,0] neg_lo:[1,0,0] neg_hi:[1,0,0]
	ds_read_b128 v[212:215], v228 offset:9488
	ds_read_b128 v[216:219], v228 offset:9504
	s_waitcnt lgkmcnt(14)
	v_pk_fma_f32 v[136:137], v[220:221], v[106:107], v[136:137] op_sel_hi:[1,0,1] neg_lo:[1,0,0] neg_hi:[1,0,0]
	v_pk_fma_f32 v[136:137], v[222:223], v[106:107], v[136:137] op_sel:[0,1,0] neg_lo:[1,0,0] neg_hi:[1,0,0]
	v_pk_fma_f32 v[136:137], v[224:225], v[108:109], v[136:137] op_sel_hi:[1,0,1] neg_lo:[1,0,0] neg_hi:[1,0,0]
	v_pk_fma_f32 v[136:137], v[226:227], v[108:109], v[136:137] op_sel:[0,1,0] neg_lo:[1,0,0] neg_hi:[1,0,0]
	ds_read_b128 v[220:223], v228 offset:9728
	ds_read_b128 v[224:227], v228 offset:9744
	s_waitcnt lgkmcnt(14)
	v_pk_fma_f32 v[136:137], v[164:165], v[110:111], v[136:137] op_sel_hi:[1,0,1] neg_lo:[1,0,0] neg_hi:[1,0,0]
	v_pk_fma_f32 v[136:137], v[166:167], v[110:111], v[136:137] op_sel:[0,1,0] neg_lo:[1,0,0] neg_hi:[1,0,0]
	v_pk_fma_f32 v[136:137], v[168:169], v[112:113], v[136:137] op_sel_hi:[1,0,1] neg_lo:[1,0,0] neg_hi:[1,0,0]
	v_pk_fma_f32 v[136:137], v[170:171], v[112:113], v[136:137] op_sel:[0,1,0] neg_lo:[1,0,0] neg_hi:[1,0,0]
	ds_read_b128 v[164:167], v228 offset:9760
	ds_read_b128 v[168:171], v228 offset:9776
	s_waitcnt lgkmcnt(14)
	v_pk_fma_f32 v[136:137], v[172:173], v[114:115], v[136:137] op_sel_hi:[1,0,1] neg_lo:[1,0,0] neg_hi:[1,0,0]
	v_pk_fma_f32 v[136:137], v[174:175], v[114:115], v[136:137] op_sel:[0,1,0] neg_lo:[1,0,0] neg_hi:[1,0,0]
	v_pk_fma_f32 v[136:137], v[176:177], v[116:117], v[136:137] op_sel_hi:[1,0,1] neg_lo:[1,0,0] neg_hi:[1,0,0]
	v_pk_fma_f32 v[136:137], v[178:179], v[116:117], v[136:137] op_sel:[0,1,0] neg_lo:[1,0,0] neg_hi:[1,0,0]
	ds_read_b128 v[172:175], v228 offset:9792
	ds_read_b128 v[176:179], v228 offset:9808
	s_waitcnt lgkmcnt(14)
	v_pk_fma_f32 v[136:137], v[180:181], v[118:119], v[136:137] op_sel_hi:[1,0,1] neg_lo:[1,0,0] neg_hi:[1,0,0]
	v_pk_fma_f32 v[136:137], v[182:183], v[118:119], v[136:137] op_sel:[0,1,0] neg_lo:[1,0,0] neg_hi:[1,0,0]
	v_pk_fma_f32 v[136:137], v[184:185], v[120:121], v[136:137] op_sel_hi:[1,0,1] neg_lo:[1,0,0] neg_hi:[1,0,0]
	v_pk_fma_f32 v[136:137], v[186:187], v[120:121], v[136:137] op_sel:[0,1,0] neg_lo:[1,0,0] neg_hi:[1,0,0]
	ds_read_b128 v[180:183], v228 offset:9824
	ds_read_b128 v[184:187], v228 offset:9840
	s_waitcnt lgkmcnt(14)
	v_pk_fma_f32 v[136:137], v[188:189], v[122:123], v[136:137] op_sel_hi:[1,0,1] neg_lo:[1,0,0] neg_hi:[1,0,0]
	v_pk_fma_f32 v[136:137], v[190:191], v[122:123], v[136:137] op_sel:[0,1,0] neg_lo:[1,0,0] neg_hi:[1,0,0]
	v_pk_fma_f32 v[136:137], v[192:193], v[124:125], v[136:137] op_sel_hi:[1,0,1] neg_lo:[1,0,0] neg_hi:[1,0,0]
	v_pk_fma_f32 v[136:137], v[194:195], v[124:125], v[136:137] op_sel:[0,1,0] neg_lo:[1,0,0] neg_hi:[1,0,0]
	ds_read_b128 v[188:191], v228 offset:9856
	ds_read_b128 v[192:195], v228 offset:9872
	s_waitcnt lgkmcnt(14)
	v_pk_fma_f32 v[136:137], v[196:197], v[126:127], v[136:137] op_sel_hi:[1,0,1] neg_lo:[1,0,0] neg_hi:[1,0,0]
	v_pk_fma_f32 v[136:137], v[198:199], v[126:127], v[136:137] op_sel:[0,1,0] neg_lo:[1,0,0] neg_hi:[1,0,0]
	v_pk_fma_f32 v[136:137], v[200:201], v[128:129], v[136:137] op_sel_hi:[1,0,1] neg_lo:[1,0,0] neg_hi:[1,0,0]
	v_pk_fma_f32 v[136:137], v[202:203], v[128:129], v[136:137] op_sel:[0,1,0] neg_lo:[1,0,0] neg_hi:[1,0,0]
	ds_read_b128 v[196:199], v228 offset:9888
	ds_read_b128 v[200:203], v228 offset:9904
	s_waitcnt lgkmcnt(14)
	v_pk_fma_f32 v[136:137], v[204:205], v[130:131], v[136:137] op_sel_hi:[1,0,1] neg_lo:[1,0,0] neg_hi:[1,0,0]
	v_pk_fma_f32 v[136:137], v[206:207], v[130:131], v[136:137] op_sel:[0,1,0] neg_lo:[1,0,0] neg_hi:[1,0,0]
	v_pk_fma_f32 v[136:137], v[208:209], v[132:133], v[136:137] op_sel_hi:[1,0,1] neg_lo:[1,0,0] neg_hi:[1,0,0]
	v_pk_fma_f32 v[136:137], v[210:211], v[132:133], v[136:137] op_sel:[0,1,0] neg_lo:[1,0,0] neg_hi:[1,0,0]
	ds_read_b128 v[204:207], v228 offset:9920
	ds_read_b128 v[208:211], v228 offset:9936
	s_waitcnt lgkmcnt(14)
	v_pk_fma_f32 v[136:137], v[212:213], v[134:135], v[136:137] op_sel_hi:[1,0,1] neg_lo:[1,0,0] neg_hi:[1,0,0]
	v_pk_fma_f32 v[136:137], v[214:215], v[134:135], v[136:137] op_sel:[0,1,0] neg_lo:[1,0,0] neg_hi:[1,0,0]
	v_fma_f32 v137, -v217, v136, v137
	ds_read_b128 v[212:215], v228 offset:9952
	ds_read_b128 v[216:219], v228 offset:9968
	s_waitcnt lgkmcnt(14)
	v_pk_fma_f32 v[138:139], v[220:221], v[100:101], v[138:139] op_sel_hi:[1,0,1] neg_lo:[1,0,0] neg_hi:[1,0,0]
	v_pk_fma_f32 v[138:139], v[222:223], v[100:101], v[138:139] op_sel:[0,1,0] neg_lo:[1,0,0] neg_hi:[1,0,0]
	v_pk_fma_f32 v[138:139], v[224:225], v[102:103], v[138:139] op_sel_hi:[1,0,1] neg_lo:[1,0,0] neg_hi:[1,0,0]
	v_pk_fma_f32 v[138:139], v[226:227], v[102:103], v[138:139] op_sel:[0,1,0] neg_lo:[1,0,0] neg_hi:[1,0,0]
	ds_read_b128 v[220:223], v228 offset:9984
	ds_read_b128 v[224:227], v228 offset:10000
	s_waitcnt lgkmcnt(14)
	v_pk_fma_f32 v[138:139], v[164:165], v[104:105], v[138:139] op_sel_hi:[1,0,1] neg_lo:[1,0,0] neg_hi:[1,0,0]
	v_pk_fma_f32 v[138:139], v[166:167], v[104:105], v[138:139] op_sel:[0,1,0] neg_lo:[1,0,0] neg_hi:[1,0,0]
	v_pk_fma_f32 v[138:139], v[168:169], v[106:107], v[138:139] op_sel_hi:[1,0,1] neg_lo:[1,0,0] neg_hi:[1,0,0]
	v_pk_fma_f32 v[138:139], v[170:171], v[106:107], v[138:139] op_sel:[0,1,0] neg_lo:[1,0,0] neg_hi:[1,0,0]
	ds_read_b128 v[164:167], v228 offset:10016
	ds_read_b128 v[168:171], v228 offset:10032
	s_waitcnt lgkmcnt(14)
	v_pk_fma_f32 v[138:139], v[172:173], v[108:109], v[138:139] op_sel_hi:[1,0,1] neg_lo:[1,0,0] neg_hi:[1,0,0]
	v_pk_fma_f32 v[138:139], v[174:175], v[108:109], v[138:139] op_sel:[0,1,0] neg_lo:[1,0,0] neg_hi:[1,0,0]
	v_pk_fma_f32 v[138:139], v[176:177], v[110:111], v[138:139] op_sel_hi:[1,0,1] neg_lo:[1,0,0] neg_hi:[1,0,0]
	v_pk_fma_f32 v[138:139], v[178:179], v[110:111], v[138:139] op_sel:[0,1,0] neg_lo:[1,0,0] neg_hi:[1,0,0]
	ds_read_b128 v[172:175], v228 offset:10240
	ds_read_b128 v[176:179], v228 offset:10256
	s_waitcnt lgkmcnt(14)
	v_pk_fma_f32 v[138:139], v[180:181], v[112:113], v[138:139] op_sel_hi:[1,0,1] neg_lo:[1,0,0] neg_hi:[1,0,0]
	v_pk_fma_f32 v[138:139], v[182:183], v[112:113], v[138:139] op_sel:[0,1,0] neg_lo:[1,0,0] neg_hi:[1,0,0]
	v_pk_fma_f32 v[138:139], v[184:185], v[114:115], v[138:139] op_sel_hi:[1,0,1] neg_lo:[1,0,0] neg_hi:[1,0,0]
	v_pk_fma_f32 v[138:139], v[186:187], v[114:115], v[138:139] op_sel:[0,1,0] neg_lo:[1,0,0] neg_hi:[1,0,0]
	ds_read_b128 v[180:183], v228 offset:10272
	ds_read_b128 v[184:187], v228 offset:10288
	s_waitcnt lgkmcnt(14)
	v_pk_fma_f32 v[138:139], v[188:189], v[116:117], v[138:139] op_sel_hi:[1,0,1] neg_lo:[1,0,0] neg_hi:[1,0,0]
	v_pk_fma_f32 v[138:139], v[190:191], v[116:117], v[138:139] op_sel:[0,1,0] neg_lo:[1,0,0] neg_hi:[1,0,0]
	v_pk_fma_f32 v[138:139], v[192:193], v[118:119], v[138:139] op_sel_hi:[1,0,1] neg_lo:[1,0,0] neg_hi:[1,0,0]
	v_pk_fma_f32 v[138:139], v[194:195], v[118:119], v[138:139] op_sel:[0,1,0] neg_lo:[1,0,0] neg_hi:[1,0,0]
	ds_read_b128 v[188:191], v228 offset:10304
	ds_read_b128 v[192:195], v228 offset:10320
	s_waitcnt lgkmcnt(14)
	v_pk_fma_f32 v[138:139], v[196:197], v[120:121], v[138:139] op_sel_hi:[1,0,1] neg_lo:[1,0,0] neg_hi:[1,0,0]
	v_pk_fma_f32 v[138:139], v[198:199], v[120:121], v[138:139] op_sel:[0,1,0] neg_lo:[1,0,0] neg_hi:[1,0,0]
	v_pk_fma_f32 v[138:139], v[200:201], v[122:123], v[138:139] op_sel_hi:[1,0,1] neg_lo:[1,0,0] neg_hi:[1,0,0]
	v_pk_fma_f32 v[138:139], v[202:203], v[122:123], v[138:139] op_sel:[0,1,0] neg_lo:[1,0,0] neg_hi:[1,0,0]
	ds_read_b128 v[196:199], v228 offset:10336
	ds_read_b128 v[200:203], v228 offset:10352
	s_waitcnt lgkmcnt(14)
	v_pk_fma_f32 v[138:139], v[204:205], v[124:125], v[138:139] op_sel_hi:[1,0,1] neg_lo:[1,0,0] neg_hi:[1,0,0]
	v_pk_fma_f32 v[138:139], v[206:207], v[124:125], v[138:139] op_sel:[0,1,0] neg_lo:[1,0,0] neg_hi:[1,0,0]
	v_pk_fma_f32 v[138:139], v[208:209], v[126:127], v[138:139] op_sel_hi:[1,0,1] neg_lo:[1,0,0] neg_hi:[1,0,0]
	v_pk_fma_f32 v[138:139], v[210:211], v[126:127], v[138:139] op_sel:[0,1,0] neg_lo:[1,0,0] neg_hi:[1,0,0]
	ds_read_b128 v[204:207], v228 offset:10368
	ds_read_b128 v[208:211], v228 offset:10384
	s_waitcnt lgkmcnt(14)
	v_pk_fma_f32 v[138:139], v[212:213], v[128:129], v[138:139] op_sel_hi:[1,0,1] neg_lo:[1,0,0] neg_hi:[1,0,0]
	v_pk_fma_f32 v[138:139], v[214:215], v[128:129], v[138:139] op_sel:[0,1,0] neg_lo:[1,0,0] neg_hi:[1,0,0]
	v_pk_fma_f32 v[138:139], v[216:217], v[130:131], v[138:139] op_sel_hi:[1,0,1] neg_lo:[1,0,0] neg_hi:[1,0,0]
	v_pk_fma_f32 v[138:139], v[218:219], v[130:131], v[138:139] op_sel:[0,1,0] neg_lo:[1,0,0] neg_hi:[1,0,0]
	ds_read_b128 v[212:215], v228 offset:10400
	ds_read_b128 v[216:219], v228 offset:10416
	s_waitcnt lgkmcnt(14)
	v_pk_fma_f32 v[138:139], v[220:221], v[132:133], v[138:139] op_sel_hi:[1,0,1] neg_lo:[1,0,0] neg_hi:[1,0,0]
	v_pk_fma_f32 v[138:139], v[222:223], v[132:133], v[138:139] op_sel:[0,1,0] neg_lo:[1,0,0] neg_hi:[1,0,0]
	v_pk_fma_f32 v[138:139], v[224:225], v[134:135], v[138:139] op_sel_hi:[1,0,1] neg_lo:[1,0,0] neg_hi:[1,0,0]
	v_pk_fma_f32 v[138:139], v[226:227], v[134:135], v[138:139] op_sel:[0,1,0] neg_lo:[1,0,0] neg_hi:[1,0,0]
	ds_read_b128 v[220:223], v228 offset:10432
	ds_read_b128 v[224:227], v228 offset:10448
	s_waitcnt lgkmcnt(14)
	v_pk_fma_f32 v[138:139], v[164:165], v[136:137], v[138:139] op_sel_hi:[1,0,1] neg_lo:[1,0,0] neg_hi:[1,0,0]
	v_pk_fma_f32 v[138:139], v[166:167], v[136:137], v[138:139] op_sel:[0,1,0] neg_lo:[1,0,0] neg_hi:[1,0,0]
	v_fma_f32 v139, -v169, v138, v139
	ds_read_b128 v[164:167], v228 offset:10464
	ds_read_b128 v[168:171], v228 offset:10480
	s_waitcnt lgkmcnt(14)
	v_pk_fma_f32 v[140:141], v[172:173], v[100:101], v[140:141] op_sel_hi:[1,0,1] neg_lo:[1,0,0] neg_hi:[1,0,0]
	v_pk_fma_f32 v[140:141], v[174:175], v[100:101], v[140:141] op_sel:[0,1,0] neg_lo:[1,0,0] neg_hi:[1,0,0]
	v_pk_fma_f32 v[140:141], v[176:177], v[102:103], v[140:141] op_sel_hi:[1,0,1] neg_lo:[1,0,0] neg_hi:[1,0,0]
	v_pk_fma_f32 v[140:141], v[178:179], v[102:103], v[140:141] op_sel:[0,1,0] neg_lo:[1,0,0] neg_hi:[1,0,0]
	ds_read_b128 v[172:175], v228 offset:10496
	ds_read_b128 v[176:179], v228 offset:10512
	s_waitcnt lgkmcnt(14)
	v_pk_fma_f32 v[140:141], v[180:181], v[104:105], v[140:141] op_sel_hi:[1,0,1] neg_lo:[1,0,0] neg_hi:[1,0,0]
	v_pk_fma_f32 v[140:141], v[182:183], v[104:105], v[140:141] op_sel:[0,1,0] neg_lo:[1,0,0] neg_hi:[1,0,0]
	v_pk_fma_f32 v[140:141], v[184:185], v[106:107], v[140:141] op_sel_hi:[1,0,1] neg_lo:[1,0,0] neg_hi:[1,0,0]
	v_pk_fma_f32 v[140:141], v[186:187], v[106:107], v[140:141] op_sel:[0,1,0] neg_lo:[1,0,0] neg_hi:[1,0,0]
	ds_read_b128 v[180:183], v228 offset:10528
	ds_read_b128 v[184:187], v228 offset:10544
	s_waitcnt lgkmcnt(14)
	v_pk_fma_f32 v[140:141], v[188:189], v[108:109], v[140:141] op_sel_hi:[1,0,1] neg_lo:[1,0,0] neg_hi:[1,0,0]
	v_pk_fma_f32 v[140:141], v[190:191], v[108:109], v[140:141] op_sel:[0,1,0] neg_lo:[1,0,0] neg_hi:[1,0,0]
	v_pk_fma_f32 v[140:141], v[192:193], v[110:111], v[140:141] op_sel_hi:[1,0,1] neg_lo:[1,0,0] neg_hi:[1,0,0]
	v_pk_fma_f32 v[140:141], v[194:195], v[110:111], v[140:141] op_sel:[0,1,0] neg_lo:[1,0,0] neg_hi:[1,0,0]
	ds_read_b128 v[188:191], v228 offset:10560
	ds_read_b128 v[192:195], v228 offset:10752
	s_waitcnt lgkmcnt(14)
	v_pk_fma_f32 v[140:141], v[196:197], v[112:113], v[140:141] op_sel_hi:[1,0,1] neg_lo:[1,0,0] neg_hi:[1,0,0]
	v_pk_fma_f32 v[140:141], v[198:199], v[112:113], v[140:141] op_sel:[0,1,0] neg_lo:[1,0,0] neg_hi:[1,0,0]
	v_pk_fma_f32 v[140:141], v[200:201], v[114:115], v[140:141] op_sel_hi:[1,0,1] neg_lo:[1,0,0] neg_hi:[1,0,0]
	v_pk_fma_f32 v[140:141], v[202:203], v[114:115], v[140:141] op_sel:[0,1,0] neg_lo:[1,0,0] neg_hi:[1,0,0]
	ds_read_b128 v[196:199], v228 offset:10768
	ds_read_b128 v[200:203], v228 offset:10784
	s_waitcnt lgkmcnt(14)
	v_pk_fma_f32 v[140:141], v[204:205], v[116:117], v[140:141] op_sel_hi:[1,0,1] neg_lo:[1,0,0] neg_hi:[1,0,0]
	v_pk_fma_f32 v[140:141], v[206:207], v[116:117], v[140:141] op_sel:[0,1,0] neg_lo:[1,0,0] neg_hi:[1,0,0]
	v_pk_fma_f32 v[140:141], v[208:209], v[118:119], v[140:141] op_sel_hi:[1,0,1] neg_lo:[1,0,0] neg_hi:[1,0,0]
	v_pk_fma_f32 v[140:141], v[210:211], v[118:119], v[140:141] op_sel:[0,1,0] neg_lo:[1,0,0] neg_hi:[1,0,0]
	ds_read_b128 v[204:207], v228 offset:10800
	ds_read_b128 v[208:211], v228 offset:10816
	s_waitcnt lgkmcnt(14)
	v_pk_fma_f32 v[140:141], v[212:213], v[120:121], v[140:141] op_sel_hi:[1,0,1] neg_lo:[1,0,0] neg_hi:[1,0,0]
	v_pk_fma_f32 v[140:141], v[214:215], v[120:121], v[140:141] op_sel:[0,1,0] neg_lo:[1,0,0] neg_hi:[1,0,0]
	v_pk_fma_f32 v[140:141], v[216:217], v[122:123], v[140:141] op_sel_hi:[1,0,1] neg_lo:[1,0,0] neg_hi:[1,0,0]
	v_pk_fma_f32 v[140:141], v[218:219], v[122:123], v[140:141] op_sel:[0,1,0] neg_lo:[1,0,0] neg_hi:[1,0,0]
	ds_read_b128 v[212:215], v228 offset:10832
	ds_read_b128 v[216:219], v228 offset:10848
	s_waitcnt lgkmcnt(14)
	v_pk_fma_f32 v[140:141], v[220:221], v[124:125], v[140:141] op_sel_hi:[1,0,1] neg_lo:[1,0,0] neg_hi:[1,0,0]
	v_pk_fma_f32 v[140:141], v[222:223], v[124:125], v[140:141] op_sel:[0,1,0] neg_lo:[1,0,0] neg_hi:[1,0,0]
	v_pk_fma_f32 v[140:141], v[224:225], v[126:127], v[140:141] op_sel_hi:[1,0,1] neg_lo:[1,0,0] neg_hi:[1,0,0]
	v_pk_fma_f32 v[140:141], v[226:227], v[126:127], v[140:141] op_sel:[0,1,0] neg_lo:[1,0,0] neg_hi:[1,0,0]
	ds_read_b128 v[220:223], v228 offset:10864
	ds_read_b128 v[224:227], v228 offset:10880
	s_waitcnt lgkmcnt(14)
	v_pk_fma_f32 v[140:141], v[164:165], v[128:129], v[140:141] op_sel_hi:[1,0,1] neg_lo:[1,0,0] neg_hi:[1,0,0]
	v_pk_fma_f32 v[140:141], v[166:167], v[128:129], v[140:141] op_sel:[0,1,0] neg_lo:[1,0,0] neg_hi:[1,0,0]
	v_pk_fma_f32 v[140:141], v[168:169], v[130:131], v[140:141] op_sel_hi:[1,0,1] neg_lo:[1,0,0] neg_hi:[1,0,0]
	v_pk_fma_f32 v[140:141], v[170:171], v[130:131], v[140:141] op_sel:[0,1,0] neg_lo:[1,0,0] neg_hi:[1,0,0]
	ds_read_b128 v[164:167], v228 offset:10896
	ds_read_b128 v[168:171], v228 offset:10912
	s_waitcnt lgkmcnt(14)
	v_pk_fma_f32 v[140:141], v[172:173], v[132:133], v[140:141] op_sel_hi:[1,0,1] neg_lo:[1,0,0] neg_hi:[1,0,0]
	v_pk_fma_f32 v[140:141], v[174:175], v[132:133], v[140:141] op_sel:[0,1,0] neg_lo:[1,0,0] neg_hi:[1,0,0]
	v_pk_fma_f32 v[140:141], v[176:177], v[134:135], v[140:141] op_sel_hi:[1,0,1] neg_lo:[1,0,0] neg_hi:[1,0,0]
	v_pk_fma_f32 v[140:141], v[178:179], v[134:135], v[140:141] op_sel:[0,1,0] neg_lo:[1,0,0] neg_hi:[1,0,0]
	ds_read_b128 v[172:175], v228 offset:10928
	ds_read_b128 v[176:179], v228 offset:10944
	s_waitcnt lgkmcnt(14)
	v_pk_fma_f32 v[140:141], v[180:181], v[136:137], v[140:141] op_sel_hi:[1,0,1] neg_lo:[1,0,0] neg_hi:[1,0,0]
	v_pk_fma_f32 v[140:141], v[182:183], v[136:137], v[140:141] op_sel:[0,1,0] neg_lo:[1,0,0] neg_hi:[1,0,0]
	v_pk_fma_f32 v[140:141], v[184:185], v[138:139], v[140:141] op_sel_hi:[1,0,1] neg_lo:[1,0,0] neg_hi:[1,0,0]
	v_pk_fma_f32 v[140:141], v[186:187], v[138:139], v[140:141] op_sel:[0,1,0] neg_lo:[1,0,0] neg_hi:[1,0,0]
	ds_read_b128 v[180:183], v228 offset:10960
	ds_read_b128 v[184:187], v228 offset:10976
	s_waitcnt lgkmcnt(14)
	v_fma_f32 v141, -v189, v140, v141
	v_pk_fma_f32 v[142:143], v[192:193], v[100:101], v[142:143] op_sel_hi:[1,0,1] neg_lo:[1,0,0] neg_hi:[1,0,0]
	v_pk_fma_f32 v[142:143], v[194:195], v[100:101], v[142:143] op_sel:[0,1,0] neg_lo:[1,0,0] neg_hi:[1,0,0]
	ds_read_b128 v[188:191], v228 offset:10992
	ds_read_b128 v[192:195], v228 offset:11008
	s_waitcnt lgkmcnt(14)
	v_pk_fma_f32 v[142:143], v[196:197], v[102:103], v[142:143] op_sel_hi:[1,0,1] neg_lo:[1,0,0] neg_hi:[1,0,0]
	v_pk_fma_f32 v[142:143], v[198:199], v[102:103], v[142:143] op_sel:[0,1,0] neg_lo:[1,0,0] neg_hi:[1,0,0]
	v_pk_fma_f32 v[142:143], v[200:201], v[104:105], v[142:143] op_sel_hi:[1,0,1] neg_lo:[1,0,0] neg_hi:[1,0,0]
	v_pk_fma_f32 v[142:143], v[202:203], v[104:105], v[142:143] op_sel:[0,1,0] neg_lo:[1,0,0] neg_hi:[1,0,0]
	ds_read_b128 v[196:199], v228 offset:11024
	ds_read_b128 v[200:203], v228 offset:11040
	s_waitcnt lgkmcnt(14)
	v_pk_fma_f32 v[142:143], v[204:205], v[106:107], v[142:143] op_sel_hi:[1,0,1] neg_lo:[1,0,0] neg_hi:[1,0,0]
	v_pk_fma_f32 v[142:143], v[206:207], v[106:107], v[142:143] op_sel:[0,1,0] neg_lo:[1,0,0] neg_hi:[1,0,0]
	v_pk_fma_f32 v[142:143], v[208:209], v[108:109], v[142:143] op_sel_hi:[1,0,1] neg_lo:[1,0,0] neg_hi:[1,0,0]
	v_pk_fma_f32 v[142:143], v[210:211], v[108:109], v[142:143] op_sel:[0,1,0] neg_lo:[1,0,0] neg_hi:[1,0,0]
	ds_read_b128 v[204:207], v228 offset:11056
	ds_read_b128 v[208:211], v228 offset:11072
	s_waitcnt lgkmcnt(14)
	v_pk_fma_f32 v[142:143], v[212:213], v[110:111], v[142:143] op_sel_hi:[1,0,1] neg_lo:[1,0,0] neg_hi:[1,0,0]
	v_pk_fma_f32 v[142:143], v[214:215], v[110:111], v[142:143] op_sel:[0,1,0] neg_lo:[1,0,0] neg_hi:[1,0,0]
	v_pk_fma_f32 v[142:143], v[216:217], v[112:113], v[142:143] op_sel_hi:[1,0,1] neg_lo:[1,0,0] neg_hi:[1,0,0]
	v_pk_fma_f32 v[142:143], v[218:219], v[112:113], v[142:143] op_sel:[0,1,0] neg_lo:[1,0,0] neg_hi:[1,0,0]
	ds_read_b128 v[212:215], v228 offset:11088
	ds_read_b128 v[216:219], v228 offset:11264
	s_waitcnt lgkmcnt(14)
	v_pk_fma_f32 v[142:143], v[220:221], v[114:115], v[142:143] op_sel_hi:[1,0,1] neg_lo:[1,0,0] neg_hi:[1,0,0]
	v_pk_fma_f32 v[142:143], v[222:223], v[114:115], v[142:143] op_sel:[0,1,0] neg_lo:[1,0,0] neg_hi:[1,0,0]
	v_pk_fma_f32 v[142:143], v[224:225], v[116:117], v[142:143] op_sel_hi:[1,0,1] neg_lo:[1,0,0] neg_hi:[1,0,0]
	v_pk_fma_f32 v[142:143], v[226:227], v[116:117], v[142:143] op_sel:[0,1,0] neg_lo:[1,0,0] neg_hi:[1,0,0]
	ds_read_b128 v[220:223], v228 offset:11280
	ds_read_b128 v[224:227], v228 offset:11296
	s_waitcnt lgkmcnt(14)
	v_pk_fma_f32 v[142:143], v[164:165], v[118:119], v[142:143] op_sel_hi:[1,0,1] neg_lo:[1,0,0] neg_hi:[1,0,0]
	v_pk_fma_f32 v[142:143], v[166:167], v[118:119], v[142:143] op_sel:[0,1,0] neg_lo:[1,0,0] neg_hi:[1,0,0]
	v_pk_fma_f32 v[142:143], v[168:169], v[120:121], v[142:143] op_sel_hi:[1,0,1] neg_lo:[1,0,0] neg_hi:[1,0,0]
	v_pk_fma_f32 v[142:143], v[170:171], v[120:121], v[142:143] op_sel:[0,1,0] neg_lo:[1,0,0] neg_hi:[1,0,0]
	ds_read_b128 v[164:167], v228 offset:11312
	ds_read_b128 v[168:171], v228 offset:11328
	s_waitcnt lgkmcnt(14)
	v_pk_fma_f32 v[142:143], v[172:173], v[122:123], v[142:143] op_sel_hi:[1,0,1] neg_lo:[1,0,0] neg_hi:[1,0,0]
	v_pk_fma_f32 v[142:143], v[174:175], v[122:123], v[142:143] op_sel:[0,1,0] neg_lo:[1,0,0] neg_hi:[1,0,0]
	v_pk_fma_f32 v[142:143], v[176:177], v[124:125], v[142:143] op_sel_hi:[1,0,1] neg_lo:[1,0,0] neg_hi:[1,0,0]
	v_pk_fma_f32 v[142:143], v[178:179], v[124:125], v[142:143] op_sel:[0,1,0] neg_lo:[1,0,0] neg_hi:[1,0,0]
	ds_read_b128 v[172:175], v228 offset:11344
	ds_read_b128 v[176:179], v228 offset:11360
	s_waitcnt lgkmcnt(14)
	v_pk_fma_f32 v[142:143], v[180:181], v[126:127], v[142:143] op_sel_hi:[1,0,1] neg_lo:[1,0,0] neg_hi:[1,0,0]
	v_pk_fma_f32 v[142:143], v[182:183], v[126:127], v[142:143] op_sel:[0,1,0] neg_lo:[1,0,0] neg_hi:[1,0,0]
	v_pk_fma_f32 v[142:143], v[184:185], v[128:129], v[142:143] op_sel_hi:[1,0,1] neg_lo:[1,0,0] neg_hi:[1,0,0]
	v_pk_fma_f32 v[142:143], v[186:187], v[128:129], v[142:143] op_sel:[0,1,0] neg_lo:[1,0,0] neg_hi:[1,0,0]
	ds_read_b128 v[180:183], v228 offset:11376
	ds_read_b128 v[184:187], v228 offset:11392
	s_waitcnt lgkmcnt(14)
	v_pk_fma_f32 v[142:143], v[188:189], v[130:131], v[142:143] op_sel_hi:[1,0,1] neg_lo:[1,0,0] neg_hi:[1,0,0]
	v_pk_fma_f32 v[142:143], v[190:191], v[130:131], v[142:143] op_sel:[0,1,0] neg_lo:[1,0,0] neg_hi:[1,0,0]
	v_pk_fma_f32 v[142:143], v[192:193], v[132:133], v[142:143] op_sel_hi:[1,0,1] neg_lo:[1,0,0] neg_hi:[1,0,0]
	v_pk_fma_f32 v[142:143], v[194:195], v[132:133], v[142:143] op_sel:[0,1,0] neg_lo:[1,0,0] neg_hi:[1,0,0]
	ds_read_b128 v[188:191], v228 offset:11408
	ds_read_b128 v[192:195], v228 offset:11424
	s_waitcnt lgkmcnt(14)
	v_pk_fma_f32 v[142:143], v[196:197], v[134:135], v[142:143] op_sel_hi:[1,0,1] neg_lo:[1,0,0] neg_hi:[1,0,0]
	v_pk_fma_f32 v[142:143], v[198:199], v[134:135], v[142:143] op_sel:[0,1,0] neg_lo:[1,0,0] neg_hi:[1,0,0]
	v_pk_fma_f32 v[142:143], v[200:201], v[136:137], v[142:143] op_sel_hi:[1,0,1] neg_lo:[1,0,0] neg_hi:[1,0,0]
	v_pk_fma_f32 v[142:143], v[202:203], v[136:137], v[142:143] op_sel:[0,1,0] neg_lo:[1,0,0] neg_hi:[1,0,0]
	ds_read_b128 v[196:199], v228 offset:11440
	ds_read_b128 v[200:203], v228 offset:11456
	s_waitcnt lgkmcnt(14)
	v_pk_fma_f32 v[142:143], v[204:205], v[138:139], v[142:143] op_sel_hi:[1,0,1] neg_lo:[1,0,0] neg_hi:[1,0,0]
	v_pk_fma_f32 v[142:143], v[206:207], v[138:139], v[142:143] op_sel:[0,1,0] neg_lo:[1,0,0] neg_hi:[1,0,0]
	v_pk_fma_f32 v[142:143], v[208:209], v[140:141], v[142:143] op_sel_hi:[1,0,1] neg_lo:[1,0,0] neg_hi:[1,0,0]
	v_pk_fma_f32 v[142:143], v[210:211], v[140:141], v[142:143] op_sel:[0,1,0] neg_lo:[1,0,0] neg_hi:[1,0,0]
	ds_read_b128 v[204:207], v228 offset:11472
	ds_read_b128 v[208:211], v228 offset:11488
	s_waitcnt lgkmcnt(14)
	v_fma_f32 v143, -v213, v142, v143
	v_pk_fma_f32 v[144:145], v[216:217], v[100:101], v[144:145] op_sel_hi:[1,0,1] neg_lo:[1,0,0] neg_hi:[1,0,0]
	v_pk_fma_f32 v[144:145], v[218:219], v[100:101], v[144:145] op_sel:[0,1,0] neg_lo:[1,0,0] neg_hi:[1,0,0]
	ds_read_b128 v[212:215], v228 offset:11504
	ds_read_b128 v[216:219], v228 offset:11520
	s_waitcnt lgkmcnt(14)
	v_pk_fma_f32 v[144:145], v[220:221], v[102:103], v[144:145] op_sel_hi:[1,0,1] neg_lo:[1,0,0] neg_hi:[1,0,0]
	v_pk_fma_f32 v[144:145], v[222:223], v[102:103], v[144:145] op_sel:[0,1,0] neg_lo:[1,0,0] neg_hi:[1,0,0]
	v_pk_fma_f32 v[144:145], v[224:225], v[104:105], v[144:145] op_sel_hi:[1,0,1] neg_lo:[1,0,0] neg_hi:[1,0,0]
	v_pk_fma_f32 v[144:145], v[226:227], v[104:105], v[144:145] op_sel:[0,1,0] neg_lo:[1,0,0] neg_hi:[1,0,0]
	ds_read_b128 v[220:223], v228 offset:11536
	ds_read_b128 v[224:227], v228 offset:11552
	s_waitcnt lgkmcnt(14)
	v_pk_fma_f32 v[144:145], v[164:165], v[106:107], v[144:145] op_sel_hi:[1,0,1] neg_lo:[1,0,0] neg_hi:[1,0,0]
	v_pk_fma_f32 v[144:145], v[166:167], v[106:107], v[144:145] op_sel:[0,1,0] neg_lo:[1,0,0] neg_hi:[1,0,0]
	v_pk_fma_f32 v[144:145], v[168:169], v[108:109], v[144:145] op_sel_hi:[1,0,1] neg_lo:[1,0,0] neg_hi:[1,0,0]
	v_pk_fma_f32 v[144:145], v[170:171], v[108:109], v[144:145] op_sel:[0,1,0] neg_lo:[1,0,0] neg_hi:[1,0,0]
	ds_read_b128 v[164:167], v228 offset:11568
	ds_read_b128 v[168:171], v228 offset:11584
	s_waitcnt lgkmcnt(14)
	v_pk_fma_f32 v[144:145], v[172:173], v[110:111], v[144:145] op_sel_hi:[1,0,1] neg_lo:[1,0,0] neg_hi:[1,0,0]
	v_pk_fma_f32 v[144:145], v[174:175], v[110:111], v[144:145] op_sel:[0,1,0] neg_lo:[1,0,0] neg_hi:[1,0,0]
	v_pk_fma_f32 v[144:145], v[176:177], v[112:113], v[144:145] op_sel_hi:[1,0,1] neg_lo:[1,0,0] neg_hi:[1,0,0]
	v_pk_fma_f32 v[144:145], v[178:179], v[112:113], v[144:145] op_sel:[0,1,0] neg_lo:[1,0,0] neg_hi:[1,0,0]
	ds_read_b128 v[172:175], v228 offset:11600
	ds_read_b128 v[176:179], v228 offset:11616
	s_waitcnt lgkmcnt(14)
	v_pk_fma_f32 v[144:145], v[180:181], v[114:115], v[144:145] op_sel_hi:[1,0,1] neg_lo:[1,0,0] neg_hi:[1,0,0]
	v_pk_fma_f32 v[144:145], v[182:183], v[114:115], v[144:145] op_sel:[0,1,0] neg_lo:[1,0,0] neg_hi:[1,0,0]
	v_pk_fma_f32 v[144:145], v[184:185], v[116:117], v[144:145] op_sel_hi:[1,0,1] neg_lo:[1,0,0] neg_hi:[1,0,0]
	v_pk_fma_f32 v[144:145], v[186:187], v[116:117], v[144:145] op_sel:[0,1,0] neg_lo:[1,0,0] neg_hi:[1,0,0]
	ds_read_b128 v[180:183], v228 offset:11776
	ds_read_b128 v[184:187], v228 offset:11792
	s_waitcnt lgkmcnt(14)
	v_pk_fma_f32 v[144:145], v[188:189], v[118:119], v[144:145] op_sel_hi:[1,0,1] neg_lo:[1,0,0] neg_hi:[1,0,0]
	v_pk_fma_f32 v[144:145], v[190:191], v[118:119], v[144:145] op_sel:[0,1,0] neg_lo:[1,0,0] neg_hi:[1,0,0]
	v_pk_fma_f32 v[144:145], v[192:193], v[120:121], v[144:145] op_sel_hi:[1,0,1] neg_lo:[1,0,0] neg_hi:[1,0,0]
	v_pk_fma_f32 v[144:145], v[194:195], v[120:121], v[144:145] op_sel:[0,1,0] neg_lo:[1,0,0] neg_hi:[1,0,0]
	ds_read_b128 v[188:191], v228 offset:11808
	ds_read_b128 v[192:195], v228 offset:11824
	s_waitcnt lgkmcnt(14)
	v_pk_fma_f32 v[144:145], v[196:197], v[122:123], v[144:145] op_sel_hi:[1,0,1] neg_lo:[1,0,0] neg_hi:[1,0,0]
	v_pk_fma_f32 v[144:145], v[198:199], v[122:123], v[144:145] op_sel:[0,1,0] neg_lo:[1,0,0] neg_hi:[1,0,0]
	v_pk_fma_f32 v[144:145], v[200:201], v[124:125], v[144:145] op_sel_hi:[1,0,1] neg_lo:[1,0,0] neg_hi:[1,0,0]
	v_pk_fma_f32 v[144:145], v[202:203], v[124:125], v[144:145] op_sel:[0,1,0] neg_lo:[1,0,0] neg_hi:[1,0,0]
	ds_read_b128 v[196:199], v228 offset:11840
	ds_read_b128 v[200:203], v228 offset:11856
	s_waitcnt lgkmcnt(14)
	v_pk_fma_f32 v[144:145], v[204:205], v[126:127], v[144:145] op_sel_hi:[1,0,1] neg_lo:[1,0,0] neg_hi:[1,0,0]
	v_pk_fma_f32 v[144:145], v[206:207], v[126:127], v[144:145] op_sel:[0,1,0] neg_lo:[1,0,0] neg_hi:[1,0,0]
	v_pk_fma_f32 v[144:145], v[208:209], v[128:129], v[144:145] op_sel_hi:[1,0,1] neg_lo:[1,0,0] neg_hi:[1,0,0]
	v_pk_fma_f32 v[144:145], v[210:211], v[128:129], v[144:145] op_sel:[0,1,0] neg_lo:[1,0,0] neg_hi:[1,0,0]
	ds_read_b128 v[204:207], v228 offset:11872
	ds_read_b128 v[208:211], v228 offset:11888
	s_waitcnt lgkmcnt(14)
	v_pk_fma_f32 v[144:145], v[212:213], v[130:131], v[144:145] op_sel_hi:[1,0,1] neg_lo:[1,0,0] neg_hi:[1,0,0]
	v_pk_fma_f32 v[144:145], v[214:215], v[130:131], v[144:145] op_sel:[0,1,0] neg_lo:[1,0,0] neg_hi:[1,0,0]
	v_pk_fma_f32 v[144:145], v[216:217], v[132:133], v[144:145] op_sel_hi:[1,0,1] neg_lo:[1,0,0] neg_hi:[1,0,0]
	v_pk_fma_f32 v[144:145], v[218:219], v[132:133], v[144:145] op_sel:[0,1,0] neg_lo:[1,0,0] neg_hi:[1,0,0]
	ds_read_b128 v[212:215], v228 offset:11904
	ds_read_b128 v[216:219], v228 offset:11920
	s_waitcnt lgkmcnt(14)
	v_pk_fma_f32 v[144:145], v[220:221], v[134:135], v[144:145] op_sel_hi:[1,0,1] neg_lo:[1,0,0] neg_hi:[1,0,0]
	v_pk_fma_f32 v[144:145], v[222:223], v[134:135], v[144:145] op_sel:[0,1,0] neg_lo:[1,0,0] neg_hi:[1,0,0]
	v_pk_fma_f32 v[144:145], v[224:225], v[136:137], v[144:145] op_sel_hi:[1,0,1] neg_lo:[1,0,0] neg_hi:[1,0,0]
	v_pk_fma_f32 v[144:145], v[226:227], v[136:137], v[144:145] op_sel:[0,1,0] neg_lo:[1,0,0] neg_hi:[1,0,0]
	ds_read_b128 v[220:223], v228 offset:11936
	ds_read_b128 v[224:227], v228 offset:11952
	s_waitcnt lgkmcnt(14)
	v_pk_fma_f32 v[144:145], v[164:165], v[138:139], v[144:145] op_sel_hi:[1,0,1] neg_lo:[1,0,0] neg_hi:[1,0,0]
	v_pk_fma_f32 v[144:145], v[166:167], v[138:139], v[144:145] op_sel:[0,1,0] neg_lo:[1,0,0] neg_hi:[1,0,0]
	v_pk_fma_f32 v[144:145], v[168:169], v[140:141], v[144:145] op_sel_hi:[1,0,1] neg_lo:[1,0,0] neg_hi:[1,0,0]
	v_pk_fma_f32 v[144:145], v[170:171], v[140:141], v[144:145] op_sel:[0,1,0] neg_lo:[1,0,0] neg_hi:[1,0,0]
	ds_read_b128 v[164:167], v228 offset:11968
	ds_read_b128 v[168:171], v228 offset:11984
	s_waitcnt lgkmcnt(14)
	v_pk_fma_f32 v[144:145], v[172:173], v[142:143], v[144:145] op_sel_hi:[1,0,1] neg_lo:[1,0,0] neg_hi:[1,0,0]
	v_pk_fma_f32 v[144:145], v[174:175], v[142:143], v[144:145] op_sel:[0,1,0] neg_lo:[1,0,0] neg_hi:[1,0,0]
	v_fma_f32 v145, -v177, v144, v145
	ds_read_b128 v[172:175], v228 offset:12000
	ds_read_b128 v[176:179], v228 offset:12016
	s_waitcnt lgkmcnt(14)
	v_pk_fma_f32 v[146:147], v[180:181], v[100:101], v[146:147] op_sel_hi:[1,0,1] neg_lo:[1,0,0] neg_hi:[1,0,0]
	v_pk_fma_f32 v[146:147], v[182:183], v[100:101], v[146:147] op_sel:[0,1,0] neg_lo:[1,0,0] neg_hi:[1,0,0]
	v_pk_fma_f32 v[146:147], v[184:185], v[102:103], v[146:147] op_sel_hi:[1,0,1] neg_lo:[1,0,0] neg_hi:[1,0,0]
	v_pk_fma_f32 v[146:147], v[186:187], v[102:103], v[146:147] op_sel:[0,1,0] neg_lo:[1,0,0] neg_hi:[1,0,0]
	ds_read_b128 v[180:183], v228 offset:12032
	ds_read_b128 v[184:187], v228 offset:12048
	s_waitcnt lgkmcnt(14)
	v_pk_fma_f32 v[146:147], v[188:189], v[104:105], v[146:147] op_sel_hi:[1,0,1] neg_lo:[1,0,0] neg_hi:[1,0,0]
	v_pk_fma_f32 v[146:147], v[190:191], v[104:105], v[146:147] op_sel:[0,1,0] neg_lo:[1,0,0] neg_hi:[1,0,0]
	v_pk_fma_f32 v[146:147], v[192:193], v[106:107], v[146:147] op_sel_hi:[1,0,1] neg_lo:[1,0,0] neg_hi:[1,0,0]
	v_pk_fma_f32 v[146:147], v[194:195], v[106:107], v[146:147] op_sel:[0,1,0] neg_lo:[1,0,0] neg_hi:[1,0,0]
	ds_read_b128 v[188:191], v228 offset:12064
	ds_read_b128 v[192:195], v228 offset:12080
	s_waitcnt lgkmcnt(14)
	v_pk_fma_f32 v[146:147], v[196:197], v[108:109], v[146:147] op_sel_hi:[1,0,1] neg_lo:[1,0,0] neg_hi:[1,0,0]
	v_pk_fma_f32 v[146:147], v[198:199], v[108:109], v[146:147] op_sel:[0,1,0] neg_lo:[1,0,0] neg_hi:[1,0,0]
	v_pk_fma_f32 v[146:147], v[200:201], v[110:111], v[146:147] op_sel_hi:[1,0,1] neg_lo:[1,0,0] neg_hi:[1,0,0]
	v_pk_fma_f32 v[146:147], v[202:203], v[110:111], v[146:147] op_sel:[0,1,0] neg_lo:[1,0,0] neg_hi:[1,0,0]
	ds_read_b128 v[196:199], v228 offset:12096
	ds_read_b128 v[200:203], v228 offset:12112
	s_waitcnt lgkmcnt(14)
	v_pk_fma_f32 v[146:147], v[204:205], v[112:113], v[146:147] op_sel_hi:[1,0,1] neg_lo:[1,0,0] neg_hi:[1,0,0]
	v_pk_fma_f32 v[146:147], v[206:207], v[112:113], v[146:147] op_sel:[0,1,0] neg_lo:[1,0,0] neg_hi:[1,0,0]
	v_pk_fma_f32 v[146:147], v[208:209], v[114:115], v[146:147] op_sel_hi:[1,0,1] neg_lo:[1,0,0] neg_hi:[1,0,0]
	v_pk_fma_f32 v[146:147], v[210:211], v[114:115], v[146:147] op_sel:[0,1,0] neg_lo:[1,0,0] neg_hi:[1,0,0]
	ds_read_b128 v[204:207], v228 offset:12128
	ds_read_b128 v[208:211], v228 offset:12144
	s_waitcnt lgkmcnt(14)
	v_pk_fma_f32 v[146:147], v[212:213], v[116:117], v[146:147] op_sel_hi:[1,0,1] neg_lo:[1,0,0] neg_hi:[1,0,0]
	v_pk_fma_f32 v[146:147], v[214:215], v[116:117], v[146:147] op_sel:[0,1,0] neg_lo:[1,0,0] neg_hi:[1,0,0]
	v_pk_fma_f32 v[146:147], v[216:217], v[118:119], v[146:147] op_sel_hi:[1,0,1] neg_lo:[1,0,0] neg_hi:[1,0,0]
	v_pk_fma_f32 v[146:147], v[218:219], v[118:119], v[146:147] op_sel:[0,1,0] neg_lo:[1,0,0] neg_hi:[1,0,0]
	ds_read_b128 v[212:215], v228 offset:12288
	ds_read_b128 v[216:219], v228 offset:12304
	s_waitcnt lgkmcnt(14)
	v_pk_fma_f32 v[146:147], v[220:221], v[120:121], v[146:147] op_sel_hi:[1,0,1] neg_lo:[1,0,0] neg_hi:[1,0,0]
	v_pk_fma_f32 v[146:147], v[222:223], v[120:121], v[146:147] op_sel:[0,1,0] neg_lo:[1,0,0] neg_hi:[1,0,0]
	v_pk_fma_f32 v[146:147], v[224:225], v[122:123], v[146:147] op_sel_hi:[1,0,1] neg_lo:[1,0,0] neg_hi:[1,0,0]
	v_pk_fma_f32 v[146:147], v[226:227], v[122:123], v[146:147] op_sel:[0,1,0] neg_lo:[1,0,0] neg_hi:[1,0,0]
	ds_read_b128 v[220:223], v228 offset:12320
	ds_read_b128 v[224:227], v228 offset:12336
	s_waitcnt lgkmcnt(14)
	v_pk_fma_f32 v[146:147], v[164:165], v[124:125], v[146:147] op_sel_hi:[1,0,1] neg_lo:[1,0,0] neg_hi:[1,0,0]
	v_pk_fma_f32 v[146:147], v[166:167], v[124:125], v[146:147] op_sel:[0,1,0] neg_lo:[1,0,0] neg_hi:[1,0,0]
	v_pk_fma_f32 v[146:147], v[168:169], v[126:127], v[146:147] op_sel_hi:[1,0,1] neg_lo:[1,0,0] neg_hi:[1,0,0]
	v_pk_fma_f32 v[146:147], v[170:171], v[126:127], v[146:147] op_sel:[0,1,0] neg_lo:[1,0,0] neg_hi:[1,0,0]
	ds_read_b128 v[164:167], v228 offset:12352
	ds_read_b128 v[168:171], v228 offset:12368
	s_waitcnt lgkmcnt(14)
	v_pk_fma_f32 v[146:147], v[172:173], v[128:129], v[146:147] op_sel_hi:[1,0,1] neg_lo:[1,0,0] neg_hi:[1,0,0]
	v_pk_fma_f32 v[146:147], v[174:175], v[128:129], v[146:147] op_sel:[0,1,0] neg_lo:[1,0,0] neg_hi:[1,0,0]
	v_pk_fma_f32 v[146:147], v[176:177], v[130:131], v[146:147] op_sel_hi:[1,0,1] neg_lo:[1,0,0] neg_hi:[1,0,0]
	v_pk_fma_f32 v[146:147], v[178:179], v[130:131], v[146:147] op_sel:[0,1,0] neg_lo:[1,0,0] neg_hi:[1,0,0]
	ds_read_b128 v[172:175], v228 offset:12384
	ds_read_b128 v[176:179], v228 offset:12400
	s_waitcnt lgkmcnt(14)
	v_pk_fma_f32 v[146:147], v[180:181], v[132:133], v[146:147] op_sel_hi:[1,0,1] neg_lo:[1,0,0] neg_hi:[1,0,0]
	v_pk_fma_f32 v[146:147], v[182:183], v[132:133], v[146:147] op_sel:[0,1,0] neg_lo:[1,0,0] neg_hi:[1,0,0]
	v_pk_fma_f32 v[146:147], v[184:185], v[134:135], v[146:147] op_sel_hi:[1,0,1] neg_lo:[1,0,0] neg_hi:[1,0,0]
	v_pk_fma_f32 v[146:147], v[186:187], v[134:135], v[146:147] op_sel:[0,1,0] neg_lo:[1,0,0] neg_hi:[1,0,0]
	ds_read_b128 v[180:183], v228 offset:12416
	ds_read_b128 v[184:187], v228 offset:12432
	s_waitcnt lgkmcnt(14)
	v_pk_fma_f32 v[146:147], v[188:189], v[136:137], v[146:147] op_sel_hi:[1,0,1] neg_lo:[1,0,0] neg_hi:[1,0,0]
	v_pk_fma_f32 v[146:147], v[190:191], v[136:137], v[146:147] op_sel:[0,1,0] neg_lo:[1,0,0] neg_hi:[1,0,0]
	v_pk_fma_f32 v[146:147], v[192:193], v[138:139], v[146:147] op_sel_hi:[1,0,1] neg_lo:[1,0,0] neg_hi:[1,0,0]
	v_pk_fma_f32 v[146:147], v[194:195], v[138:139], v[146:147] op_sel:[0,1,0] neg_lo:[1,0,0] neg_hi:[1,0,0]
	ds_read_b128 v[188:191], v228 offset:12448
	ds_read_b128 v[192:195], v228 offset:12464
	s_waitcnt lgkmcnt(14)
	v_pk_fma_f32 v[146:147], v[196:197], v[140:141], v[146:147] op_sel_hi:[1,0,1] neg_lo:[1,0,0] neg_hi:[1,0,0]
	v_pk_fma_f32 v[146:147], v[198:199], v[140:141], v[146:147] op_sel:[0,1,0] neg_lo:[1,0,0] neg_hi:[1,0,0]
	v_pk_fma_f32 v[146:147], v[200:201], v[142:143], v[146:147] op_sel_hi:[1,0,1] neg_lo:[1,0,0] neg_hi:[1,0,0]
	v_pk_fma_f32 v[146:147], v[202:203], v[142:143], v[146:147] op_sel:[0,1,0] neg_lo:[1,0,0] neg_hi:[1,0,0]
	ds_read_b128 v[196:199], v228 offset:12480
	ds_read_b128 v[200:203], v228 offset:12496
	s_waitcnt lgkmcnt(14)
	v_pk_fma_f32 v[146:147], v[204:205], v[144:145], v[146:147] op_sel_hi:[1,0,1] neg_lo:[1,0,0] neg_hi:[1,0,0]
	v_pk_fma_f32 v[146:147], v[206:207], v[144:145], v[146:147] op_sel:[0,1,0] neg_lo:[1,0,0] neg_hi:[1,0,0]
	v_fma_f32 v147, -v209, v146, v147
	ds_read_b128 v[204:207], v228 offset:12512
	ds_read_b128 v[208:211], v228 offset:12528
	s_waitcnt lgkmcnt(14)
	v_pk_fma_f32 v[148:149], v[212:213], v[100:101], v[148:149] op_sel_hi:[1,0,1] neg_lo:[1,0,0] neg_hi:[1,0,0]
	v_pk_fma_f32 v[148:149], v[214:215], v[100:101], v[148:149] op_sel:[0,1,0] neg_lo:[1,0,0] neg_hi:[1,0,0]
	v_pk_fma_f32 v[148:149], v[216:217], v[102:103], v[148:149] op_sel_hi:[1,0,1] neg_lo:[1,0,0] neg_hi:[1,0,0]
	v_pk_fma_f32 v[148:149], v[218:219], v[102:103], v[148:149] op_sel:[0,1,0] neg_lo:[1,0,0] neg_hi:[1,0,0]
	ds_read_b128 v[212:215], v228 offset:12544
	ds_read_b128 v[216:219], v228 offset:12560
	s_waitcnt lgkmcnt(14)
	v_pk_fma_f32 v[148:149], v[220:221], v[104:105], v[148:149] op_sel_hi:[1,0,1] neg_lo:[1,0,0] neg_hi:[1,0,0]
	v_pk_fma_f32 v[148:149], v[222:223], v[104:105], v[148:149] op_sel:[0,1,0] neg_lo:[1,0,0] neg_hi:[1,0,0]
	v_pk_fma_f32 v[148:149], v[224:225], v[106:107], v[148:149] op_sel_hi:[1,0,1] neg_lo:[1,0,0] neg_hi:[1,0,0]
	v_pk_fma_f32 v[148:149], v[226:227], v[106:107], v[148:149] op_sel:[0,1,0] neg_lo:[1,0,0] neg_hi:[1,0,0]
	ds_read_b128 v[220:223], v228 offset:12576
	ds_read_b128 v[224:227], v228 offset:12592
	s_waitcnt lgkmcnt(14)
	v_pk_fma_f32 v[148:149], v[164:165], v[108:109], v[148:149] op_sel_hi:[1,0,1] neg_lo:[1,0,0] neg_hi:[1,0,0]
	v_pk_fma_f32 v[148:149], v[166:167], v[108:109], v[148:149] op_sel:[0,1,0] neg_lo:[1,0,0] neg_hi:[1,0,0]
	v_pk_fma_f32 v[148:149], v[168:169], v[110:111], v[148:149] op_sel_hi:[1,0,1] neg_lo:[1,0,0] neg_hi:[1,0,0]
	v_pk_fma_f32 v[148:149], v[170:171], v[110:111], v[148:149] op_sel:[0,1,0] neg_lo:[1,0,0] neg_hi:[1,0,0]
	ds_read_b128 v[164:167], v228 offset:12608
	ds_read_b128 v[168:171], v228 offset:12624
	s_waitcnt lgkmcnt(14)
	v_pk_fma_f32 v[148:149], v[172:173], v[112:113], v[148:149] op_sel_hi:[1,0,1] neg_lo:[1,0,0] neg_hi:[1,0,0]
	v_pk_fma_f32 v[148:149], v[174:175], v[112:113], v[148:149] op_sel:[0,1,0] neg_lo:[1,0,0] neg_hi:[1,0,0]
	v_pk_fma_f32 v[148:149], v[176:177], v[114:115], v[148:149] op_sel_hi:[1,0,1] neg_lo:[1,0,0] neg_hi:[1,0,0]
	v_pk_fma_f32 v[148:149], v[178:179], v[114:115], v[148:149] op_sel:[0,1,0] neg_lo:[1,0,0] neg_hi:[1,0,0]
	ds_read_b128 v[172:175], v228 offset:12640
	ds_read_b128 v[176:179], v228 offset:12656
	s_waitcnt lgkmcnt(14)
	v_pk_fma_f32 v[148:149], v[180:181], v[116:117], v[148:149] op_sel_hi:[1,0,1] neg_lo:[1,0,0] neg_hi:[1,0,0]
	v_pk_fma_f32 v[148:149], v[182:183], v[116:117], v[148:149] op_sel:[0,1,0] neg_lo:[1,0,0] neg_hi:[1,0,0]
	v_pk_fma_f32 v[148:149], v[184:185], v[118:119], v[148:149] op_sel_hi:[1,0,1] neg_lo:[1,0,0] neg_hi:[1,0,0]
	v_pk_fma_f32 v[148:149], v[186:187], v[118:119], v[148:149] op_sel:[0,1,0] neg_lo:[1,0,0] neg_hi:[1,0,0]
	ds_read_b128 v[180:183], v228 offset:12672
	ds_read_b128 v[184:187], v228 offset:12800
	s_waitcnt lgkmcnt(14)
	v_pk_fma_f32 v[148:149], v[188:189], v[120:121], v[148:149] op_sel_hi:[1,0,1] neg_lo:[1,0,0] neg_hi:[1,0,0]
	v_pk_fma_f32 v[148:149], v[190:191], v[120:121], v[148:149] op_sel:[0,1,0] neg_lo:[1,0,0] neg_hi:[1,0,0]
	v_pk_fma_f32 v[148:149], v[192:193], v[122:123], v[148:149] op_sel_hi:[1,0,1] neg_lo:[1,0,0] neg_hi:[1,0,0]
	v_pk_fma_f32 v[148:149], v[194:195], v[122:123], v[148:149] op_sel:[0,1,0] neg_lo:[1,0,0] neg_hi:[1,0,0]
	ds_read_b128 v[188:191], v228 offset:12816
	ds_read_b128 v[192:195], v228 offset:12832
	s_waitcnt lgkmcnt(14)
	v_pk_fma_f32 v[148:149], v[196:197], v[124:125], v[148:149] op_sel_hi:[1,0,1] neg_lo:[1,0,0] neg_hi:[1,0,0]
	v_pk_fma_f32 v[148:149], v[198:199], v[124:125], v[148:149] op_sel:[0,1,0] neg_lo:[1,0,0] neg_hi:[1,0,0]
	v_pk_fma_f32 v[148:149], v[200:201], v[126:127], v[148:149] op_sel_hi:[1,0,1] neg_lo:[1,0,0] neg_hi:[1,0,0]
	v_pk_fma_f32 v[148:149], v[202:203], v[126:127], v[148:149] op_sel:[0,1,0] neg_lo:[1,0,0] neg_hi:[1,0,0]
	ds_read_b128 v[196:199], v228 offset:12848
	ds_read_b128 v[200:203], v228 offset:12864
	s_waitcnt lgkmcnt(14)
	v_pk_fma_f32 v[148:149], v[204:205], v[128:129], v[148:149] op_sel_hi:[1,0,1] neg_lo:[1,0,0] neg_hi:[1,0,0]
	v_pk_fma_f32 v[148:149], v[206:207], v[128:129], v[148:149] op_sel:[0,1,0] neg_lo:[1,0,0] neg_hi:[1,0,0]
	v_pk_fma_f32 v[148:149], v[208:209], v[130:131], v[148:149] op_sel_hi:[1,0,1] neg_lo:[1,0,0] neg_hi:[1,0,0]
	v_pk_fma_f32 v[148:149], v[210:211], v[130:131], v[148:149] op_sel:[0,1,0] neg_lo:[1,0,0] neg_hi:[1,0,0]
	ds_read_b128 v[204:207], v228 offset:12880
	ds_read_b128 v[208:211], v228 offset:12896
	s_waitcnt lgkmcnt(14)
	v_pk_fma_f32 v[148:149], v[212:213], v[132:133], v[148:149] op_sel_hi:[1,0,1] neg_lo:[1,0,0] neg_hi:[1,0,0]
	v_pk_fma_f32 v[148:149], v[214:215], v[132:133], v[148:149] op_sel:[0,1,0] neg_lo:[1,0,0] neg_hi:[1,0,0]
	v_pk_fma_f32 v[148:149], v[216:217], v[134:135], v[148:149] op_sel_hi:[1,0,1] neg_lo:[1,0,0] neg_hi:[1,0,0]
	v_pk_fma_f32 v[148:149], v[218:219], v[134:135], v[148:149] op_sel:[0,1,0] neg_lo:[1,0,0] neg_hi:[1,0,0]
	ds_read_b128 v[212:215], v228 offset:12912
	ds_read_b128 v[216:219], v228 offset:12928
	s_waitcnt lgkmcnt(14)
	v_pk_fma_f32 v[148:149], v[220:221], v[136:137], v[148:149] op_sel_hi:[1,0,1] neg_lo:[1,0,0] neg_hi:[1,0,0]
	v_pk_fma_f32 v[148:149], v[222:223], v[136:137], v[148:149] op_sel:[0,1,0] neg_lo:[1,0,0] neg_hi:[1,0,0]
	v_pk_fma_f32 v[148:149], v[224:225], v[138:139], v[148:149] op_sel_hi:[1,0,1] neg_lo:[1,0,0] neg_hi:[1,0,0]
	v_pk_fma_f32 v[148:149], v[226:227], v[138:139], v[148:149] op_sel:[0,1,0] neg_lo:[1,0,0] neg_hi:[1,0,0]
	ds_read_b128 v[220:223], v228 offset:12944
	ds_read_b128 v[224:227], v228 offset:12960
	s_waitcnt lgkmcnt(14)
	v_pk_fma_f32 v[148:149], v[164:165], v[140:141], v[148:149] op_sel_hi:[1,0,1] neg_lo:[1,0,0] neg_hi:[1,0,0]
	v_pk_fma_f32 v[148:149], v[166:167], v[140:141], v[148:149] op_sel:[0,1,0] neg_lo:[1,0,0] neg_hi:[1,0,0]
	v_pk_fma_f32 v[148:149], v[168:169], v[142:143], v[148:149] op_sel_hi:[1,0,1] neg_lo:[1,0,0] neg_hi:[1,0,0]
	v_pk_fma_f32 v[148:149], v[170:171], v[142:143], v[148:149] op_sel:[0,1,0] neg_lo:[1,0,0] neg_hi:[1,0,0]
	ds_read_b128 v[164:167], v228 offset:12976
	ds_read_b128 v[168:171], v228 offset:12992
	s_waitcnt lgkmcnt(14)
	v_pk_fma_f32 v[148:149], v[172:173], v[144:145], v[148:149] op_sel_hi:[1,0,1] neg_lo:[1,0,0] neg_hi:[1,0,0]
	v_pk_fma_f32 v[148:149], v[174:175], v[144:145], v[148:149] op_sel:[0,1,0] neg_lo:[1,0,0] neg_hi:[1,0,0]
	v_pk_fma_f32 v[148:149], v[176:177], v[146:147], v[148:149] op_sel_hi:[1,0,1] neg_lo:[1,0,0] neg_hi:[1,0,0]
	v_pk_fma_f32 v[148:149], v[178:179], v[146:147], v[148:149] op_sel:[0,1,0] neg_lo:[1,0,0] neg_hi:[1,0,0]
	ds_read_b128 v[172:175], v228 offset:13008
	ds_read_b128 v[176:179], v228 offset:13024
	s_waitcnt lgkmcnt(14)
	v_fma_f32 v149, -v181, v148, v149
	v_pk_fma_f32 v[150:151], v[184:185], v[100:101], v[150:151] op_sel_hi:[1,0,1] neg_lo:[1,0,0] neg_hi:[1,0,0]
	v_pk_fma_f32 v[150:151], v[186:187], v[100:101], v[150:151] op_sel:[0,1,0] neg_lo:[1,0,0] neg_hi:[1,0,0]
	ds_read_b128 v[180:183], v228 offset:13040
	ds_read_b128 v[184:187], v228 offset:13056
	s_waitcnt lgkmcnt(14)
	v_pk_fma_f32 v[150:151], v[188:189], v[102:103], v[150:151] op_sel_hi:[1,0,1] neg_lo:[1,0,0] neg_hi:[1,0,0]
	v_pk_fma_f32 v[150:151], v[190:191], v[102:103], v[150:151] op_sel:[0,1,0] neg_lo:[1,0,0] neg_hi:[1,0,0]
	v_pk_fma_f32 v[150:151], v[192:193], v[104:105], v[150:151] op_sel_hi:[1,0,1] neg_lo:[1,0,0] neg_hi:[1,0,0]
	v_pk_fma_f32 v[150:151], v[194:195], v[104:105], v[150:151] op_sel:[0,1,0] neg_lo:[1,0,0] neg_hi:[1,0,0]
	ds_read_b128 v[188:191], v228 offset:13072
	ds_read_b128 v[192:195], v228 offset:13088
	s_waitcnt lgkmcnt(14)
	v_pk_fma_f32 v[150:151], v[196:197], v[106:107], v[150:151] op_sel_hi:[1,0,1] neg_lo:[1,0,0] neg_hi:[1,0,0]
	v_pk_fma_f32 v[150:151], v[198:199], v[106:107], v[150:151] op_sel:[0,1,0] neg_lo:[1,0,0] neg_hi:[1,0,0]
	v_pk_fma_f32 v[150:151], v[200:201], v[108:109], v[150:151] op_sel_hi:[1,0,1] neg_lo:[1,0,0] neg_hi:[1,0,0]
	v_pk_fma_f32 v[150:151], v[202:203], v[108:109], v[150:151] op_sel:[0,1,0] neg_lo:[1,0,0] neg_hi:[1,0,0]
	ds_read_b128 v[196:199], v228 offset:13104
	ds_read_b128 v[200:203], v228 offset:13120
	s_waitcnt lgkmcnt(14)
	v_pk_fma_f32 v[150:151], v[204:205], v[110:111], v[150:151] op_sel_hi:[1,0,1] neg_lo:[1,0,0] neg_hi:[1,0,0]
	v_pk_fma_f32 v[150:151], v[206:207], v[110:111], v[150:151] op_sel:[0,1,0] neg_lo:[1,0,0] neg_hi:[1,0,0]
	v_pk_fma_f32 v[150:151], v[208:209], v[112:113], v[150:151] op_sel_hi:[1,0,1] neg_lo:[1,0,0] neg_hi:[1,0,0]
	v_pk_fma_f32 v[150:151], v[210:211], v[112:113], v[150:151] op_sel:[0,1,0] neg_lo:[1,0,0] neg_hi:[1,0,0]
	ds_read_b128 v[204:207], v228 offset:13136
	ds_read_b128 v[208:211], v228 offset:13152
	s_waitcnt lgkmcnt(14)
	v_pk_fma_f32 v[150:151], v[212:213], v[114:115], v[150:151] op_sel_hi:[1,0,1] neg_lo:[1,0,0] neg_hi:[1,0,0]
	v_pk_fma_f32 v[150:151], v[214:215], v[114:115], v[150:151] op_sel:[0,1,0] neg_lo:[1,0,0] neg_hi:[1,0,0]
	v_pk_fma_f32 v[150:151], v[216:217], v[116:117], v[150:151] op_sel_hi:[1,0,1] neg_lo:[1,0,0] neg_hi:[1,0,0]
	v_pk_fma_f32 v[150:151], v[218:219], v[116:117], v[150:151] op_sel:[0,1,0] neg_lo:[1,0,0] neg_hi:[1,0,0]
	ds_read_b128 v[212:215], v228 offset:13168
	ds_read_b128 v[216:219], v228 offset:13184
	s_waitcnt lgkmcnt(14)
	v_pk_fma_f32 v[150:151], v[220:221], v[118:119], v[150:151] op_sel_hi:[1,0,1] neg_lo:[1,0,0] neg_hi:[1,0,0]
	v_pk_fma_f32 v[150:151], v[222:223], v[118:119], v[150:151] op_sel:[0,1,0] neg_lo:[1,0,0] neg_hi:[1,0,0]
	v_pk_fma_f32 v[150:151], v[224:225], v[120:121], v[150:151] op_sel_hi:[1,0,1] neg_lo:[1,0,0] neg_hi:[1,0,0]
	v_pk_fma_f32 v[150:151], v[226:227], v[120:121], v[150:151] op_sel:[0,1,0] neg_lo:[1,0,0] neg_hi:[1,0,0]
	ds_read_b128 v[220:223], v228 offset:13200
	ds_read_b128 v[224:227], v228 offset:13312
	s_waitcnt lgkmcnt(14)
	v_pk_fma_f32 v[150:151], v[164:165], v[122:123], v[150:151] op_sel_hi:[1,0,1] neg_lo:[1,0,0] neg_hi:[1,0,0]
	v_pk_fma_f32 v[150:151], v[166:167], v[122:123], v[150:151] op_sel:[0,1,0] neg_lo:[1,0,0] neg_hi:[1,0,0]
	v_pk_fma_f32 v[150:151], v[168:169], v[124:125], v[150:151] op_sel_hi:[1,0,1] neg_lo:[1,0,0] neg_hi:[1,0,0]
	v_pk_fma_f32 v[150:151], v[170:171], v[124:125], v[150:151] op_sel:[0,1,0] neg_lo:[1,0,0] neg_hi:[1,0,0]
	ds_read_b128 v[164:167], v228 offset:13328
	ds_read_b128 v[168:171], v228 offset:13344
	s_waitcnt lgkmcnt(14)
	v_pk_fma_f32 v[150:151], v[172:173], v[126:127], v[150:151] op_sel_hi:[1,0,1] neg_lo:[1,0,0] neg_hi:[1,0,0]
	v_pk_fma_f32 v[150:151], v[174:175], v[126:127], v[150:151] op_sel:[0,1,0] neg_lo:[1,0,0] neg_hi:[1,0,0]
	v_pk_fma_f32 v[150:151], v[176:177], v[128:129], v[150:151] op_sel_hi:[1,0,1] neg_lo:[1,0,0] neg_hi:[1,0,0]
	v_pk_fma_f32 v[150:151], v[178:179], v[128:129], v[150:151] op_sel:[0,1,0] neg_lo:[1,0,0] neg_hi:[1,0,0]
	ds_read_b128 v[172:175], v228 offset:13360
	ds_read_b128 v[176:179], v228 offset:13376
	s_waitcnt lgkmcnt(14)
	v_pk_fma_f32 v[150:151], v[180:181], v[130:131], v[150:151] op_sel_hi:[1,0,1] neg_lo:[1,0,0] neg_hi:[1,0,0]
	v_pk_fma_f32 v[150:151], v[182:183], v[130:131], v[150:151] op_sel:[0,1,0] neg_lo:[1,0,0] neg_hi:[1,0,0]
	v_pk_fma_f32 v[150:151], v[184:185], v[132:133], v[150:151] op_sel_hi:[1,0,1] neg_lo:[1,0,0] neg_hi:[1,0,0]
	v_pk_fma_f32 v[150:151], v[186:187], v[132:133], v[150:151] op_sel:[0,1,0] neg_lo:[1,0,0] neg_hi:[1,0,0]
	ds_read_b128 v[180:183], v228 offset:13392
	ds_read_b128 v[184:187], v228 offset:13408
	s_waitcnt lgkmcnt(14)
	v_pk_fma_f32 v[150:151], v[188:189], v[134:135], v[150:151] op_sel_hi:[1,0,1] neg_lo:[1,0,0] neg_hi:[1,0,0]
	v_pk_fma_f32 v[150:151], v[190:191], v[134:135], v[150:151] op_sel:[0,1,0] neg_lo:[1,0,0] neg_hi:[1,0,0]
	v_pk_fma_f32 v[150:151], v[192:193], v[136:137], v[150:151] op_sel_hi:[1,0,1] neg_lo:[1,0,0] neg_hi:[1,0,0]
	v_pk_fma_f32 v[150:151], v[194:195], v[136:137], v[150:151] op_sel:[0,1,0] neg_lo:[1,0,0] neg_hi:[1,0,0]
	ds_read_b128 v[188:191], v228 offset:13424
	ds_read_b128 v[192:195], v228 offset:13440
	s_waitcnt lgkmcnt(14)
	v_pk_fma_f32 v[150:151], v[196:197], v[138:139], v[150:151] op_sel_hi:[1,0,1] neg_lo:[1,0,0] neg_hi:[1,0,0]
	v_pk_fma_f32 v[150:151], v[198:199], v[138:139], v[150:151] op_sel:[0,1,0] neg_lo:[1,0,0] neg_hi:[1,0,0]
	v_pk_fma_f32 v[150:151], v[200:201], v[140:141], v[150:151] op_sel_hi:[1,0,1] neg_lo:[1,0,0] neg_hi:[1,0,0]
	v_pk_fma_f32 v[150:151], v[202:203], v[140:141], v[150:151] op_sel:[0,1,0] neg_lo:[1,0,0] neg_hi:[1,0,0]
	ds_read_b128 v[196:199], v228 offset:13456
	ds_read_b128 v[200:203], v228 offset:13472
	s_waitcnt lgkmcnt(14)
	v_pk_fma_f32 v[150:151], v[204:205], v[142:143], v[150:151] op_sel_hi:[1,0,1] neg_lo:[1,0,0] neg_hi:[1,0,0]
	v_pk_fma_f32 v[150:151], v[206:207], v[142:143], v[150:151] op_sel:[0,1,0] neg_lo:[1,0,0] neg_hi:[1,0,0]
	v_pk_fma_f32 v[150:151], v[208:209], v[144:145], v[150:151] op_sel_hi:[1,0,1] neg_lo:[1,0,0] neg_hi:[1,0,0]
	v_pk_fma_f32 v[150:151], v[210:211], v[144:145], v[150:151] op_sel:[0,1,0] neg_lo:[1,0,0] neg_hi:[1,0,0]
	ds_read_b128 v[204:207], v228 offset:13488
	ds_read_b128 v[208:211], v228 offset:13504
	s_waitcnt lgkmcnt(14)
	v_pk_fma_f32 v[150:151], v[212:213], v[146:147], v[150:151] op_sel_hi:[1,0,1] neg_lo:[1,0,0] neg_hi:[1,0,0]
	v_pk_fma_f32 v[150:151], v[214:215], v[146:147], v[150:151] op_sel:[0,1,0] neg_lo:[1,0,0] neg_hi:[1,0,0]
	v_pk_fma_f32 v[150:151], v[216:217], v[148:149], v[150:151] op_sel_hi:[1,0,1] neg_lo:[1,0,0] neg_hi:[1,0,0]
	v_pk_fma_f32 v[150:151], v[218:219], v[148:149], v[150:151] op_sel:[0,1,0] neg_lo:[1,0,0] neg_hi:[1,0,0]
	ds_read_b128 v[212:215], v228 offset:13520
	ds_read_b128 v[216:219], v228 offset:13536
	s_waitcnt lgkmcnt(14)
	v_fma_f32 v151, -v221, v150, v151
	v_pk_fma_f32 v[152:153], v[224:225], v[100:101], v[152:153] op_sel_hi:[1,0,1] neg_lo:[1,0,0] neg_hi:[1,0,0]
	v_pk_fma_f32 v[152:153], v[226:227], v[100:101], v[152:153] op_sel:[0,1,0] neg_lo:[1,0,0] neg_hi:[1,0,0]
	ds_read_b128 v[220:223], v228 offset:13552
	ds_read_b128 v[224:227], v228 offset:13568
	s_waitcnt lgkmcnt(14)
	v_pk_fma_f32 v[152:153], v[164:165], v[102:103], v[152:153] op_sel_hi:[1,0,1] neg_lo:[1,0,0] neg_hi:[1,0,0]
	v_pk_fma_f32 v[152:153], v[166:167], v[102:103], v[152:153] op_sel:[0,1,0] neg_lo:[1,0,0] neg_hi:[1,0,0]
	v_pk_fma_f32 v[152:153], v[168:169], v[104:105], v[152:153] op_sel_hi:[1,0,1] neg_lo:[1,0,0] neg_hi:[1,0,0]
	v_pk_fma_f32 v[152:153], v[170:171], v[104:105], v[152:153] op_sel:[0,1,0] neg_lo:[1,0,0] neg_hi:[1,0,0]
	ds_read_b128 v[164:167], v228 offset:13584
	ds_read_b128 v[168:171], v228 offset:13600
	s_waitcnt lgkmcnt(14)
	v_pk_fma_f32 v[152:153], v[172:173], v[106:107], v[152:153] op_sel_hi:[1,0,1] neg_lo:[1,0,0] neg_hi:[1,0,0]
	v_pk_fma_f32 v[152:153], v[174:175], v[106:107], v[152:153] op_sel:[0,1,0] neg_lo:[1,0,0] neg_hi:[1,0,0]
	v_pk_fma_f32 v[152:153], v[176:177], v[108:109], v[152:153] op_sel_hi:[1,0,1] neg_lo:[1,0,0] neg_hi:[1,0,0]
	v_pk_fma_f32 v[152:153], v[178:179], v[108:109], v[152:153] op_sel:[0,1,0] neg_lo:[1,0,0] neg_hi:[1,0,0]
	ds_read_b128 v[172:175], v228 offset:13616
	ds_read_b128 v[176:179], v228 offset:13632
	s_waitcnt lgkmcnt(14)
	v_pk_fma_f32 v[152:153], v[180:181], v[110:111], v[152:153] op_sel_hi:[1,0,1] neg_lo:[1,0,0] neg_hi:[1,0,0]
	v_pk_fma_f32 v[152:153], v[182:183], v[110:111], v[152:153] op_sel:[0,1,0] neg_lo:[1,0,0] neg_hi:[1,0,0]
	v_pk_fma_f32 v[152:153], v[184:185], v[112:113], v[152:153] op_sel_hi:[1,0,1] neg_lo:[1,0,0] neg_hi:[1,0,0]
	v_pk_fma_f32 v[152:153], v[186:187], v[112:113], v[152:153] op_sel:[0,1,0] neg_lo:[1,0,0] neg_hi:[1,0,0]
	ds_read_b128 v[180:183], v228 offset:13648
	ds_read_b128 v[184:187], v228 offset:13664
	s_waitcnt lgkmcnt(14)
	v_pk_fma_f32 v[152:153], v[188:189], v[114:115], v[152:153] op_sel_hi:[1,0,1] neg_lo:[1,0,0] neg_hi:[1,0,0]
	v_pk_fma_f32 v[152:153], v[190:191], v[114:115], v[152:153] op_sel:[0,1,0] neg_lo:[1,0,0] neg_hi:[1,0,0]
	v_pk_fma_f32 v[152:153], v[192:193], v[116:117], v[152:153] op_sel_hi:[1,0,1] neg_lo:[1,0,0] neg_hi:[1,0,0]
	v_pk_fma_f32 v[152:153], v[194:195], v[116:117], v[152:153] op_sel:[0,1,0] neg_lo:[1,0,0] neg_hi:[1,0,0]
	ds_read_b128 v[188:191], v228 offset:13680
	ds_read_b128 v[192:195], v228 offset:13696
	s_waitcnt lgkmcnt(14)
	v_pk_fma_f32 v[152:153], v[196:197], v[118:119], v[152:153] op_sel_hi:[1,0,1] neg_lo:[1,0,0] neg_hi:[1,0,0]
	v_pk_fma_f32 v[152:153], v[198:199], v[118:119], v[152:153] op_sel:[0,1,0] neg_lo:[1,0,0] neg_hi:[1,0,0]
	v_pk_fma_f32 v[152:153], v[200:201], v[120:121], v[152:153] op_sel_hi:[1,0,1] neg_lo:[1,0,0] neg_hi:[1,0,0]
	v_pk_fma_f32 v[152:153], v[202:203], v[120:121], v[152:153] op_sel:[0,1,0] neg_lo:[1,0,0] neg_hi:[1,0,0]
	ds_read_b128 v[196:199], v228 offset:13712
	ds_read_b128 v[200:203], v228 offset:13728
	s_waitcnt lgkmcnt(14)
	v_pk_fma_f32 v[152:153], v[204:205], v[122:123], v[152:153] op_sel_hi:[1,0,1] neg_lo:[1,0,0] neg_hi:[1,0,0]
	v_pk_fma_f32 v[152:153], v[206:207], v[122:123], v[152:153] op_sel:[0,1,0] neg_lo:[1,0,0] neg_hi:[1,0,0]
	v_pk_fma_f32 v[152:153], v[208:209], v[124:125], v[152:153] op_sel_hi:[1,0,1] neg_lo:[1,0,0] neg_hi:[1,0,0]
	v_pk_fma_f32 v[152:153], v[210:211], v[124:125], v[152:153] op_sel:[0,1,0] neg_lo:[1,0,0] neg_hi:[1,0,0]
	ds_read_b128 v[204:207], v228 offset:13824
	ds_read_b128 v[208:211], v228 offset:13840
	s_waitcnt lgkmcnt(14)
	v_pk_fma_f32 v[152:153], v[212:213], v[126:127], v[152:153] op_sel_hi:[1,0,1] neg_lo:[1,0,0] neg_hi:[1,0,0]
	v_pk_fma_f32 v[152:153], v[214:215], v[126:127], v[152:153] op_sel:[0,1,0] neg_lo:[1,0,0] neg_hi:[1,0,0]
	v_pk_fma_f32 v[152:153], v[216:217], v[128:129], v[152:153] op_sel_hi:[1,0,1] neg_lo:[1,0,0] neg_hi:[1,0,0]
	v_pk_fma_f32 v[152:153], v[218:219], v[128:129], v[152:153] op_sel:[0,1,0] neg_lo:[1,0,0] neg_hi:[1,0,0]
	ds_read_b128 v[212:215], v228 offset:13856
	ds_read_b128 v[216:219], v228 offset:13872
	s_waitcnt lgkmcnt(14)
	v_pk_fma_f32 v[152:153], v[220:221], v[130:131], v[152:153] op_sel_hi:[1,0,1] neg_lo:[1,0,0] neg_hi:[1,0,0]
	v_pk_fma_f32 v[152:153], v[222:223], v[130:131], v[152:153] op_sel:[0,1,0] neg_lo:[1,0,0] neg_hi:[1,0,0]
	v_pk_fma_f32 v[152:153], v[224:225], v[132:133], v[152:153] op_sel_hi:[1,0,1] neg_lo:[1,0,0] neg_hi:[1,0,0]
	v_pk_fma_f32 v[152:153], v[226:227], v[132:133], v[152:153] op_sel:[0,1,0] neg_lo:[1,0,0] neg_hi:[1,0,0]
	ds_read_b128 v[220:223], v228 offset:13888
	ds_read_b128 v[224:227], v228 offset:13904
	s_waitcnt lgkmcnt(14)
	v_pk_fma_f32 v[152:153], v[164:165], v[134:135], v[152:153] op_sel_hi:[1,0,1] neg_lo:[1,0,0] neg_hi:[1,0,0]
	v_pk_fma_f32 v[152:153], v[166:167], v[134:135], v[152:153] op_sel:[0,1,0] neg_lo:[1,0,0] neg_hi:[1,0,0]
	v_pk_fma_f32 v[152:153], v[168:169], v[136:137], v[152:153] op_sel_hi:[1,0,1] neg_lo:[1,0,0] neg_hi:[1,0,0]
	v_pk_fma_f32 v[152:153], v[170:171], v[136:137], v[152:153] op_sel:[0,1,0] neg_lo:[1,0,0] neg_hi:[1,0,0]
	ds_read_b128 v[164:167], v228 offset:13920
	ds_read_b128 v[168:171], v228 offset:13936
	s_waitcnt lgkmcnt(14)
	v_pk_fma_f32 v[152:153], v[172:173], v[138:139], v[152:153] op_sel_hi:[1,0,1] neg_lo:[1,0,0] neg_hi:[1,0,0]
	v_pk_fma_f32 v[152:153], v[174:175], v[138:139], v[152:153] op_sel:[0,1,0] neg_lo:[1,0,0] neg_hi:[1,0,0]
	v_pk_fma_f32 v[152:153], v[176:177], v[140:141], v[152:153] op_sel_hi:[1,0,1] neg_lo:[1,0,0] neg_hi:[1,0,0]
	v_pk_fma_f32 v[152:153], v[178:179], v[140:141], v[152:153] op_sel:[0,1,0] neg_lo:[1,0,0] neg_hi:[1,0,0]
	ds_read_b128 v[172:175], v228 offset:13952
	ds_read_b128 v[176:179], v228 offset:13968
	s_waitcnt lgkmcnt(14)
	v_pk_fma_f32 v[152:153], v[180:181], v[142:143], v[152:153] op_sel_hi:[1,0,1] neg_lo:[1,0,0] neg_hi:[1,0,0]
	v_pk_fma_f32 v[152:153], v[182:183], v[142:143], v[152:153] op_sel:[0,1,0] neg_lo:[1,0,0] neg_hi:[1,0,0]
	v_pk_fma_f32 v[152:153], v[184:185], v[144:145], v[152:153] op_sel_hi:[1,0,1] neg_lo:[1,0,0] neg_hi:[1,0,0]
	v_pk_fma_f32 v[152:153], v[186:187], v[144:145], v[152:153] op_sel:[0,1,0] neg_lo:[1,0,0] neg_hi:[1,0,0]
	ds_read_b128 v[180:183], v228 offset:13984
	ds_read_b128 v[184:187], v228 offset:14000
	s_waitcnt lgkmcnt(14)
	v_pk_fma_f32 v[152:153], v[188:189], v[146:147], v[152:153] op_sel_hi:[1,0,1] neg_lo:[1,0,0] neg_hi:[1,0,0]
	v_pk_fma_f32 v[152:153], v[190:191], v[146:147], v[152:153] op_sel:[0,1,0] neg_lo:[1,0,0] neg_hi:[1,0,0]
	v_pk_fma_f32 v[152:153], v[192:193], v[148:149], v[152:153] op_sel_hi:[1,0,1] neg_lo:[1,0,0] neg_hi:[1,0,0]
	v_pk_fma_f32 v[152:153], v[194:195], v[148:149], v[152:153] op_sel:[0,1,0] neg_lo:[1,0,0] neg_hi:[1,0,0]
	ds_read_b128 v[188:191], v228 offset:14016
	ds_read_b128 v[192:195], v228 offset:14032
	s_waitcnt lgkmcnt(14)
	v_pk_fma_f32 v[152:153], v[196:197], v[150:151], v[152:153] op_sel_hi:[1,0,1] neg_lo:[1,0,0] neg_hi:[1,0,0]
	v_pk_fma_f32 v[152:153], v[198:199], v[150:151], v[152:153] op_sel:[0,1,0] neg_lo:[1,0,0] neg_hi:[1,0,0]
	v_fma_f32 v153, -v201, v152, v153
	ds_read_b128 v[196:199], v228 offset:14048
	ds_read_b128 v[200:203], v228 offset:14064
	s_waitcnt lgkmcnt(14)
	v_pk_fma_f32 v[154:155], v[204:205], v[100:101], v[154:155] op_sel_hi:[1,0,1] neg_lo:[1,0,0] neg_hi:[1,0,0]
	v_pk_fma_f32 v[154:155], v[206:207], v[100:101], v[154:155] op_sel:[0,1,0] neg_lo:[1,0,0] neg_hi:[1,0,0]
	v_pk_fma_f32 v[154:155], v[208:209], v[102:103], v[154:155] op_sel_hi:[1,0,1] neg_lo:[1,0,0] neg_hi:[1,0,0]
	v_pk_fma_f32 v[154:155], v[210:211], v[102:103], v[154:155] op_sel:[0,1,0] neg_lo:[1,0,0] neg_hi:[1,0,0]
	ds_read_b128 v[204:207], v228 offset:14080
	ds_read_b128 v[208:211], v228 offset:14096
	s_waitcnt lgkmcnt(14)
	v_pk_fma_f32 v[154:155], v[212:213], v[104:105], v[154:155] op_sel_hi:[1,0,1] neg_lo:[1,0,0] neg_hi:[1,0,0]
	v_pk_fma_f32 v[154:155], v[214:215], v[104:105], v[154:155] op_sel:[0,1,0] neg_lo:[1,0,0] neg_hi:[1,0,0]
	v_pk_fma_f32 v[154:155], v[216:217], v[106:107], v[154:155] op_sel_hi:[1,0,1] neg_lo:[1,0,0] neg_hi:[1,0,0]
	v_pk_fma_f32 v[154:155], v[218:219], v[106:107], v[154:155] op_sel:[0,1,0] neg_lo:[1,0,0] neg_hi:[1,0,0]
	ds_read_b128 v[212:215], v228 offset:14112
	ds_read_b128 v[216:219], v228 offset:14128
	s_waitcnt lgkmcnt(14)
	v_pk_fma_f32 v[154:155], v[220:221], v[108:109], v[154:155] op_sel_hi:[1,0,1] neg_lo:[1,0,0] neg_hi:[1,0,0]
	v_pk_fma_f32 v[154:155], v[222:223], v[108:109], v[154:155] op_sel:[0,1,0] neg_lo:[1,0,0] neg_hi:[1,0,0]
	v_pk_fma_f32 v[154:155], v[224:225], v[110:111], v[154:155] op_sel_hi:[1,0,1] neg_lo:[1,0,0] neg_hi:[1,0,0]
	v_pk_fma_f32 v[154:155], v[226:227], v[110:111], v[154:155] op_sel:[0,1,0] neg_lo:[1,0,0] neg_hi:[1,0,0]
	ds_read_b128 v[220:223], v228 offset:14144
	ds_read_b128 v[224:227], v228 offset:14160
	s_waitcnt lgkmcnt(14)
	v_pk_fma_f32 v[154:155], v[164:165], v[112:113], v[154:155] op_sel_hi:[1,0,1] neg_lo:[1,0,0] neg_hi:[1,0,0]
	v_pk_fma_f32 v[154:155], v[166:167], v[112:113], v[154:155] op_sel:[0,1,0] neg_lo:[1,0,0] neg_hi:[1,0,0]
	v_pk_fma_f32 v[154:155], v[168:169], v[114:115], v[154:155] op_sel_hi:[1,0,1] neg_lo:[1,0,0] neg_hi:[1,0,0]
	v_pk_fma_f32 v[154:155], v[170:171], v[114:115], v[154:155] op_sel:[0,1,0] neg_lo:[1,0,0] neg_hi:[1,0,0]
	ds_read_b128 v[164:167], v228 offset:14176
	ds_read_b128 v[168:171], v228 offset:14192
	s_waitcnt lgkmcnt(14)
	v_pk_fma_f32 v[154:155], v[172:173], v[116:117], v[154:155] op_sel_hi:[1,0,1] neg_lo:[1,0,0] neg_hi:[1,0,0]
	v_pk_fma_f32 v[154:155], v[174:175], v[116:117], v[154:155] op_sel:[0,1,0] neg_lo:[1,0,0] neg_hi:[1,0,0]
	v_pk_fma_f32 v[154:155], v[176:177], v[118:119], v[154:155] op_sel_hi:[1,0,1] neg_lo:[1,0,0] neg_hi:[1,0,0]
	v_pk_fma_f32 v[154:155], v[178:179], v[118:119], v[154:155] op_sel:[0,1,0] neg_lo:[1,0,0] neg_hi:[1,0,0]
	ds_read_b128 v[172:175], v228 offset:14208
	ds_read_b128 v[176:179], v228 offset:14224
	s_waitcnt lgkmcnt(14)
	v_pk_fma_f32 v[154:155], v[180:181], v[120:121], v[154:155] op_sel_hi:[1,0,1] neg_lo:[1,0,0] neg_hi:[1,0,0]
	v_pk_fma_f32 v[154:155], v[182:183], v[120:121], v[154:155] op_sel:[0,1,0] neg_lo:[1,0,0] neg_hi:[1,0,0]
	v_pk_fma_f32 v[154:155], v[184:185], v[122:123], v[154:155] op_sel_hi:[1,0,1] neg_lo:[1,0,0] neg_hi:[1,0,0]
	v_pk_fma_f32 v[154:155], v[186:187], v[122:123], v[154:155] op_sel:[0,1,0] neg_lo:[1,0,0] neg_hi:[1,0,0]
	ds_read_b128 v[180:183], v228 offset:14240
	ds_read_b128 v[184:187], v228 offset:14256
	s_waitcnt lgkmcnt(14)
	v_pk_fma_f32 v[154:155], v[188:189], v[124:125], v[154:155] op_sel_hi:[1,0,1] neg_lo:[1,0,0] neg_hi:[1,0,0]
	v_pk_fma_f32 v[154:155], v[190:191], v[124:125], v[154:155] op_sel:[0,1,0] neg_lo:[1,0,0] neg_hi:[1,0,0]
	v_pk_fma_f32 v[154:155], v[192:193], v[126:127], v[154:155] op_sel_hi:[1,0,1] neg_lo:[1,0,0] neg_hi:[1,0,0]
	v_pk_fma_f32 v[154:155], v[194:195], v[126:127], v[154:155] op_sel:[0,1,0] neg_lo:[1,0,0] neg_hi:[1,0,0]
	ds_read_b128 v[188:191], v228 offset:14336
	ds_read_b128 v[192:195], v228 offset:14352
	s_waitcnt lgkmcnt(14)
	v_pk_fma_f32 v[154:155], v[196:197], v[128:129], v[154:155] op_sel_hi:[1,0,1] neg_lo:[1,0,0] neg_hi:[1,0,0]
	v_pk_fma_f32 v[154:155], v[198:199], v[128:129], v[154:155] op_sel:[0,1,0] neg_lo:[1,0,0] neg_hi:[1,0,0]
	v_pk_fma_f32 v[154:155], v[200:201], v[130:131], v[154:155] op_sel_hi:[1,0,1] neg_lo:[1,0,0] neg_hi:[1,0,0]
	v_pk_fma_f32 v[154:155], v[202:203], v[130:131], v[154:155] op_sel:[0,1,0] neg_lo:[1,0,0] neg_hi:[1,0,0]
	ds_read_b128 v[196:199], v228 offset:14368
	ds_read_b128 v[200:203], v228 offset:14384
	s_waitcnt lgkmcnt(14)
	v_pk_fma_f32 v[154:155], v[204:205], v[132:133], v[154:155] op_sel_hi:[1,0,1] neg_lo:[1,0,0] neg_hi:[1,0,0]
	v_pk_fma_f32 v[154:155], v[206:207], v[132:133], v[154:155] op_sel:[0,1,0] neg_lo:[1,0,0] neg_hi:[1,0,0]
	v_pk_fma_f32 v[154:155], v[208:209], v[134:135], v[154:155] op_sel_hi:[1,0,1] neg_lo:[1,0,0] neg_hi:[1,0,0]
	v_pk_fma_f32 v[154:155], v[210:211], v[134:135], v[154:155] op_sel:[0,1,0] neg_lo:[1,0,0] neg_hi:[1,0,0]
	ds_read_b128 v[204:207], v228 offset:14400
	ds_read_b128 v[208:211], v228 offset:14416
	s_waitcnt lgkmcnt(14)
	v_pk_fma_f32 v[154:155], v[212:213], v[136:137], v[154:155] op_sel_hi:[1,0,1] neg_lo:[1,0,0] neg_hi:[1,0,0]
	v_pk_fma_f32 v[154:155], v[214:215], v[136:137], v[154:155] op_sel:[0,1,0] neg_lo:[1,0,0] neg_hi:[1,0,0]
	v_pk_fma_f32 v[154:155], v[216:217], v[138:139], v[154:155] op_sel_hi:[1,0,1] neg_lo:[1,0,0] neg_hi:[1,0,0]
	v_pk_fma_f32 v[154:155], v[218:219], v[138:139], v[154:155] op_sel:[0,1,0] neg_lo:[1,0,0] neg_hi:[1,0,0]
	ds_read_b128 v[212:215], v228 offset:14432
	ds_read_b128 v[216:219], v228 offset:14448
	s_waitcnt lgkmcnt(14)
	v_pk_fma_f32 v[154:155], v[220:221], v[140:141], v[154:155] op_sel_hi:[1,0,1] neg_lo:[1,0,0] neg_hi:[1,0,0]
	v_pk_fma_f32 v[154:155], v[222:223], v[140:141], v[154:155] op_sel:[0,1,0] neg_lo:[1,0,0] neg_hi:[1,0,0]
	v_pk_fma_f32 v[154:155], v[224:225], v[142:143], v[154:155] op_sel_hi:[1,0,1] neg_lo:[1,0,0] neg_hi:[1,0,0]
	v_pk_fma_f32 v[154:155], v[226:227], v[142:143], v[154:155] op_sel:[0,1,0] neg_lo:[1,0,0] neg_hi:[1,0,0]
	ds_read_b128 v[220:223], v228 offset:14464
	ds_read_b128 v[224:227], v228 offset:14480
	s_waitcnt lgkmcnt(14)
	v_pk_fma_f32 v[154:155], v[164:165], v[144:145], v[154:155] op_sel_hi:[1,0,1] neg_lo:[1,0,0] neg_hi:[1,0,0]
	v_pk_fma_f32 v[154:155], v[166:167], v[144:145], v[154:155] op_sel:[0,1,0] neg_lo:[1,0,0] neg_hi:[1,0,0]
	v_pk_fma_f32 v[154:155], v[168:169], v[146:147], v[154:155] op_sel_hi:[1,0,1] neg_lo:[1,0,0] neg_hi:[1,0,0]
	v_pk_fma_f32 v[154:155], v[170:171], v[146:147], v[154:155] op_sel:[0,1,0] neg_lo:[1,0,0] neg_hi:[1,0,0]
	ds_read_b128 v[164:167], v228 offset:14496
	ds_read_b128 v[168:171], v228 offset:14512
	s_waitcnt lgkmcnt(14)
	v_pk_fma_f32 v[154:155], v[172:173], v[148:149], v[154:155] op_sel_hi:[1,0,1] neg_lo:[1,0,0] neg_hi:[1,0,0]
	v_pk_fma_f32 v[154:155], v[174:175], v[148:149], v[154:155] op_sel:[0,1,0] neg_lo:[1,0,0] neg_hi:[1,0,0]
	v_pk_fma_f32 v[154:155], v[176:177], v[150:151], v[154:155] op_sel_hi:[1,0,1] neg_lo:[1,0,0] neg_hi:[1,0,0]
	v_pk_fma_f32 v[154:155], v[178:179], v[150:151], v[154:155] op_sel:[0,1,0] neg_lo:[1,0,0] neg_hi:[1,0,0]
	ds_read_b128 v[172:175], v228 offset:14528
	ds_read_b128 v[176:179], v228 offset:14544
	s_waitcnt lgkmcnt(14)
	v_pk_fma_f32 v[154:155], v[180:181], v[152:153], v[154:155] op_sel_hi:[1,0,1] neg_lo:[1,0,0] neg_hi:[1,0,0]
	v_pk_fma_f32 v[154:155], v[182:183], v[152:153], v[154:155] op_sel:[0,1,0] neg_lo:[1,0,0] neg_hi:[1,0,0]
	v_fma_f32 v155, -v185, v154, v155
	ds_read_b128 v[180:183], v228 offset:14560
	ds_read_b128 v[184:187], v228 offset:14576
	s_waitcnt lgkmcnt(14)
	v_pk_fma_f32 v[156:157], v[188:189], v[100:101], v[156:157] op_sel_hi:[1,0,1] neg_lo:[1,0,0] neg_hi:[1,0,0]
	v_pk_fma_f32 v[156:157], v[190:191], v[100:101], v[156:157] op_sel:[0,1,0] neg_lo:[1,0,0] neg_hi:[1,0,0]
	v_pk_fma_f32 v[156:157], v[192:193], v[102:103], v[156:157] op_sel_hi:[1,0,1] neg_lo:[1,0,0] neg_hi:[1,0,0]
	v_pk_fma_f32 v[156:157], v[194:195], v[102:103], v[156:157] op_sel:[0,1,0] neg_lo:[1,0,0] neg_hi:[1,0,0]
	ds_read_b128 v[188:191], v228 offset:14592
	ds_read_b128 v[192:195], v228 offset:14608
	s_waitcnt lgkmcnt(14)
	v_pk_fma_f32 v[156:157], v[196:197], v[104:105], v[156:157] op_sel_hi:[1,0,1] neg_lo:[1,0,0] neg_hi:[1,0,0]
	v_pk_fma_f32 v[156:157], v[198:199], v[104:105], v[156:157] op_sel:[0,1,0] neg_lo:[1,0,0] neg_hi:[1,0,0]
	v_pk_fma_f32 v[156:157], v[200:201], v[106:107], v[156:157] op_sel_hi:[1,0,1] neg_lo:[1,0,0] neg_hi:[1,0,0]
	v_pk_fma_f32 v[156:157], v[202:203], v[106:107], v[156:157] op_sel:[0,1,0] neg_lo:[1,0,0] neg_hi:[1,0,0]
	ds_read_b128 v[196:199], v228 offset:14624
	ds_read_b128 v[200:203], v228 offset:14640
	s_waitcnt lgkmcnt(14)
	v_pk_fma_f32 v[156:157], v[204:205], v[108:109], v[156:157] op_sel_hi:[1,0,1] neg_lo:[1,0,0] neg_hi:[1,0,0]
	v_pk_fma_f32 v[156:157], v[206:207], v[108:109], v[156:157] op_sel:[0,1,0] neg_lo:[1,0,0] neg_hi:[1,0,0]
	v_pk_fma_f32 v[156:157], v[208:209], v[110:111], v[156:157] op_sel_hi:[1,0,1] neg_lo:[1,0,0] neg_hi:[1,0,0]
	v_pk_fma_f32 v[156:157], v[210:211], v[110:111], v[156:157] op_sel:[0,1,0] neg_lo:[1,0,0] neg_hi:[1,0,0]
	ds_read_b128 v[204:207], v228 offset:14656
	ds_read_b128 v[208:211], v228 offset:14672
	s_waitcnt lgkmcnt(14)
	v_pk_fma_f32 v[156:157], v[212:213], v[112:113], v[156:157] op_sel_hi:[1,0,1] neg_lo:[1,0,0] neg_hi:[1,0,0]
	v_pk_fma_f32 v[156:157], v[214:215], v[112:113], v[156:157] op_sel:[0,1,0] neg_lo:[1,0,0] neg_hi:[1,0,0]
	v_pk_fma_f32 v[156:157], v[216:217], v[114:115], v[156:157] op_sel_hi:[1,0,1] neg_lo:[1,0,0] neg_hi:[1,0,0]
	v_pk_fma_f32 v[156:157], v[218:219], v[114:115], v[156:157] op_sel:[0,1,0] neg_lo:[1,0,0] neg_hi:[1,0,0]
	ds_read_b128 v[212:215], v228 offset:14688
	ds_read_b128 v[216:219], v228 offset:14704
	s_waitcnt lgkmcnt(14)
	v_pk_fma_f32 v[156:157], v[220:221], v[116:117], v[156:157] op_sel_hi:[1,0,1] neg_lo:[1,0,0] neg_hi:[1,0,0]
	v_pk_fma_f32 v[156:157], v[222:223], v[116:117], v[156:157] op_sel:[0,1,0] neg_lo:[1,0,0] neg_hi:[1,0,0]
	v_pk_fma_f32 v[156:157], v[224:225], v[118:119], v[156:157] op_sel_hi:[1,0,1] neg_lo:[1,0,0] neg_hi:[1,0,0]
	v_pk_fma_f32 v[156:157], v[226:227], v[118:119], v[156:157] op_sel:[0,1,0] neg_lo:[1,0,0] neg_hi:[1,0,0]
	ds_read_b128 v[220:223], v228 offset:14720
	ds_read_b128 v[224:227], v228 offset:14736
	s_waitcnt lgkmcnt(14)
	v_pk_fma_f32 v[156:157], v[164:165], v[120:121], v[156:157] op_sel_hi:[1,0,1] neg_lo:[1,0,0] neg_hi:[1,0,0]
	v_pk_fma_f32 v[156:157], v[166:167], v[120:121], v[156:157] op_sel:[0,1,0] neg_lo:[1,0,0] neg_hi:[1,0,0]
	v_pk_fma_f32 v[156:157], v[168:169], v[122:123], v[156:157] op_sel_hi:[1,0,1] neg_lo:[1,0,0] neg_hi:[1,0,0]
	v_pk_fma_f32 v[156:157], v[170:171], v[122:123], v[156:157] op_sel:[0,1,0] neg_lo:[1,0,0] neg_hi:[1,0,0]
	ds_read_b128 v[164:167], v228 offset:14752
	ds_read_b128 v[168:171], v228 offset:14768
	s_waitcnt lgkmcnt(14)
	v_pk_fma_f32 v[156:157], v[172:173], v[124:125], v[156:157] op_sel_hi:[1,0,1] neg_lo:[1,0,0] neg_hi:[1,0,0]
	v_pk_fma_f32 v[156:157], v[174:175], v[124:125], v[156:157] op_sel:[0,1,0] neg_lo:[1,0,0] neg_hi:[1,0,0]
	v_pk_fma_f32 v[156:157], v[176:177], v[126:127], v[156:157] op_sel_hi:[1,0,1] neg_lo:[1,0,0] neg_hi:[1,0,0]
	v_pk_fma_f32 v[156:157], v[178:179], v[126:127], v[156:157] op_sel:[0,1,0] neg_lo:[1,0,0] neg_hi:[1,0,0]
	ds_read_b128 v[172:175], v228 offset:14784
	ds_read_b128 v[176:179], v228 offset:14848
	s_waitcnt lgkmcnt(14)
	v_pk_fma_f32 v[156:157], v[180:181], v[128:129], v[156:157] op_sel_hi:[1,0,1] neg_lo:[1,0,0] neg_hi:[1,0,0]
	v_pk_fma_f32 v[156:157], v[182:183], v[128:129], v[156:157] op_sel:[0,1,0] neg_lo:[1,0,0] neg_hi:[1,0,0]
	v_pk_fma_f32 v[156:157], v[184:185], v[130:131], v[156:157] op_sel_hi:[1,0,1] neg_lo:[1,0,0] neg_hi:[1,0,0]
	v_pk_fma_f32 v[156:157], v[186:187], v[130:131], v[156:157] op_sel:[0,1,0] neg_lo:[1,0,0] neg_hi:[1,0,0]
	ds_read_b128 v[180:183], v228 offset:14864
	ds_read_b128 v[184:187], v228 offset:14880
	s_waitcnt lgkmcnt(14)
	v_pk_fma_f32 v[156:157], v[188:189], v[132:133], v[156:157] op_sel_hi:[1,0,1] neg_lo:[1,0,0] neg_hi:[1,0,0]
	v_pk_fma_f32 v[156:157], v[190:191], v[132:133], v[156:157] op_sel:[0,1,0] neg_lo:[1,0,0] neg_hi:[1,0,0]
	v_pk_fma_f32 v[156:157], v[192:193], v[134:135], v[156:157] op_sel_hi:[1,0,1] neg_lo:[1,0,0] neg_hi:[1,0,0]
	v_pk_fma_f32 v[156:157], v[194:195], v[134:135], v[156:157] op_sel:[0,1,0] neg_lo:[1,0,0] neg_hi:[1,0,0]
	ds_read_b128 v[188:191], v228 offset:14896
	ds_read_b128 v[192:195], v228 offset:14912
	s_waitcnt lgkmcnt(14)
	v_pk_fma_f32 v[156:157], v[196:197], v[136:137], v[156:157] op_sel_hi:[1,0,1] neg_lo:[1,0,0] neg_hi:[1,0,0]
	v_pk_fma_f32 v[156:157], v[198:199], v[136:137], v[156:157] op_sel:[0,1,0] neg_lo:[1,0,0] neg_hi:[1,0,0]
	v_pk_fma_f32 v[156:157], v[200:201], v[138:139], v[156:157] op_sel_hi:[1,0,1] neg_lo:[1,0,0] neg_hi:[1,0,0]
	v_pk_fma_f32 v[156:157], v[202:203], v[138:139], v[156:157] op_sel:[0,1,0] neg_lo:[1,0,0] neg_hi:[1,0,0]
	ds_read_b128 v[196:199], v228 offset:14928
	ds_read_b128 v[200:203], v228 offset:14944
	s_waitcnt lgkmcnt(14)
	v_pk_fma_f32 v[156:157], v[204:205], v[140:141], v[156:157] op_sel_hi:[1,0,1] neg_lo:[1,0,0] neg_hi:[1,0,0]
	v_pk_fma_f32 v[156:157], v[206:207], v[140:141], v[156:157] op_sel:[0,1,0] neg_lo:[1,0,0] neg_hi:[1,0,0]
	v_pk_fma_f32 v[156:157], v[208:209], v[142:143], v[156:157] op_sel_hi:[1,0,1] neg_lo:[1,0,0] neg_hi:[1,0,0]
	v_pk_fma_f32 v[156:157], v[210:211], v[142:143], v[156:157] op_sel:[0,1,0] neg_lo:[1,0,0] neg_hi:[1,0,0]
	ds_read_b128 v[204:207], v228 offset:14960
	ds_read_b128 v[208:211], v228 offset:14976
	s_waitcnt lgkmcnt(14)
	v_pk_fma_f32 v[156:157], v[212:213], v[144:145], v[156:157] op_sel_hi:[1,0,1] neg_lo:[1,0,0] neg_hi:[1,0,0]
	v_pk_fma_f32 v[156:157], v[214:215], v[144:145], v[156:157] op_sel:[0,1,0] neg_lo:[1,0,0] neg_hi:[1,0,0]
	v_pk_fma_f32 v[156:157], v[216:217], v[146:147], v[156:157] op_sel_hi:[1,0,1] neg_lo:[1,0,0] neg_hi:[1,0,0]
	v_pk_fma_f32 v[156:157], v[218:219], v[146:147], v[156:157] op_sel:[0,1,0] neg_lo:[1,0,0] neg_hi:[1,0,0]
	ds_read_b128 v[212:215], v228 offset:14992
	ds_read_b128 v[216:219], v228 offset:15008
	s_waitcnt lgkmcnt(14)
	v_pk_fma_f32 v[156:157], v[220:221], v[148:149], v[156:157] op_sel_hi:[1,0,1] neg_lo:[1,0,0] neg_hi:[1,0,0]
	v_pk_fma_f32 v[156:157], v[222:223], v[148:149], v[156:157] op_sel:[0,1,0] neg_lo:[1,0,0] neg_hi:[1,0,0]
	v_pk_fma_f32 v[156:157], v[224:225], v[150:151], v[156:157] op_sel_hi:[1,0,1] neg_lo:[1,0,0] neg_hi:[1,0,0]
	v_pk_fma_f32 v[156:157], v[226:227], v[150:151], v[156:157] op_sel:[0,1,0] neg_lo:[1,0,0] neg_hi:[1,0,0]
	ds_read_b128 v[220:223], v228 offset:15024
	ds_read_b128 v[224:227], v228 offset:15040
	s_waitcnt lgkmcnt(14)
	v_pk_fma_f32 v[156:157], v[164:165], v[152:153], v[156:157] op_sel_hi:[1,0,1] neg_lo:[1,0,0] neg_hi:[1,0,0]
	v_pk_fma_f32 v[156:157], v[166:167], v[152:153], v[156:157] op_sel:[0,1,0] neg_lo:[1,0,0] neg_hi:[1,0,0]
	v_pk_fma_f32 v[156:157], v[168:169], v[154:155], v[156:157] op_sel_hi:[1,0,1] neg_lo:[1,0,0] neg_hi:[1,0,0]
	v_pk_fma_f32 v[156:157], v[170:171], v[154:155], v[156:157] op_sel:[0,1,0] neg_lo:[1,0,0] neg_hi:[1,0,0]
	ds_read_b128 v[164:167], v228 offset:15056
	ds_read_b128 v[168:171], v228 offset:15072
	s_waitcnt lgkmcnt(14)
	v_fma_f32 v157, -v173, v156, v157
	v_pk_fma_f32 v[158:159], v[176:177], v[100:101], v[158:159] op_sel_hi:[1,0,1] neg_lo:[1,0,0] neg_hi:[1,0,0]
	v_pk_fma_f32 v[158:159], v[178:179], v[100:101], v[158:159] op_sel:[0,1,0] neg_lo:[1,0,0] neg_hi:[1,0,0]
	ds_read_b128 v[172:175], v228 offset:15088
	ds_read_b128 v[176:179], v228 offset:15104
	s_waitcnt lgkmcnt(14)
	v_pk_fma_f32 v[158:159], v[180:181], v[102:103], v[158:159] op_sel_hi:[1,0,1] neg_lo:[1,0,0] neg_hi:[1,0,0]
	v_pk_fma_f32 v[158:159], v[182:183], v[102:103], v[158:159] op_sel:[0,1,0] neg_lo:[1,0,0] neg_hi:[1,0,0]
	v_pk_fma_f32 v[158:159], v[184:185], v[104:105], v[158:159] op_sel_hi:[1,0,1] neg_lo:[1,0,0] neg_hi:[1,0,0]
	v_pk_fma_f32 v[158:159], v[186:187], v[104:105], v[158:159] op_sel:[0,1,0] neg_lo:[1,0,0] neg_hi:[1,0,0]
	ds_read_b128 v[180:183], v228 offset:15120
	ds_read_b128 v[184:187], v228 offset:15136
	s_waitcnt lgkmcnt(14)
	v_pk_fma_f32 v[158:159], v[188:189], v[106:107], v[158:159] op_sel_hi:[1,0,1] neg_lo:[1,0,0] neg_hi:[1,0,0]
	v_pk_fma_f32 v[158:159], v[190:191], v[106:107], v[158:159] op_sel:[0,1,0] neg_lo:[1,0,0] neg_hi:[1,0,0]
	v_pk_fma_f32 v[158:159], v[192:193], v[108:109], v[158:159] op_sel_hi:[1,0,1] neg_lo:[1,0,0] neg_hi:[1,0,0]
	v_pk_fma_f32 v[158:159], v[194:195], v[108:109], v[158:159] op_sel:[0,1,0] neg_lo:[1,0,0] neg_hi:[1,0,0]
	ds_read_b128 v[188:191], v228 offset:15152
	ds_read_b128 v[192:195], v228 offset:15168
	s_waitcnt lgkmcnt(14)
	v_pk_fma_f32 v[158:159], v[196:197], v[110:111], v[158:159] op_sel_hi:[1,0,1] neg_lo:[1,0,0] neg_hi:[1,0,0]
	v_pk_fma_f32 v[158:159], v[198:199], v[110:111], v[158:159] op_sel:[0,1,0] neg_lo:[1,0,0] neg_hi:[1,0,0]
	v_pk_fma_f32 v[158:159], v[200:201], v[112:113], v[158:159] op_sel_hi:[1,0,1] neg_lo:[1,0,0] neg_hi:[1,0,0]
	v_pk_fma_f32 v[158:159], v[202:203], v[112:113], v[158:159] op_sel:[0,1,0] neg_lo:[1,0,0] neg_hi:[1,0,0]
	ds_read_b128 v[196:199], v228 offset:15184
	ds_read_b128 v[200:203], v228 offset:15200
	s_waitcnt lgkmcnt(14)
	v_pk_fma_f32 v[158:159], v[204:205], v[114:115], v[158:159] op_sel_hi:[1,0,1] neg_lo:[1,0,0] neg_hi:[1,0,0]
	v_pk_fma_f32 v[158:159], v[206:207], v[114:115], v[158:159] op_sel:[0,1,0] neg_lo:[1,0,0] neg_hi:[1,0,0]
	v_pk_fma_f32 v[158:159], v[208:209], v[116:117], v[158:159] op_sel_hi:[1,0,1] neg_lo:[1,0,0] neg_hi:[1,0,0]
	v_pk_fma_f32 v[158:159], v[210:211], v[116:117], v[158:159] op_sel:[0,1,0] neg_lo:[1,0,0] neg_hi:[1,0,0]
	ds_read_b128 v[204:207], v228 offset:15216
	ds_read_b128 v[208:211], v228 offset:15232
	s_waitcnt lgkmcnt(14)
	v_pk_fma_f32 v[158:159], v[212:213], v[118:119], v[158:159] op_sel_hi:[1,0,1] neg_lo:[1,0,0] neg_hi:[1,0,0]
	v_pk_fma_f32 v[158:159], v[214:215], v[118:119], v[158:159] op_sel:[0,1,0] neg_lo:[1,0,0] neg_hi:[1,0,0]
	v_pk_fma_f32 v[158:159], v[216:217], v[120:121], v[158:159] op_sel_hi:[1,0,1] neg_lo:[1,0,0] neg_hi:[1,0,0]
	v_pk_fma_f32 v[158:159], v[218:219], v[120:121], v[158:159] op_sel:[0,1,0] neg_lo:[1,0,0] neg_hi:[1,0,0]
	ds_read_b128 v[212:215], v228 offset:15248
	ds_read_b128 v[216:219], v228 offset:15264
	s_waitcnt lgkmcnt(14)
	v_pk_fma_f32 v[158:159], v[220:221], v[122:123], v[158:159] op_sel_hi:[1,0,1] neg_lo:[1,0,0] neg_hi:[1,0,0]
	v_pk_fma_f32 v[158:159], v[222:223], v[122:123], v[158:159] op_sel:[0,1,0] neg_lo:[1,0,0] neg_hi:[1,0,0]
	v_pk_fma_f32 v[158:159], v[224:225], v[124:125], v[158:159] op_sel_hi:[1,0,1] neg_lo:[1,0,0] neg_hi:[1,0,0]
	v_pk_fma_f32 v[158:159], v[226:227], v[124:125], v[158:159] op_sel:[0,1,0] neg_lo:[1,0,0] neg_hi:[1,0,0]
	ds_read_b128 v[220:223], v228 offset:15280
	ds_read_b128 v[224:227], v228 offset:15296
	s_waitcnt lgkmcnt(14)
	v_pk_fma_f32 v[158:159], v[164:165], v[126:127], v[158:159] op_sel_hi:[1,0,1] neg_lo:[1,0,0] neg_hi:[1,0,0]
	v_pk_fma_f32 v[158:159], v[166:167], v[126:127], v[158:159] op_sel:[0,1,0] neg_lo:[1,0,0] neg_hi:[1,0,0]
	v_pk_fma_f32 v[158:159], v[168:169], v[128:129], v[158:159] op_sel_hi:[1,0,1] neg_lo:[1,0,0] neg_hi:[1,0,0]
	v_pk_fma_f32 v[158:159], v[170:171], v[128:129], v[158:159] op_sel:[0,1,0] neg_lo:[1,0,0] neg_hi:[1,0,0]
	ds_read_b128 v[164:167], v228 offset:15312
	ds_read_b128 v[168:171], v228 offset:15360
	s_waitcnt lgkmcnt(14)
	v_pk_fma_f32 v[158:159], v[172:173], v[130:131], v[158:159] op_sel_hi:[1,0,1] neg_lo:[1,0,0] neg_hi:[1,0,0]
	v_pk_fma_f32 v[158:159], v[174:175], v[130:131], v[158:159] op_sel:[0,1,0] neg_lo:[1,0,0] neg_hi:[1,0,0]
	v_pk_fma_f32 v[158:159], v[176:177], v[132:133], v[158:159] op_sel_hi:[1,0,1] neg_lo:[1,0,0] neg_hi:[1,0,0]
	v_pk_fma_f32 v[158:159], v[178:179], v[132:133], v[158:159] op_sel:[0,1,0] neg_lo:[1,0,0] neg_hi:[1,0,0]
	ds_read_b128 v[172:175], v228 offset:15376
	ds_read_b128 v[176:179], v228 offset:15392
	s_waitcnt lgkmcnt(14)
	v_pk_fma_f32 v[158:159], v[180:181], v[134:135], v[158:159] op_sel_hi:[1,0,1] neg_lo:[1,0,0] neg_hi:[1,0,0]
	v_pk_fma_f32 v[158:159], v[182:183], v[134:135], v[158:159] op_sel:[0,1,0] neg_lo:[1,0,0] neg_hi:[1,0,0]
	v_pk_fma_f32 v[158:159], v[184:185], v[136:137], v[158:159] op_sel_hi:[1,0,1] neg_lo:[1,0,0] neg_hi:[1,0,0]
	v_pk_fma_f32 v[158:159], v[186:187], v[136:137], v[158:159] op_sel:[0,1,0] neg_lo:[1,0,0] neg_hi:[1,0,0]
	ds_read_b128 v[180:183], v228 offset:15408
	ds_read_b128 v[184:187], v228 offset:15424
	s_waitcnt lgkmcnt(14)
	v_pk_fma_f32 v[158:159], v[188:189], v[138:139], v[158:159] op_sel_hi:[1,0,1] neg_lo:[1,0,0] neg_hi:[1,0,0]
	v_pk_fma_f32 v[158:159], v[190:191], v[138:139], v[158:159] op_sel:[0,1,0] neg_lo:[1,0,0] neg_hi:[1,0,0]
	v_pk_fma_f32 v[158:159], v[192:193], v[140:141], v[158:159] op_sel_hi:[1,0,1] neg_lo:[1,0,0] neg_hi:[1,0,0]
	v_pk_fma_f32 v[158:159], v[194:195], v[140:141], v[158:159] op_sel:[0,1,0] neg_lo:[1,0,0] neg_hi:[1,0,0]
	ds_read_b128 v[188:191], v228 offset:15440
	ds_read_b128 v[192:195], v228 offset:15456
	s_waitcnt lgkmcnt(14)
	v_pk_fma_f32 v[158:159], v[196:197], v[142:143], v[158:159] op_sel_hi:[1,0,1] neg_lo:[1,0,0] neg_hi:[1,0,0]
	v_pk_fma_f32 v[158:159], v[198:199], v[142:143], v[158:159] op_sel:[0,1,0] neg_lo:[1,0,0] neg_hi:[1,0,0]
	v_pk_fma_f32 v[158:159], v[200:201], v[144:145], v[158:159] op_sel_hi:[1,0,1] neg_lo:[1,0,0] neg_hi:[1,0,0]
	v_pk_fma_f32 v[158:159], v[202:203], v[144:145], v[158:159] op_sel:[0,1,0] neg_lo:[1,0,0] neg_hi:[1,0,0]
	ds_read_b128 v[196:199], v228 offset:15472
	ds_read_b128 v[200:203], v228 offset:15488
	s_waitcnt lgkmcnt(14)
	v_pk_fma_f32 v[158:159], v[204:205], v[146:147], v[158:159] op_sel_hi:[1,0,1] neg_lo:[1,0,0] neg_hi:[1,0,0]
	v_pk_fma_f32 v[158:159], v[206:207], v[146:147], v[158:159] op_sel:[0,1,0] neg_lo:[1,0,0] neg_hi:[1,0,0]
	v_pk_fma_f32 v[158:159], v[208:209], v[148:149], v[158:159] op_sel_hi:[1,0,1] neg_lo:[1,0,0] neg_hi:[1,0,0]
	v_pk_fma_f32 v[158:159], v[210:211], v[148:149], v[158:159] op_sel:[0,1,0] neg_lo:[1,0,0] neg_hi:[1,0,0]
	ds_read_b128 v[204:207], v228 offset:15504
	ds_read_b128 v[208:211], v228 offset:15520
	s_waitcnt lgkmcnt(14)
	v_pk_fma_f32 v[158:159], v[212:213], v[150:151], v[158:159] op_sel_hi:[1,0,1] neg_lo:[1,0,0] neg_hi:[1,0,0]
	v_pk_fma_f32 v[158:159], v[214:215], v[150:151], v[158:159] op_sel:[0,1,0] neg_lo:[1,0,0] neg_hi:[1,0,0]
	v_pk_fma_f32 v[158:159], v[216:217], v[152:153], v[158:159] op_sel_hi:[1,0,1] neg_lo:[1,0,0] neg_hi:[1,0,0]
	v_pk_fma_f32 v[158:159], v[218:219], v[152:153], v[158:159] op_sel:[0,1,0] neg_lo:[1,0,0] neg_hi:[1,0,0]
	ds_read_b128 v[212:215], v228 offset:15536
	ds_read_b128 v[216:219], v228 offset:15552
	s_waitcnt lgkmcnt(14)
	v_pk_fma_f32 v[158:159], v[220:221], v[154:155], v[158:159] op_sel_hi:[1,0,1] neg_lo:[1,0,0] neg_hi:[1,0,0]
	v_pk_fma_f32 v[158:159], v[222:223], v[154:155], v[158:159] op_sel:[0,1,0] neg_lo:[1,0,0] neg_hi:[1,0,0]
	v_pk_fma_f32 v[158:159], v[224:225], v[156:157], v[158:159] op_sel_hi:[1,0,1] neg_lo:[1,0,0] neg_hi:[1,0,0]
	v_pk_fma_f32 v[158:159], v[226:227], v[156:157], v[158:159] op_sel:[0,1,0] neg_lo:[1,0,0] neg_hi:[1,0,0]
	ds_read_b128 v[220:223], v228 offset:15568
	ds_read_b128 v[224:227], v228 offset:15584
	s_waitcnt lgkmcnt(14)
	v_fma_f32 v159, -v165, v158, v159
	v_pk_fma_f32 v[160:161], v[168:169], v[100:101], v[160:161] op_sel_hi:[1,0,1] neg_lo:[1,0,0] neg_hi:[1,0,0]
	v_pk_fma_f32 v[160:161], v[170:171], v[100:101], v[160:161] op_sel:[0,1,0] neg_lo:[1,0,0] neg_hi:[1,0,0]
	ds_read_b128 v[164:167], v228 offset:15600
	ds_read_b128 v[168:171], v228 offset:15616
	s_barrier
	s_waitcnt lgkmcnt(14)
	v_pk_fma_f32 v[160:161], v[172:173], v[102:103], v[160:161] op_sel_hi:[1,0,1] neg_lo:[1,0,0] neg_hi:[1,0,0]
	v_pk_fma_f32 v[160:161], v[174:175], v[102:103], v[160:161] op_sel:[0,1,0] neg_lo:[1,0,0] neg_hi:[1,0,0]
	v_pk_fma_f32 v[160:161], v[176:177], v[104:105], v[160:161] op_sel_hi:[1,0,1] neg_lo:[1,0,0] neg_hi:[1,0,0]
	v_pk_fma_f32 v[160:161], v[178:179], v[104:105], v[160:161] op_sel:[0,1,0] neg_lo:[1,0,0] neg_hi:[1,0,0]
	ds_read_b128 v[172:175], v228 offset:15632
	ds_read_b128 v[176:179], v228 offset:15648
	s_waitcnt lgkmcnt(14)
	v_pk_fma_f32 v[160:161], v[180:181], v[106:107], v[160:161] op_sel_hi:[1,0,1] neg_lo:[1,0,0] neg_hi:[1,0,0]
	v_pk_fma_f32 v[160:161], v[182:183], v[106:107], v[160:161] op_sel:[0,1,0] neg_lo:[1,0,0] neg_hi:[1,0,0]
	v_pk_fma_f32 v[160:161], v[184:185], v[108:109], v[160:161] op_sel_hi:[1,0,1] neg_lo:[1,0,0] neg_hi:[1,0,0]
	v_pk_fma_f32 v[160:161], v[186:187], v[108:109], v[160:161] op_sel:[0,1,0] neg_lo:[1,0,0] neg_hi:[1,0,0]
	ds_read_b128 v[180:183], v228 offset:15664
	ds_read_b128 v[184:187], v228 offset:15680
	s_waitcnt lgkmcnt(14)
	v_pk_fma_f32 v[160:161], v[188:189], v[110:111], v[160:161] op_sel_hi:[1,0,1] neg_lo:[1,0,0] neg_hi:[1,0,0]
	v_pk_fma_f32 v[160:161], v[190:191], v[110:111], v[160:161] op_sel:[0,1,0] neg_lo:[1,0,0] neg_hi:[1,0,0]
	v_pk_fma_f32 v[160:161], v[192:193], v[112:113], v[160:161] op_sel_hi:[1,0,1] neg_lo:[1,0,0] neg_hi:[1,0,0]
	v_pk_fma_f32 v[160:161], v[194:195], v[112:113], v[160:161] op_sel:[0,1,0] neg_lo:[1,0,0] neg_hi:[1,0,0]
	ds_read_b128 v[188:191], v228 offset:15696
	ds_read_b128 v[192:195], v228 offset:15712
	s_waitcnt lgkmcnt(14)
	v_pk_fma_f32 v[160:161], v[196:197], v[114:115], v[160:161] op_sel_hi:[1,0,1] neg_lo:[1,0,0] neg_hi:[1,0,0]
	v_pk_fma_f32 v[160:161], v[198:199], v[114:115], v[160:161] op_sel:[0,1,0] neg_lo:[1,0,0] neg_hi:[1,0,0]
	v_pk_fma_f32 v[160:161], v[200:201], v[116:117], v[160:161] op_sel_hi:[1,0,1] neg_lo:[1,0,0] neg_hi:[1,0,0]
	v_pk_fma_f32 v[160:161], v[202:203], v[116:117], v[160:161] op_sel:[0,1,0] neg_lo:[1,0,0] neg_hi:[1,0,0]
	ds_read_b128 v[196:199], v228 offset:15728
	ds_read_b128 v[200:203], v228 offset:15744
	s_waitcnt lgkmcnt(14)
	v_pk_fma_f32 v[160:161], v[204:205], v[118:119], v[160:161] op_sel_hi:[1,0,1] neg_lo:[1,0,0] neg_hi:[1,0,0]
	v_pk_fma_f32 v[160:161], v[206:207], v[118:119], v[160:161] op_sel:[0,1,0] neg_lo:[1,0,0] neg_hi:[1,0,0]
	v_pk_fma_f32 v[160:161], v[208:209], v[120:121], v[160:161] op_sel_hi:[1,0,1] neg_lo:[1,0,0] neg_hi:[1,0,0]
	v_pk_fma_f32 v[160:161], v[210:211], v[120:121], v[160:161] op_sel:[0,1,0] neg_lo:[1,0,0] neg_hi:[1,0,0]
	ds_read_b128 v[204:207], v228 offset:15760
	ds_read_b128 v[208:211], v228 offset:15776
	s_waitcnt lgkmcnt(14)
	v_pk_fma_f32 v[160:161], v[212:213], v[122:123], v[160:161] op_sel_hi:[1,0,1] neg_lo:[1,0,0] neg_hi:[1,0,0]
	v_pk_fma_f32 v[160:161], v[214:215], v[122:123], v[160:161] op_sel:[0,1,0] neg_lo:[1,0,0] neg_hi:[1,0,0]
	v_pk_fma_f32 v[160:161], v[216:217], v[124:125], v[160:161] op_sel_hi:[1,0,1] neg_lo:[1,0,0] neg_hi:[1,0,0]
	v_pk_fma_f32 v[160:161], v[218:219], v[124:125], v[160:161] op_sel:[0,1,0] neg_lo:[1,0,0] neg_hi:[1,0,0]
	ds_read_b128 v[212:215], v228 offset:15792
	ds_read_b128 v[216:219], v228 offset:15808
	s_waitcnt lgkmcnt(14)
	v_pk_fma_f32 v[160:161], v[220:221], v[126:127], v[160:161] op_sel_hi:[1,0,1] neg_lo:[1,0,0] neg_hi:[1,0,0]
	v_pk_fma_f32 v[160:161], v[222:223], v[126:127], v[160:161] op_sel:[0,1,0] neg_lo:[1,0,0] neg_hi:[1,0,0]
	v_pk_fma_f32 v[160:161], v[224:225], v[128:129], v[160:161] op_sel_hi:[1,0,1] neg_lo:[1,0,0] neg_hi:[1,0,0]
	v_pk_fma_f32 v[160:161], v[226:227], v[128:129], v[160:161] op_sel:[0,1,0] neg_lo:[1,0,0] neg_hi:[1,0,0]
	ds_read_b128 v[220:223], v228 offset:15824
	ds_read_b128 v[224:227], v228 offset:15840
	s_waitcnt lgkmcnt(14)
	v_pk_fma_f32 v[160:161], v[164:165], v[130:131], v[160:161] op_sel_hi:[1,0,1] neg_lo:[1,0,0] neg_hi:[1,0,0]
	v_pk_fma_f32 v[160:161], v[166:167], v[130:131], v[160:161] op_sel:[0,1,0] neg_lo:[1,0,0] neg_hi:[1,0,0]
	v_pk_fma_f32 v[160:161], v[168:169], v[132:133], v[160:161] op_sel_hi:[1,0,1] neg_lo:[1,0,0] neg_hi:[1,0,0]
	v_pk_fma_f32 v[160:161], v[170:171], v[132:133], v[160:161] op_sel:[0,1,0] neg_lo:[1,0,0] neg_hi:[1,0,0]
	ds_read_b128 v[164:167], v228 offset:15872
	ds_read_b128 v[168:171], v228 offset:15888
	s_waitcnt lgkmcnt(14)
	v_pk_fma_f32 v[160:161], v[172:173], v[134:135], v[160:161] op_sel_hi:[1,0,1] neg_lo:[1,0,0] neg_hi:[1,0,0]
	v_pk_fma_f32 v[160:161], v[174:175], v[134:135], v[160:161] op_sel:[0,1,0] neg_lo:[1,0,0] neg_hi:[1,0,0]
	v_pk_fma_f32 v[160:161], v[176:177], v[136:137], v[160:161] op_sel_hi:[1,0,1] neg_lo:[1,0,0] neg_hi:[1,0,0]
	v_pk_fma_f32 v[160:161], v[178:179], v[136:137], v[160:161] op_sel:[0,1,0] neg_lo:[1,0,0] neg_hi:[1,0,0]
	ds_read_b128 v[172:175], v228 offset:15904
	ds_read_b128 v[176:179], v228 offset:15920
	s_waitcnt lgkmcnt(14)
	v_pk_fma_f32 v[160:161], v[180:181], v[138:139], v[160:161] op_sel_hi:[1,0,1] neg_lo:[1,0,0] neg_hi:[1,0,0]
	v_pk_fma_f32 v[160:161], v[182:183], v[138:139], v[160:161] op_sel:[0,1,0] neg_lo:[1,0,0] neg_hi:[1,0,0]
	v_pk_fma_f32 v[160:161], v[184:185], v[140:141], v[160:161] op_sel_hi:[1,0,1] neg_lo:[1,0,0] neg_hi:[1,0,0]
	v_pk_fma_f32 v[160:161], v[186:187], v[140:141], v[160:161] op_sel:[0,1,0] neg_lo:[1,0,0] neg_hi:[1,0,0]
	ds_read_b128 v[180:183], v228 offset:15936
	ds_read_b128 v[184:187], v228 offset:15952
	s_waitcnt lgkmcnt(14)
	v_pk_fma_f32 v[160:161], v[188:189], v[142:143], v[160:161] op_sel_hi:[1,0,1] neg_lo:[1,0,0] neg_hi:[1,0,0]
	v_pk_fma_f32 v[160:161], v[190:191], v[142:143], v[160:161] op_sel:[0,1,0] neg_lo:[1,0,0] neg_hi:[1,0,0]
	v_pk_fma_f32 v[160:161], v[192:193], v[144:145], v[160:161] op_sel_hi:[1,0,1] neg_lo:[1,0,0] neg_hi:[1,0,0]
	v_pk_fma_f32 v[160:161], v[194:195], v[144:145], v[160:161] op_sel:[0,1,0] neg_lo:[1,0,0] neg_hi:[1,0,0]
	ds_read_b128 v[188:191], v228 offset:15968
	ds_read_b128 v[192:195], v228 offset:15984
	s_waitcnt lgkmcnt(14)
	v_pk_fma_f32 v[160:161], v[196:197], v[146:147], v[160:161] op_sel_hi:[1,0,1] neg_lo:[1,0,0] neg_hi:[1,0,0]
	v_pk_fma_f32 v[160:161], v[198:199], v[146:147], v[160:161] op_sel:[0,1,0] neg_lo:[1,0,0] neg_hi:[1,0,0]
	v_pk_fma_f32 v[160:161], v[200:201], v[148:149], v[160:161] op_sel_hi:[1,0,1] neg_lo:[1,0,0] neg_hi:[1,0,0]
	v_pk_fma_f32 v[160:161], v[202:203], v[148:149], v[160:161] op_sel:[0,1,0] neg_lo:[1,0,0] neg_hi:[1,0,0]
	ds_read_b128 v[196:199], v228 offset:16000
	ds_read_b128 v[200:203], v228 offset:16016
	s_waitcnt lgkmcnt(14)
	v_pk_fma_f32 v[160:161], v[204:205], v[150:151], v[160:161] op_sel_hi:[1,0,1] neg_lo:[1,0,0] neg_hi:[1,0,0]
	v_pk_fma_f32 v[160:161], v[206:207], v[150:151], v[160:161] op_sel:[0,1,0] neg_lo:[1,0,0] neg_hi:[1,0,0]
	v_pk_fma_f32 v[160:161], v[208:209], v[152:153], v[160:161] op_sel_hi:[1,0,1] neg_lo:[1,0,0] neg_hi:[1,0,0]
	v_pk_fma_f32 v[160:161], v[210:211], v[152:153], v[160:161] op_sel:[0,1,0] neg_lo:[1,0,0] neg_hi:[1,0,0]
	ds_read_b128 v[204:207], v228 offset:16032
	ds_read_b128 v[208:211], v228 offset:16048
	s_waitcnt lgkmcnt(14)
	v_pk_fma_f32 v[160:161], v[212:213], v[154:155], v[160:161] op_sel_hi:[1,0,1] neg_lo:[1,0,0] neg_hi:[1,0,0]
	v_pk_fma_f32 v[160:161], v[214:215], v[154:155], v[160:161] op_sel:[0,1,0] neg_lo:[1,0,0] neg_hi:[1,0,0]
	v_pk_fma_f32 v[160:161], v[216:217], v[156:157], v[160:161] op_sel_hi:[1,0,1] neg_lo:[1,0,0] neg_hi:[1,0,0]
	v_pk_fma_f32 v[160:161], v[218:219], v[156:157], v[160:161] op_sel:[0,1,0] neg_lo:[1,0,0] neg_hi:[1,0,0]
	ds_read_b128 v[212:215], v228 offset:16064
	ds_read_b128 v[216:219], v228 offset:16080
	s_waitcnt lgkmcnt(14)
	v_pk_fma_f32 v[160:161], v[220:221], v[158:159], v[160:161] op_sel_hi:[1,0,1] neg_lo:[1,0,0] neg_hi:[1,0,0]
	v_pk_fma_f32 v[160:161], v[222:223], v[158:159], v[160:161] op_sel:[0,1,0] neg_lo:[1,0,0] neg_hi:[1,0,0]
	v_fma_f32 v161, -v225, v160, v161
	ds_read_b128 v[220:223], v228 offset:16096
	ds_read_b128 v[224:227], v228 offset:16112
	s_waitcnt lgkmcnt(14)
	v_pk_fma_f32 v[162:163], v[164:165], v[100:101], v[162:163] op_sel_hi:[1,0,1] neg_lo:[1,0,0] neg_hi:[1,0,0]
	v_pk_fma_f32 v[162:163], v[166:167], v[100:101], v[162:163] op_sel:[0,1,0] neg_lo:[1,0,0] neg_hi:[1,0,0]
	v_pk_fma_f32 v[162:163], v[168:169], v[102:103], v[162:163] op_sel_hi:[1,0,1] neg_lo:[1,0,0] neg_hi:[1,0,0]
	v_pk_fma_f32 v[162:163], v[170:171], v[102:103], v[162:163] op_sel:[0,1,0] neg_lo:[1,0,0] neg_hi:[1,0,0]
	ds_read_b128 v[164:167], v228 offset:16128
	ds_read_b128 v[168:171], v228 offset:16144
	s_waitcnt lgkmcnt(14)
	v_pk_fma_f32 v[162:163], v[172:173], v[104:105], v[162:163] op_sel_hi:[1,0,1] neg_lo:[1,0,0] neg_hi:[1,0,0]
	v_pk_fma_f32 v[162:163], v[174:175], v[104:105], v[162:163] op_sel:[0,1,0] neg_lo:[1,0,0] neg_hi:[1,0,0]
	v_pk_fma_f32 v[162:163], v[176:177], v[106:107], v[162:163] op_sel_hi:[1,0,1] neg_lo:[1,0,0] neg_hi:[1,0,0]
	v_pk_fma_f32 v[162:163], v[178:179], v[106:107], v[162:163] op_sel:[0,1,0] neg_lo:[1,0,0] neg_hi:[1,0,0]
	ds_read_b128 v[172:175], v228 offset:16160
	ds_read_b128 v[176:179], v228 offset:16176
	s_waitcnt lgkmcnt(14)
	v_pk_fma_f32 v[162:163], v[180:181], v[108:109], v[162:163] op_sel_hi:[1,0,1] neg_lo:[1,0,0] neg_hi:[1,0,0]
	v_pk_fma_f32 v[162:163], v[182:183], v[108:109], v[162:163] op_sel:[0,1,0] neg_lo:[1,0,0] neg_hi:[1,0,0]
	v_pk_fma_f32 v[162:163], v[184:185], v[110:111], v[162:163] op_sel_hi:[1,0,1] neg_lo:[1,0,0] neg_hi:[1,0,0]
	v_pk_fma_f32 v[162:163], v[186:187], v[110:111], v[162:163] op_sel:[0,1,0] neg_lo:[1,0,0] neg_hi:[1,0,0]
	ds_read_b128 v[180:183], v228 offset:16192
	ds_read_b128 v[184:187], v228 offset:16208
	s_waitcnt lgkmcnt(14)
	v_pk_fma_f32 v[162:163], v[188:189], v[112:113], v[162:163] op_sel_hi:[1,0,1] neg_lo:[1,0,0] neg_hi:[1,0,0]
	v_pk_fma_f32 v[162:163], v[190:191], v[112:113], v[162:163] op_sel:[0,1,0] neg_lo:[1,0,0] neg_hi:[1,0,0]
	v_pk_fma_f32 v[162:163], v[192:193], v[114:115], v[162:163] op_sel_hi:[1,0,1] neg_lo:[1,0,0] neg_hi:[1,0,0]
	v_pk_fma_f32 v[162:163], v[194:195], v[114:115], v[162:163] op_sel:[0,1,0] neg_lo:[1,0,0] neg_hi:[1,0,0]
	ds_read_b128 v[188:191], v228 offset:16224
	ds_read_b128 v[192:195], v228 offset:16240
	s_waitcnt lgkmcnt(14)
	v_pk_fma_f32 v[162:163], v[196:197], v[116:117], v[162:163] op_sel_hi:[1,0,1] neg_lo:[1,0,0] neg_hi:[1,0,0]
	v_pk_fma_f32 v[162:163], v[198:199], v[116:117], v[162:163] op_sel:[0,1,0] neg_lo:[1,0,0] neg_hi:[1,0,0]
	v_pk_fma_f32 v[162:163], v[200:201], v[118:119], v[162:163] op_sel_hi:[1,0,1] neg_lo:[1,0,0] neg_hi:[1,0,0]
	v_pk_fma_f32 v[162:163], v[202:203], v[118:119], v[162:163] op_sel:[0,1,0] neg_lo:[1,0,0] neg_hi:[1,0,0]
	ds_read_b128 v[196:199], v228 offset:16256
	ds_read_b128 v[200:203], v228 offset:16272
	s_waitcnt lgkmcnt(14)
	v_pk_fma_f32 v[162:163], v[204:205], v[120:121], v[162:163] op_sel_hi:[1,0,1] neg_lo:[1,0,0] neg_hi:[1,0,0]
	v_pk_fma_f32 v[162:163], v[206:207], v[120:121], v[162:163] op_sel:[0,1,0] neg_lo:[1,0,0] neg_hi:[1,0,0]
	v_pk_fma_f32 v[162:163], v[208:209], v[122:123], v[162:163] op_sel_hi:[1,0,1] neg_lo:[1,0,0] neg_hi:[1,0,0]
	v_pk_fma_f32 v[162:163], v[210:211], v[122:123], v[162:163] op_sel:[0,1,0] neg_lo:[1,0,0] neg_hi:[1,0,0]
	ds_read_b128 v[204:207], v228 offset:16288
	ds_read_b128 v[208:211], v228 offset:16304
	s_waitcnt lgkmcnt(14)
	v_pk_fma_f32 v[162:163], v[212:213], v[124:125], v[162:163] op_sel_hi:[1,0,1] neg_lo:[1,0,0] neg_hi:[1,0,0]
	v_pk_fma_f32 v[162:163], v[214:215], v[124:125], v[162:163] op_sel:[0,1,0] neg_lo:[1,0,0] neg_hi:[1,0,0]
	v_pk_fma_f32 v[162:163], v[216:217], v[126:127], v[162:163] op_sel_hi:[1,0,1] neg_lo:[1,0,0] neg_hi:[1,0,0]
	v_pk_fma_f32 v[162:163], v[218:219], v[126:127], v[162:163] op_sel:[0,1,0] neg_lo:[1,0,0] neg_hi:[1,0,0]
	ds_read_b128 v[212:215], v228 offset:16320
	ds_read_b128 v[216:219], v228 offset:16336
	s_waitcnt lgkmcnt(14)
	v_pk_fma_f32 v[162:163], v[220:221], v[128:129], v[162:163] op_sel_hi:[1,0,1] neg_lo:[1,0,0] neg_hi:[1,0,0]
	v_pk_fma_f32 v[162:163], v[222:223], v[128:129], v[162:163] op_sel:[0,1,0] neg_lo:[1,0,0] neg_hi:[1,0,0]
	v_pk_fma_f32 v[162:163], v[224:225], v[130:131], v[162:163] op_sel_hi:[1,0,1] neg_lo:[1,0,0] neg_hi:[1,0,0]
	v_pk_fma_f32 v[162:163], v[226:227], v[130:131], v[162:163] op_sel:[0,1,0] neg_lo:[1,0,0] neg_hi:[1,0,0]
	ds_read_b128 v[220:223], v228 offset:16352
	ds_read_b128 v[224:227], v228 offset:16368
	s_waitcnt lgkmcnt(14)
	v_pk_fma_f32 v[162:163], v[164:165], v[132:133], v[162:163] op_sel_hi:[1,0,1] neg_lo:[1,0,0] neg_hi:[1,0,0]
	v_pk_fma_f32 v[162:163], v[166:167], v[132:133], v[162:163] op_sel:[0,1,0] neg_lo:[1,0,0] neg_hi:[1,0,0]
	v_pk_fma_f32 v[162:163], v[168:169], v[134:135], v[162:163] op_sel_hi:[1,0,1] neg_lo:[1,0,0] neg_hi:[1,0,0]
	v_pk_fma_f32 v[162:163], v[170:171], v[134:135], v[162:163] op_sel:[0,1,0] neg_lo:[1,0,0] neg_hi:[1,0,0]
	s_waitcnt lgkmcnt(12)
	v_pk_fma_f32 v[162:163], v[172:173], v[136:137], v[162:163] op_sel_hi:[1,0,1] neg_lo:[1,0,0] neg_hi:[1,0,0]
	v_pk_fma_f32 v[162:163], v[174:175], v[136:137], v[162:163] op_sel:[0,1,0] neg_lo:[1,0,0] neg_hi:[1,0,0]
	v_pk_fma_f32 v[162:163], v[176:177], v[138:139], v[162:163] op_sel_hi:[1,0,1] neg_lo:[1,0,0] neg_hi:[1,0,0]
	v_pk_fma_f32 v[162:163], v[178:179], v[138:139], v[162:163] op_sel:[0,1,0] neg_lo:[1,0,0] neg_hi:[1,0,0]
	s_waitcnt lgkmcnt(10)
	v_pk_fma_f32 v[162:163], v[180:181], v[140:141], v[162:163] op_sel_hi:[1,0,1] neg_lo:[1,0,0] neg_hi:[1,0,0]
	v_pk_fma_f32 v[162:163], v[182:183], v[140:141], v[162:163] op_sel:[0,1,0] neg_lo:[1,0,0] neg_hi:[1,0,0]
	v_pk_fma_f32 v[162:163], v[184:185], v[142:143], v[162:163] op_sel_hi:[1,0,1] neg_lo:[1,0,0] neg_hi:[1,0,0]
	v_pk_fma_f32 v[162:163], v[186:187], v[142:143], v[162:163] op_sel:[0,1,0] neg_lo:[1,0,0] neg_hi:[1,0,0]
	s_waitcnt lgkmcnt(8)
	v_pk_fma_f32 v[162:163], v[188:189], v[144:145], v[162:163] op_sel_hi:[1,0,1] neg_lo:[1,0,0] neg_hi:[1,0,0]
	v_pk_fma_f32 v[162:163], v[190:191], v[144:145], v[162:163] op_sel:[0,1,0] neg_lo:[1,0,0] neg_hi:[1,0,0]
	v_pk_fma_f32 v[162:163], v[192:193], v[146:147], v[162:163] op_sel_hi:[1,0,1] neg_lo:[1,0,0] neg_hi:[1,0,0]
	v_pk_fma_f32 v[162:163], v[194:195], v[146:147], v[162:163] op_sel:[0,1,0] neg_lo:[1,0,0] neg_hi:[1,0,0]
	s_waitcnt lgkmcnt(6)
	v_pk_fma_f32 v[162:163], v[196:197], v[148:149], v[162:163] op_sel_hi:[1,0,1] neg_lo:[1,0,0] neg_hi:[1,0,0]
	v_pk_fma_f32 v[162:163], v[198:199], v[148:149], v[162:163] op_sel:[0,1,0] neg_lo:[1,0,0] neg_hi:[1,0,0]
	v_pk_fma_f32 v[162:163], v[200:201], v[150:151], v[162:163] op_sel_hi:[1,0,1] neg_lo:[1,0,0] neg_hi:[1,0,0]
	v_pk_fma_f32 v[162:163], v[202:203], v[150:151], v[162:163] op_sel:[0,1,0] neg_lo:[1,0,0] neg_hi:[1,0,0]
	s_waitcnt lgkmcnt(4)
	v_pk_fma_f32 v[162:163], v[204:205], v[152:153], v[162:163] op_sel_hi:[1,0,1] neg_lo:[1,0,0] neg_hi:[1,0,0]
	v_pk_fma_f32 v[162:163], v[206:207], v[152:153], v[162:163] op_sel:[0,1,0] neg_lo:[1,0,0] neg_hi:[1,0,0]
	v_pk_fma_f32 v[162:163], v[208:209], v[154:155], v[162:163] op_sel_hi:[1,0,1] neg_lo:[1,0,0] neg_hi:[1,0,0]
	v_pk_fma_f32 v[162:163], v[210:211], v[154:155], v[162:163] op_sel:[0,1,0] neg_lo:[1,0,0] neg_hi:[1,0,0]
	s_waitcnt lgkmcnt(2)
	v_pk_fma_f32 v[162:163], v[212:213], v[156:157], v[162:163] op_sel_hi:[1,0,1] neg_lo:[1,0,0] neg_hi:[1,0,0]
	v_pk_fma_f32 v[162:163], v[214:215], v[156:157], v[162:163] op_sel:[0,1,0] neg_lo:[1,0,0] neg_hi:[1,0,0]
	v_pk_fma_f32 v[162:163], v[216:217], v[158:159], v[162:163] op_sel_hi:[1,0,1] neg_lo:[1,0,0] neg_hi:[1,0,0]
	v_pk_fma_f32 v[162:163], v[218:219], v[158:159], v[162:163] op_sel:[0,1,0] neg_lo:[1,0,0] neg_hi:[1,0,0]
	s_waitcnt lgkmcnt(0)
	v_pk_fma_f32 v[162:163], v[220:221], v[160:161], v[162:163] op_sel_hi:[1,0,1] neg_lo:[1,0,0] neg_hi:[1,0,0]
	v_pk_fma_f32 v[162:163], v[222:223], v[160:161], v[162:163] op_sel:[0,1,0] neg_lo:[1,0,0] neg_hi:[1,0,0]
	v_fma_f32 v163, -v225, v162, v163
	v_cvt_pk_bf16_f32 v35, v102, v103
	v_cvt_pk_bf16_f32 v34, v100, v101
	v_cvt_pk_bf16_f32 v32, v104, v105
	v_cvt_pk_bf16_f32 v33, v106, v107
	v_cvt_pk_bf16_f32 v30, v108, v109
	v_cvt_pk_bf16_f32 v31, v110, v111
	v_cvt_pk_bf16_f32 v28, v112, v113
	v_cvt_pk_bf16_f32 v29, v114, v115
	v_cvt_pk_bf16_f32 v26, v116, v117
	v_cvt_pk_bf16_f32 v27, v118, v119
	v_cvt_pk_bf16_f32 v24, v120, v121
	v_cvt_pk_bf16_f32 v25, v122, v123
	v_cvt_pk_bf16_f32 v18, v124, v125
	v_cvt_pk_bf16_f32 v19, v126, v127
	v_cvt_pk_bf16_f32 v16, v128, v129
	v_cvt_pk_bf16_f32 v17, v130, v131
	v_cvt_pk_bf16_f32 v14, v132, v133
	v_cvt_pk_bf16_f32 v15, v134, v135
	v_cvt_pk_bf16_f32 v12, v136, v137
	v_cvt_pk_bf16_f32 v13, v138, v139
	v_cvt_pk_bf16_f32 v10, v140, v141
	v_cvt_pk_bf16_f32 v11, v142, v143
	v_cvt_pk_bf16_f32 v8, v144, v145
	v_cvt_pk_bf16_f32 v9, v146, v147
	v_cvt_pk_bf16_f32 v6, v148, v149
	v_cvt_pk_bf16_f32 v7, v150, v151
	v_cvt_pk_bf16_f32 v4, v152, v153
	v_cvt_pk_bf16_f32 v5, v154, v155
	v_cvt_pk_bf16_f32 v2, v156, v157
	v_cvt_pk_bf16_f32 v3, v158, v159
	v_cvt_pk_bf16_f32 v0, v160, v161
	v_cvt_pk_bf16_f32 v1, v162, v163
	s_and_saveexec_b64 s[0:1], vcc
	s_xor_b64 s[0:1], exec, s[0:1]
	s_cbranch_execz .LBB0_419
	v_and_b32_e32 v39, 0x7ffffff0, v39
	v_lshlrev_b32_e32 v39, 1, v39
	v_lshlrev_b32_e32 v22, 1, v22
	v_add3_u32 v22, 0, v39, v22
	v_lshlrev_b32_e32 v39, 2, v77
	v_lshlrev_b32_e32 v38, 1, v38
	v_and_b32_e32 v39, 16, v39
	v_add3_u32 v22, v22, v38, v39
	ds_write_b16 v22, v34
	ds_write_b16_d16_hi v22, v34 offset:272
	ds_write_b16 v22, v35 offset:544
	ds_write_b16_d16_hi v22, v35 offset:816
	ds_write_b16 v22, v32 offset:1088
	ds_write_b16_d16_hi v22, v32 offset:1360
	ds_write_b16 v22, v33 offset:1632
	ds_write_b16_d16_hi v22, v33 offset:1904
	ds_write_b16 v22, v30 offset:2176
	ds_write_b16_d16_hi v22, v30 offset:2448
	ds_write_b16 v22, v31 offset:2720
	ds_write_b16_d16_hi v22, v31 offset:2992
	ds_write_b16 v22, v28 offset:3264
	ds_write_b16_d16_hi v22, v28 offset:3536
	ds_write_b16 v22, v29 offset:3808
	ds_write_b16_d16_hi v22, v29 offset:4080
	ds_write_b16 v22, v26 offset:4352
	ds_write_b16_d16_hi v22, v26 offset:4624
	ds_write_b16 v22, v27 offset:4896
	ds_write_b16_d16_hi v22, v27 offset:5168
	ds_write_b16 v22, v24 offset:5440
	ds_write_b16_d16_hi v22, v24 offset:5712
	ds_write_b16 v22, v25 offset:5984
	ds_write_b16_d16_hi v22, v25 offset:6256
	ds_write_b16 v22, v18 offset:6528
	ds_write_b16_d16_hi v22, v18 offset:6800
	ds_write_b16 v22, v19 offset:7072
	ds_write_b16_d16_hi v22, v19 offset:7344
	ds_write_b16 v22, v16 offset:7616
	ds_write_b16_d16_hi v22, v16 offset:7888
	ds_write_b16 v22, v17 offset:8160
	ds_write_b16_d16_hi v22, v17 offset:8432
	ds_write_b16 v22, v14 offset:8704
	ds_write_b16_d16_hi v22, v14 offset:8976
	ds_write_b16 v22, v15 offset:9248
	ds_write_b16_d16_hi v22, v15 offset:9520
	ds_write_b16 v22, v12 offset:9792
	ds_write_b16_d16_hi v22, v12 offset:10064
	ds_write_b16 v22, v13 offset:10336
	ds_write_b16_d16_hi v22, v13 offset:10608
	ds_write_b16 v22, v10 offset:10880
	ds_write_b16_d16_hi v22, v10 offset:11152
	ds_write_b16 v22, v11 offset:11424
	ds_write_b16_d16_hi v22, v11 offset:11696
	ds_write_b16 v22, v8 offset:11968
	ds_write_b16_d16_hi v22, v8 offset:12240
	ds_write_b16 v22, v9 offset:12512
	ds_write_b16_d16_hi v22, v9 offset:12784
	ds_write_b16 v22, v6 offset:13056
	ds_write_b16_d16_hi v22, v6 offset:13328
	ds_write_b16 v22, v7 offset:13600
	ds_write_b16_d16_hi v22, v7 offset:13872
	ds_write_b16 v22, v4 offset:14144
	ds_write_b16_d16_hi v22, v4 offset:14416
	ds_write_b16 v22, v5 offset:14688
	ds_write_b16_d16_hi v22, v5 offset:14960
	ds_write_b16 v22, v2 offset:15232
	ds_write_b16_d16_hi v22, v2 offset:15504
	ds_write_b16 v22, v3 offset:15776
	ds_write_b16_d16_hi v22, v3 offset:16048
	ds_write_b16 v22, v0 offset:16320
	ds_write_b16_d16_hi v22, v0 offset:16592
	ds_write_b16 v22, v1 offset:16864
	ds_write_b16_d16_hi v22, v1 offset:17136
